# combo15 with the K-loops' per-segment priority flips removed and one static s_setprio 1 for the younger half (waves 4-7) at each K-loop entry
# baseline (speedup 1.0000x reference)
;     __device__ __forceinline__ bool next(int i, Unit& u) const { const int off = i * H + (r >> 1); if (off >= 8 * nN) return false; u.pm = 16 * g + 8 * (r & 1) + (off & 7); u.pn = off >> 3; return true; }
; #define PG8_STAGE(bufoff, gbase, unused) do { _Pragma("unroll") for (int _i = 0; _i < 2; ++_i) \
;         __builtin_amdgcn_global_load_lds((const unsigned*)((const char*)(gbase) + voff + _i * 8192), (LAS unsigned*)(lds + (bufoff) + ldsw + _i * 8192), 16, 0, 0); } while (0)
; #define PG8_LDA(dst, b, h) do { _Pragma("unroll") for (int m = 0; m < 4; ++m) _Pragma("unroll") for (int k = 0; k < 2; ++k) dst[m][k] = *(const LAS bf16x8*)(lds + PG8_SA(b, h) + aoff + m * 2048 + (FP8 ? k * 16 : k * 1024)); } while (0)
; #define PG8_LDB(dst, b, h) do { _Pragma("unroll") for (int n = 0; n < 2; ++n) _Pragma("unroll") for (int k = 0; k < 2; ++k) dst[n][k] = *(const LAS bf16x8*)(lds + PG8_SB(b, h) + boff + n * 2048 + (FP8 ? k * 16 : k * 1024)); } while (0)
; #define PG8_BAR __builtin_amdgcn_s_barrier()
; template <class Epi, class Sched, bool ALIGN_EPI, bool SP2, int MODE  >
; __device__ __forceinline__ void gemm_phase(LAS unsigned char* lds, const Gemm g, const Sched S, const Epi E, unsigned long long& probe_acc, int epi_id, int wv) {
;     ...
;         const bool has_next = S.next(ui + 1, nxt);
;         const char* nA = has_next ? (const char*)g.A + (size_t)nxt.pm * tA + (g.gt ? (size_t)(nxt.pn / g.gt) * gK2 : 0) : cA; const char* nB = has_next ? (const char*)g.Bt + (size_t)nxt.pn * tB : cB;
;         for (int t = 0; t < nt; t += 2) {
;             const bool last = (t == nt - 2);
;             const char* a1 = cA + (size_t)(t + 1) * kstep;
;             const char* a2 = last ? nA : cA + (size_t)(t + 2) * kstep; const char* b2 = last ? nB : cB + (size_t)(t + 2) * kstep;
;             const char* a3 = a2 + kstep; const char* b3 = b2 + kstep;
;             if constexpr (SP2) {
;             PG8_LDB(B0, 0, 0); PG8_LDB(B1, 0, 1); PG8_SCHED; PG8_LDA(At, 0, 0); PG8_STAGE(PG8_SA(1, 1), a1 + hA, voffA);
;             PG8_WAIT_V(8); PG8_WAIT_L(0); PG8_BAR; PG8_MMA(0, 0, At, B0); PG8_MMA(0, 1, At, B1); PG8_BAR; PG8_SCHED;
;             PG8_LDA(At, 0, 1); PG8_STAGE(PG8_SB(0, 0), b2, voffB); PG8_STAGE(PG8_SB(0, 1), b2 + hB, voffB); PG8_STAGE(PG8_SA(0, 0), a2, voffA);
;             PG8_WAIT_V(8); PG8_WAIT_L(0); PG8_BAR; PG8_MMA(1, 0, At, B0); PG8_MMA(1, 1, At, B1); PG8_BAR; PG8_SCHED;
.LBB0_325:
	s_mov_b64 s[28:29], s[10:11]
	s_mov_b32 s11, s1
	s_mov_b32 s26, s1
	s_add_i32 s40, s40, 1
	v_readlane_b32 s1, v254, 6
	s_mov_b64 s[14:15], s[4:5]
	s_mul_i32 s1, s40, s1
	v_readlane_b32 s4, v254, 35
	s_add_i32 s1, s1, s4
	s_cmpk_lt_i32 s1, 0x160
	s_cselect_b64 s[24:25], -1, 0
	s_and_b32 s4, s1, 7
	v_readlane_b32 s5, v254, 18
	s_mov_b32 s10, s69
	s_mov_b32 s8, s69
	s_or_b32 s69, s4, s5
	s_ashr_i32 s1, s1, 3
	s_and_b64 s[4:5], s[24:25], exec
	s_cselect_b32 s10, s69, s10
	s_cselect_b32 s4, s1, s11
	s_ashr_i32 s11, s10, 31
	s_lshl_b64 s[10:11], s[10:11], 19
	s_add_u32 s10, s34, s10
	s_addc_u32 s11, s35, s11
	s_and_b64 s[16:17], s[24:25], exec
	s_cselect_b32 s27, s11, s29
	s_cselect_b32 s46, s10, s28
	s_ashr_i32 s5, s4, 31
	s_lshl_b64 s[4:5], s[4:5], 19
	s_add_u32 s4, s36, s4
	s_addc_u32 s5, s37, s5
	s_and_b64 s[16:17], s[24:25], exec
	s_cselect_b32 vcc_lo, s5, s15
	s_cselect_b32 vcc_hi, s4, s14
	s_add_u32 s16, s14, 0x8000
	s_addc_u32 s17, s15, 0
	s_mov_b32 s14, -2
	s_waitcnt lgkmcnt(0)
	v_add_u32_e32 v0, s39, v212
	ds_read_b128 v[132:135], v0
	ds_read_b128 v[136:139], v0 offset:1024
	ds_read_b128 v[140:143], v0 offset:2048
	ds_read_b128 v[144:147], v0 offset:3072
	v_add_u32_e32 v0, s65, v212
	ds_read_b128 v[148:151], v0
	ds_read_b128 v[152:155], v0 offset:1024
	ds_read_b128 v[156:159], v0 offset:2048
	ds_read_b128 v[160:163], v0 offset:3072
	s_add_u32 s30, s28, 0x8000
	s_addc_u32 s31, s29, 0
	s_cmp_eq_u32 s14, 12
	s_cselect_b32 s23, s27, s31
	s_cselect_b32 s22, s46, s30
	s_cselect_b32 s21, vcc_lo, s17
	s_cselect_b32 s20, vcc_hi, s16
	v_lshl_add_u64 v[184:185], s[28:29], 0, v[130:131]
	v_lshl_add_u64 v[204:205], v[184:185], 0, s[80:81]
	s_add_i32 m0, s85, 0xc000
	ds_read_b128 v[164:167], v213
	ds_read_b128 v[168:171], v213 offset:1024
	ds_read_b128 v[172:175], v213 offset:2048
	ds_read_b128 v[176:179], v213 offset:3072
	ds_read_b128 v[180:183], v213 offset:4096
	ds_read_b128 v[190:193], v213 offset:5120
	ds_read_b128 v[196:199], v213 offset:6144
	ds_read_b128 v[200:203], v213 offset:7168
	global_load_lds_dwordx4 v[204:205], off
	v_lshl_add_u64 v[184:185], v[184:185], 0, s[82:83]
	s_add_i32 m0, s85, 0xe000
	s_nop 0
	global_load_lds_dwordx4 v[184:185], off
	s_waitcnt vmcnt(8)
	s_waitcnt lgkmcnt(0)
	s_barrier
	v_mfma_i32_16x16x64_i8 v[126:129], v[132:135], v[164:167], 0
	v_mfma_i32_16x16x64_i8 v[102:105], v[140:143], v[164:167], 0
	v_mfma_i32_16x16x64_i8 v[122:125], v[132:135], v[172:175], 0
	v_mfma_i32_16x16x64_i8 v[94:97], v[140:143], v[172:175], 0
	v_mfma_i32_16x16x64_i8 v[118:121], v[132:135], v[180:183], 0
	v_mfma_i32_16x16x64_i8 v[46:49], v[140:143], v[180:183], 0
	v_mfma_i32_16x16x64_i8 v[110:113], v[132:135], v[196:199], 0
	v_mfma_i32_16x16x64_i8 v[38:41], v[140:143], v[196:199], 0
	v_mfma_i32_16x16x64_i8 v[126:129], v[136:139], v[168:171], v[126:129]
	v_mfma_i32_16x16x64_i8 v[102:105], v[144:147], v[168:171], v[102:105]
	v_mfma_i32_16x16x64_i8 v[122:125], v[136:139], v[176:179], v[122:125]
	v_mfma_i32_16x16x64_i8 v[94:97], v[144:147], v[176:179], v[94:97]
	v_mfma_i32_16x16x64_i8 v[118:121], v[136:139], v[190:193], v[118:121]
	v_mfma_i32_16x16x64_i8 v[46:49], v[144:147], v[190:193], v[46:49]
	v_mfma_i32_16x16x64_i8 v[110:113], v[136:139], v[200:203], v[110:113]
	v_mfma_i32_16x16x64_i8 v[38:41], v[144:147], v[200:203], v[38:41]
	v_mfma_i32_16x16x64_i8 v[114:117], v[148:151], v[164:167], 0
	v_mfma_i32_16x16x64_i8 v[82:85], v[156:159], v[164:167], 0
	v_mfma_i32_16x16x64_i8 v[106:109], v[148:151], v[172:175], 0
	v_mfma_i32_16x16x64_i8 v[74:77], v[156:159], v[172:175], 0
	v_mfma_i32_16x16x64_i8 v[98:101], v[148:151], v[180:183], 0
	v_mfma_i32_16x16x64_i8 v[42:45], v[156:159], v[180:183], 0
	v_mfma_i32_16x16x64_i8 v[90:93], v[148:151], v[196:199], 0
	v_mfma_i32_16x16x64_i8 v[34:37], v[156:159], v[196:199], 0
	v_mfma_i32_16x16x64_i8 v[114:117], v[152:155], v[168:171], v[114:117]
	v_mfma_i32_16x16x64_i8 v[82:85], v[160:163], v[168:171], v[82:85]
	v_mfma_i32_16x16x64_i8 v[106:109], v[152:155], v[176:179], v[106:109]
	v_mfma_i32_16x16x64_i8 v[74:77], v[160:163], v[176:179], v[74:77]
	v_mfma_i32_16x16x64_i8 v[98:101], v[152:155], v[190:193], v[98:101]
	v_mfma_i32_16x16x64_i8 v[42:45], v[160:163], v[190:193], v[42:45]
	v_mfma_i32_16x16x64_i8 v[90:93], v[152:155], v[200:203], v[90:93]
	v_mfma_i32_16x16x64_i8 v[34:37], v[160:163], v[200:203], v[34:37]
	s_barrier
	s_mov_b32 m0, s41
	v_lshl_add_u64 v[184:185], s[20:21], 0, v[130:131]
	ds_read_b128 v[164:167], v213 offset:16384
	ds_read_b128 v[168:171], v213 offset:17408
	ds_read_b128 v[172:175], v213 offset:18432
	ds_read_b128 v[176:179], v213 offset:19456
	ds_read_b128 v[180:183], v213 offset:20480
	ds_read_b128 v[190:193], v213 offset:21504
	ds_read_b128 v[196:199], v213 offset:22528
	ds_read_b128 v[200:203], v213 offset:23552
	global_load_lds_dwordx4 v[184:185], off
	v_lshl_add_u64 v[204:205], v[184:185], 0, s[70:71]
	s_mov_b32 m0, s64
	s_nop 0
	global_load_lds_dwordx4 v[204:205], off
	v_lshl_add_u64 v[204:205], v[184:185], 0, s[72:73]
	s_mov_b32 m0, s68
	s_nop 0
	global_load_lds_dwordx4 v[204:205], off
	v_lshl_add_u64 v[204:205], v[184:185], 0, s[74:75]
	s_mov_b32 m0, s84
	s_nop 0
	global_load_lds_dwordx4 v[204:205], off
	v_lshl_add_u64 v[204:205], s[22:23], 0, v[130:131]
	s_mov_b32 m0, s85
	v_lshl_add_u64 v[206:207], v[204:205], 0, s[70:71]
	global_load_lds_dwordx4 v[204:205], off
	s_mov_b32 m0, s86
	s_nop 0
	global_load_lds_dwordx4 v[206:207], off
	s_waitcnt vmcnt(8)
	s_waitcnt lgkmcnt(0)
	s_barrier
; #define PG8_STAGE(bufoff, gbase, unused) do { _Pragma("unroll") for (int _i = 0; _i < 2; ++_i) \
;         __builtin_amdgcn_global_load_lds((const unsigned*)((const char*)(gbase) + voff + _i * 8192), (LAS unsigned*)(lds + (bufoff) + ldsw + _i * 8192), 16, 0, 0); } while (0)
; #define PG8_LDA(dst, b, h) do { _Pragma("unroll") for (int m = 0; m < 4; ++m) _Pragma("unroll") for (int k = 0; k < 2; ++k) dst[m][k] = *(const LAS bf16x8*)(lds + PG8_SA(b, h) + aoff + m * 2048 + (FP8 ? k * 16 : k * 1024)); } while (0)
; #define PG8_LDB(dst, b, h) do { _Pragma("unroll") for (int n = 0; n < 2; ++n) _Pragma("unroll") for (int k = 0; k < 2; ++k) dst[n][k] = *(const LAS bf16x8*)(lds + PG8_SB(b, h) + boff + n * 2048 + (FP8 ? k * 16 : k * 1024)); } while (0)
; #define PG8_WAIT_V(n) asm volatile("s_waitcnt vmcnt(" #n ")" ::: "memory")
; #define PG8_WAIT_L(n) asm volatile("s_waitcnt lgkmcnt(" #n ")" ::: "memory")
; #define PG8_BAR __builtin_amdgcn_s_barrier()
; #define PG8_SCHED __builtin_amdgcn_sched_barrier(0)
; template <class Epi, class Sched, bool ALIGN_EPI, bool SP2, int MODE  >
; __device__ __forceinline__ void gemm_phase(LAS unsigned char* lds, const Gemm g, const Sched S, const Epi E, unsigned long long& probe_acc, int epi_id, int wv) {
;     ...
;             PG8_WAIT_V(8); PG8_WAIT_L(0); PG8_BAR; PG8_MMA(1, 0, At, B0); PG8_MMA(1, 1, At, B1); PG8_BAR; PG8_SCHED;
;             PG8_LDB(B0, 1, 0); PG8_LDB(B1, 1, 1); PG8_SCHED; PG8_LDA(At, 1, 0); PG8_STAGE(PG8_SA(0, 1), a2 + hA, voffA);
;             PG8_WAIT_V(8); PG8_WAIT_L(0); PG8_BAR; PG8_MMA(0, 0, At, B0); PG8_MMA(0, 1, At, B1); PG8_BAR; PG8_SCHED;
	v_mfma_i32_16x16x64_i8 v[86:89], v[132:135], v[164:167], 0
	v_mfma_i32_16x16x64_i8 v[30:33], v[140:143], v[164:167], 0
	v_mfma_i32_16x16x64_i8 v[78:81], v[132:135], v[172:175], 0
	v_mfma_i32_16x16x64_i8 v[22:25], v[140:143], v[172:175], 0
	v_mfma_i32_16x16x64_i8 v[70:73], v[132:135], v[180:183], 0
	v_mfma_i32_16x16x64_i8 v[14:17], v[140:143], v[180:183], 0
	v_mfma_i32_16x16x64_i8 v[62:65], v[132:135], v[196:199], 0
	v_mfma_i32_16x16x64_i8 v[2:5], v[140:143], v[196:199], 0
	v_mfma_i32_16x16x64_i8 v[86:89], v[136:139], v[168:171], v[86:89]
	v_mfma_i32_16x16x64_i8 v[30:33], v[144:147], v[168:171], v[30:33]
	v_mfma_i32_16x16x64_i8 v[78:81], v[136:139], v[176:179], v[78:81]
	v_mfma_i32_16x16x64_i8 v[22:25], v[144:147], v[176:179], v[22:25]
	v_mfma_i32_16x16x64_i8 v[70:73], v[136:139], v[190:193], v[70:73]
	v_mfma_i32_16x16x64_i8 v[14:17], v[144:147], v[190:193], v[14:17]
	v_mfma_i32_16x16x64_i8 v[62:65], v[136:139], v[200:203], v[62:65]
	v_mfma_i32_16x16x64_i8 v[2:5], v[144:147], v[200:203], v[2:5]
	v_mfma_i32_16x16x64_i8 v[66:69], v[148:151], v[164:167], 0
	v_mfma_i32_16x16x64_i8 v[26:29], v[156:159], v[164:167], 0
	v_mfma_i32_16x16x64_i8 v[58:61], v[148:151], v[172:175], 0
	v_mfma_i32_16x16x64_i8 v[18:21], v[156:159], v[172:175], 0
	v_mfma_i32_16x16x64_i8 v[54:57], v[148:151], v[180:183], 0
	v_mfma_i32_16x16x64_i8 v[10:13], v[156:159], v[180:183], 0
	v_mfma_i32_16x16x64_i8 v[50:53], v[148:151], v[196:199], 0
	v_mfma_i32_16x16x64_i8 v[6:9], v[156:159], v[196:199], 0
	v_mfma_i32_16x16x64_i8 v[66:69], v[152:155], v[168:171], v[66:69]
	v_mfma_i32_16x16x64_i8 v[26:29], v[160:163], v[168:171], v[26:29]
	v_mfma_i32_16x16x64_i8 v[58:61], v[152:155], v[176:179], v[58:61]
	v_mfma_i32_16x16x64_i8 v[18:21], v[160:163], v[176:179], v[18:21]
	v_mfma_i32_16x16x64_i8 v[54:57], v[152:155], v[190:193], v[54:57]
	v_mfma_i32_16x16x64_i8 v[10:13], v[160:163], v[190:193], v[10:13]
	v_mfma_i32_16x16x64_i8 v[50:53], v[152:155], v[200:203], v[50:53]
	v_mfma_i32_16x16x64_i8 v[6:9], v[160:163], v[200:203], v[6:9]
	s_barrier
	v_add_u32_e32 v0, s90, v212
	ds_read_b128 v[132:135], v0
	ds_read_b128 v[136:139], v0 offset:1024
	ds_read_b128 v[140:143], v0 offset:2048
	ds_read_b128 v[144:147], v0 offset:3072
	v_add_u32_e32 v0, s95, v212
	ds_read_b128 v[148:151], v0
	ds_read_b128 v[152:155], v0 offset:1024
	ds_read_b128 v[156:159], v0 offset:2048
	ds_read_b128 v[160:163], v0 offset:3072
	s_mov_b32 m0, s87
	v_lshl_add_u64 v[206:207], v[204:205], 0, s[72:73]
	ds_read_b128 v[164:167], v213 offset:32768
	ds_read_b128 v[168:171], v213 offset:33792
	ds_read_b128 v[172:175], v213 offset:34816
	ds_read_b128 v[176:179], v213 offset:35840
	ds_read_b128 v[180:183], v213 offset:36864
	ds_read_b128 v[190:193], v213 offset:37888
	ds_read_b128 v[196:199], v213 offset:38912
	ds_read_b128 v[200:203], v213 offset:39936
	global_load_lds_dwordx4 v[206:207], off
	v_lshl_add_u64 v[206:207], v[204:205], 0, s[74:75]
	s_mov_b32 m0, s88
	s_nop 0
	global_load_lds_dwordx4 v[206:207], off
	s_waitcnt vmcnt(8)
	s_waitcnt lgkmcnt(0)
	s_barrier
	v_mfma_i32_16x16x64_i8 v[126:129], v[132:135], v[164:167], v[126:129]
	v_mfma_i32_16x16x64_i8 v[102:105], v[140:143], v[164:167], v[102:105]
	v_mfma_i32_16x16x64_i8 v[122:125], v[132:135], v[172:175], v[122:125]
	v_mfma_i32_16x16x64_i8 v[94:97], v[140:143], v[172:175], v[94:97]
	v_mfma_i32_16x16x64_i8 v[118:121], v[132:135], v[180:183], v[118:121]
	v_mfma_i32_16x16x64_i8 v[46:49], v[140:143], v[180:183], v[46:49]
	v_mfma_i32_16x16x64_i8 v[110:113], v[132:135], v[196:199], v[110:113]
	v_mfma_i32_16x16x64_i8 v[38:41], v[140:143], v[196:199], v[38:41]
	v_mfma_i32_16x16x64_i8 v[126:129], v[136:139], v[168:171], v[126:129]
	v_mfma_i32_16x16x64_i8 v[102:105], v[144:147], v[168:171], v[102:105]
	v_mfma_i32_16x16x64_i8 v[122:125], v[136:139], v[176:179], v[122:125]
	v_mfma_i32_16x16x64_i8 v[94:97], v[144:147], v[176:179], v[94:97]
	v_mfma_i32_16x16x64_i8 v[118:121], v[136:139], v[190:193], v[118:121]
	v_mfma_i32_16x16x64_i8 v[46:49], v[144:147], v[190:193], v[46:49]
	v_mfma_i32_16x16x64_i8 v[110:113], v[136:139], v[200:203], v[110:113]
	v_mfma_i32_16x16x64_i8 v[38:41], v[144:147], v[200:203], v[38:41]
	v_mfma_i32_16x16x64_i8 v[114:117], v[148:151], v[164:167], v[114:117]
	v_mfma_i32_16x16x64_i8 v[82:85], v[156:159], v[164:167], v[82:85]
	v_mfma_i32_16x16x64_i8 v[106:109], v[148:151], v[172:175], v[106:109]
	v_mfma_i32_16x16x64_i8 v[74:77], v[156:159], v[172:175], v[74:77]
	v_mfma_i32_16x16x64_i8 v[98:101], v[148:151], v[180:183], v[98:101]
	v_mfma_i32_16x16x64_i8 v[42:45], v[156:159], v[180:183], v[42:45]
	v_mfma_i32_16x16x64_i8 v[90:93], v[148:151], v[196:199], v[90:93]
	v_mfma_i32_16x16x64_i8 v[34:37], v[156:159], v[196:199], v[34:37]
	v_mfma_i32_16x16x64_i8 v[114:117], v[152:155], v[168:171], v[114:117]
	v_mfma_i32_16x16x64_i8 v[82:85], v[160:163], v[168:171], v[82:85]
	v_mfma_i32_16x16x64_i8 v[106:109], v[152:155], v[176:179], v[106:109]
	v_mfma_i32_16x16x64_i8 v[74:77], v[160:163], v[176:179], v[74:77]
	v_mfma_i32_16x16x64_i8 v[98:101], v[152:155], v[190:193], v[98:101]
	v_mfma_i32_16x16x64_i8 v[42:45], v[160:163], v[190:193], v[42:45]
	v_mfma_i32_16x16x64_i8 v[90:93], v[152:155], v[200:203], v[90:93]
	v_mfma_i32_16x16x64_i8 v[34:37], v[160:163], v[200:203], v[34:37]
	s_barrier
; #define PG8_STAGE(bufoff, gbase, unused) do { _Pragma("unroll") for (int _i = 0; _i < 2; ++_i) \
;         __builtin_amdgcn_global_load_lds((const unsigned*)((const char*)(gbase) + voff + _i * 8192), (LAS unsigned*)(lds + (bufoff) + ldsw + _i * 8192), 16, 0, 0); } while (0)
; #define PG8_LDA(dst, b, h) do { _Pragma("unroll") for (int m = 0; m < 4; ++m) _Pragma("unroll") for (int k = 0; k < 2; ++k) dst[m][k] = *(const LAS bf16x8*)(lds + PG8_SA(b, h) + aoff + m * 2048 + (FP8 ? k * 16 : k * 1024)); } while (0)
; #define PG8_LDB(dst, b, h) do { _Pragma("unroll") for (int n = 0; n < 2; ++n) _Pragma("unroll") for (int k = 0; k < 2; ++k) dst[n][k] = *(const LAS bf16x8*)(lds + PG8_SB(b, h) + boff + n * 2048 + (FP8 ? k * 16 : k * 1024)); } while (0)
; template <class Epi, class Sched, bool ALIGN_EPI, bool SP2, int MODE  >
; __device__ __forceinline__ void gemm_phase(LAS unsigned char* lds, const Gemm g, const Sched S, const Epi E, unsigned long long& probe_acc, int epi_id, int wv) {
;     ...
;         for (int t = 0; t < nt; t += 2) {
;             const bool last = (t == nt - 2);
;             const char* a1 = cA + (size_t)(t + 1) * kstep;
;             const char* a2 = last ? nA : cA + (size_t)(t + 2) * kstep; const char* b2 = last ? nB : cB + (size_t)(t + 2) * kstep;
;             const char* a3 = a2 + kstep; const char* b3 = b2 + kstep;
;             if constexpr (SP2) {
;             PG8_LDB(B0, 0, 0); PG8_LDB(B1, 0, 1); PG8_SCHED; PG8_LDA(At, 0, 0); PG8_STAGE(PG8_SA(1, 1), a1 + hA, voffA);
;             PG8_WAIT_V(8); PG8_WAIT_L(0); PG8_BAR; PG8_MMA(0, 0, At, B0); PG8_MMA(0, 1, At, B1); PG8_BAR; PG8_SCHED;
;             PG8_LDA(At, 0, 1); PG8_STAGE(PG8_SB(0, 0), b2, voffB); PG8_STAGE(PG8_SB(0, 1), b2 + hB, voffB); PG8_STAGE(PG8_SA(0, 0), a2, voffA);
;             PG8_WAIT_V(8); PG8_WAIT_L(0); PG8_BAR; PG8_MMA(1, 0, At, B0); PG8_MMA(1, 1, At, B1); PG8_BAR; PG8_SCHED;
;             PG8_LDB(B0, 1, 0); PG8_LDB(B1, 1, 1); PG8_SCHED; PG8_LDA(At, 1, 0); PG8_STAGE(PG8_SA(0, 1), a2 + hA, voffA);
;             PG8_WAIT_V(8); PG8_WAIT_L(0); PG8_BAR; PG8_MMA(0, 0, At, B0); PG8_MMA(0, 1, At, B1); PG8_BAR; PG8_SCHED;
;             PG8_LDA(At, 1, 1); PG8_STAGE(PG8_SB(1, 0), b3, voffB); PG8_STAGE(PG8_SB(1, 1), b3 + hB, voffB); PG8_STAGE(PG8_SA(1, 0), a3, voffA);
;             PG8_WAIT_V(8); PG8_WAIT_L(0); PG8_BAR; PG8_MMA(1, 0, At, B0); PG8_MMA(1, 1, At, B1); PG8_BAR; PG8_SCHED;
	s_mov_b32 m0, s91
	v_lshl_add_u64 v[206:207], v[184:185], 0, s[76:77]
	ds_read_b128 v[164:167], v213 offset:49152
	ds_read_b128 v[168:171], v213 offset:50176
	ds_read_b128 v[172:175], v213 offset:51200
	ds_read_b128 v[176:179], v213 offset:52224
	ds_read_b128 v[180:183], v213 offset:53248
	ds_read_b128 v[190:193], v213 offset:54272
	ds_read_b128 v[196:199], v213 offset:55296
	ds_read_b128 v[200:203], v213 offset:56320
	global_load_lds_dwordx4 v[206:207], off
	v_lshl_add_u64 v[206:207], v[184:185], 0, s[78:79]
	s_mov_b32 m0, s92
	s_nop 0
	global_load_lds_dwordx4 v[206:207], off
	v_lshl_add_u64 v[206:207], v[184:185], 0, s[80:81]
	s_mov_b32 m0, s2
	v_lshl_add_u64 v[184:185], v[184:185], 0, s[82:83]
	global_load_lds_dwordx4 v[206:207], off
	s_mov_b32 m0, s3
	s_nop 0
	global_load_lds_dwordx4 v[184:185], off
	v_lshl_add_u64 v[184:185], v[204:205], 0, s[76:77]
	s_mov_b32 m0, s93
	s_nop 0
	global_load_lds_dwordx4 v[184:185], off
	v_lshl_add_u64 v[184:185], v[204:205], 0, s[78:79]
	s_mov_b32 m0, s94
	s_nop 0
	global_load_lds_dwordx4 v[184:185], off
	s_waitcnt vmcnt(8)
	s_waitcnt lgkmcnt(0)
	s_barrier
	v_mfma_i32_16x16x64_i8 v[86:89], v[132:135], v[164:167], v[86:89]
	v_mfma_i32_16x16x64_i8 v[30:33], v[140:143], v[164:167], v[30:33]
	v_mfma_i32_16x16x64_i8 v[78:81], v[132:135], v[172:175], v[78:81]
	v_mfma_i32_16x16x64_i8 v[22:25], v[140:143], v[172:175], v[22:25]
	v_mfma_i32_16x16x64_i8 v[70:73], v[132:135], v[180:183], v[70:73]
	v_mfma_i32_16x16x64_i8 v[14:17], v[140:143], v[180:183], v[14:17]
	v_mfma_i32_16x16x64_i8 v[62:65], v[132:135], v[196:199], v[62:65]
	v_mfma_i32_16x16x64_i8 v[2:5], v[140:143], v[196:199], v[2:5]
	v_mfma_i32_16x16x64_i8 v[86:89], v[136:139], v[168:171], v[86:89]
	v_mfma_i32_16x16x64_i8 v[30:33], v[144:147], v[168:171], v[30:33]
	v_mfma_i32_16x16x64_i8 v[78:81], v[136:139], v[176:179], v[78:81]
	v_mfma_i32_16x16x64_i8 v[22:25], v[144:147], v[176:179], v[22:25]
	v_mfma_i32_16x16x64_i8 v[70:73], v[136:139], v[190:193], v[70:73]
	v_mfma_i32_16x16x64_i8 v[14:17], v[144:147], v[190:193], v[14:17]
	v_mfma_i32_16x16x64_i8 v[62:65], v[136:139], v[200:203], v[62:65]
	v_mfma_i32_16x16x64_i8 v[2:5], v[144:147], v[200:203], v[2:5]
	v_mfma_i32_16x16x64_i8 v[66:69], v[148:151], v[164:167], v[66:69]
	v_mfma_i32_16x16x64_i8 v[26:29], v[156:159], v[164:167], v[26:29]
	v_mfma_i32_16x16x64_i8 v[58:61], v[148:151], v[172:175], v[58:61]
	v_mfma_i32_16x16x64_i8 v[18:21], v[156:159], v[172:175], v[18:21]
	v_mfma_i32_16x16x64_i8 v[54:57], v[148:151], v[180:183], v[54:57]
	v_mfma_i32_16x16x64_i8 v[10:13], v[156:159], v[180:183], v[10:13]
	v_mfma_i32_16x16x64_i8 v[50:53], v[148:151], v[196:199], v[50:53]
	v_mfma_i32_16x16x64_i8 v[6:9], v[156:159], v[196:199], v[6:9]
	v_mfma_i32_16x16x64_i8 v[66:69], v[152:155], v[168:171], v[66:69]
	v_mfma_i32_16x16x64_i8 v[26:29], v[160:163], v[168:171], v[26:29]
	v_mfma_i32_16x16x64_i8 v[58:61], v[152:155], v[176:179], v[58:61]
	v_mfma_i32_16x16x64_i8 v[18:21], v[160:163], v[176:179], v[18:21]
	v_mfma_i32_16x16x64_i8 v[54:57], v[152:155], v[190:193], v[54:57]
	v_mfma_i32_16x16x64_i8 v[10:13], v[160:163], v[190:193], v[10:13]
	v_mfma_i32_16x16x64_i8 v[50:53], v[152:155], v[200:203], v[50:53]
	v_mfma_i32_16x16x64_i8 v[6:9], v[160:163], v[200:203], v[6:9]
	s_barrier
	s_add_i32 s14, s14, 2
	s_add_u32 s16, s16, 0x8000
	s_addc_u32 s17, s17, 0
	s_cmp_gt_u32 s14, 13
	s_mov_b64 s[28:29], s[30:31]
	v_readlane_b32 s98, v254, 1
	s_nop 3
	s_cmp_ge_u32 s98, 4
	s_cbranch_scc0 .Lprio_skip_0
	s_setprio 1
.Lprio_skip_0:
.LBB0_326:
	v_add_u32_e32 v0, s39, v212
	ds_read_b128 v[132:135], v0
	ds_read_b128 v[136:139], v0 offset:1024
	ds_read_b128 v[140:143], v0 offset:2048
	ds_read_b128 v[144:147], v0 offset:3072
	v_add_u32_e32 v0, s65, v212
	ds_read_b128 v[148:151], v0
	ds_read_b128 v[152:155], v0 offset:1024
	ds_read_b128 v[156:159], v0 offset:2048
	ds_read_b128 v[160:163], v0 offset:3072
	s_add_u32 s30, s28, 0x8000
	s_addc_u32 s31, s29, 0
	s_cmp_eq_u32 s14, 12
	s_cselect_b32 s23, s27, s31
	s_cselect_b32 s22, s46, s30
	s_cselect_b32 s21, vcc_lo, s17
	s_cselect_b32 s20, vcc_hi, s16
	v_lshl_add_u64 v[184:185], s[28:29], 0, v[130:131]
	v_lshl_add_u64 v[204:205], v[184:185], 0, s[80:81]
	s_add_i32 m0, s85, 0xc000
	ds_read_b128 v[164:167], v213
	ds_read_b128 v[168:171], v213 offset:1024
	ds_read_b128 v[172:175], v213 offset:2048
	ds_read_b128 v[176:179], v213 offset:3072
	ds_read_b128 v[180:183], v213 offset:4096
	ds_read_b128 v[190:193], v213 offset:5120
	ds_read_b128 v[196:199], v213 offset:6144
	ds_read_b128 v[200:203], v213 offset:7168
	global_load_lds_dwordx4 v[204:205], off
	v_lshl_add_u64 v[184:185], v[184:185], 0, s[82:83]
	s_add_i32 m0, s85, 0xe000
	s_nop 0
	global_load_lds_dwordx4 v[184:185], off
	s_waitcnt vmcnt(8)
	s_waitcnt lgkmcnt(0)
	s_barrier
; #define PG8_STAGE(bufoff, gbase, unused) do { _Pragma("unroll") for (int _i = 0; _i < 2; ++_i) \
;         __builtin_amdgcn_global_load_lds((const unsigned*)((const char*)(gbase) + voff + _i * 8192), (LAS unsigned*)(lds + (bufoff) + ldsw + _i * 8192), 16, 0, 0); } while (0)
; #define PG8_LDA(dst, b, h) do { _Pragma("unroll") for (int m = 0; m < 4; ++m) _Pragma("unroll") for (int k = 0; k < 2; ++k) dst[m][k] = *(const LAS bf16x8*)(lds + PG8_SA(b, h) + aoff + m * 2048 + (FP8 ? k * 16 : k * 1024)); } while (0)
; #define PG8_WAIT_V(n) asm volatile("s_waitcnt vmcnt(" #n ")" ::: "memory")
; #define PG8_WAIT_L(n) asm volatile("s_waitcnt lgkmcnt(" #n ")" ::: "memory")
; #define PG8_BAR __builtin_amdgcn_s_barrier()
; #define PG8_SCHED __builtin_amdgcn_sched_barrier(0)
; template <class Epi, class Sched, bool ALIGN_EPI, bool SP2, int MODE  >
; __device__ __forceinline__ void gemm_phase(LAS unsigned char* lds, const Gemm g, const Sched S, const Epi E, unsigned long long& probe_acc, int epi_id, int wv) {
;     ...
;             PG8_WAIT_V(8); PG8_WAIT_L(0); PG8_BAR; PG8_MMA(0, 0, At, B0); PG8_MMA(0, 1, At, B1); PG8_BAR; PG8_SCHED;
;             PG8_LDA(At, 0, 1); PG8_STAGE(PG8_SB(0, 0), b2, voffB); PG8_STAGE(PG8_SB(0, 1), b2 + hB, voffB); PG8_STAGE(PG8_SA(0, 0), a2, voffA);
;             PG8_WAIT_V(8); PG8_WAIT_L(0); PG8_BAR; PG8_MMA(1, 0, At, B0); PG8_MMA(1, 1, At, B1); PG8_BAR; PG8_SCHED;
	v_mfma_i32_16x16x64_i8 v[126:129], v[132:135], v[164:167], v[126:129]
	v_mfma_i32_16x16x64_i8 v[102:105], v[140:143], v[164:167], v[102:105]
	v_mfma_i32_16x16x64_i8 v[122:125], v[132:135], v[172:175], v[122:125]
	v_mfma_i32_16x16x64_i8 v[94:97], v[140:143], v[172:175], v[94:97]
	v_mfma_i32_16x16x64_i8 v[118:121], v[132:135], v[180:183], v[118:121]
	v_mfma_i32_16x16x64_i8 v[46:49], v[140:143], v[180:183], v[46:49]
	v_mfma_i32_16x16x64_i8 v[110:113], v[132:135], v[196:199], v[110:113]
	v_mfma_i32_16x16x64_i8 v[38:41], v[140:143], v[196:199], v[38:41]
	v_mfma_i32_16x16x64_i8 v[126:129], v[136:139], v[168:171], v[126:129]
	v_mfma_i32_16x16x64_i8 v[102:105], v[144:147], v[168:171], v[102:105]
	v_mfma_i32_16x16x64_i8 v[122:125], v[136:139], v[176:179], v[122:125]
	v_mfma_i32_16x16x64_i8 v[94:97], v[144:147], v[176:179], v[94:97]
	v_mfma_i32_16x16x64_i8 v[118:121], v[136:139], v[190:193], v[118:121]
	v_mfma_i32_16x16x64_i8 v[46:49], v[144:147], v[190:193], v[46:49]
	v_mfma_i32_16x16x64_i8 v[110:113], v[136:139], v[200:203], v[110:113]
	v_mfma_i32_16x16x64_i8 v[38:41], v[144:147], v[200:203], v[38:41]
	v_mfma_i32_16x16x64_i8 v[114:117], v[148:151], v[164:167], v[114:117]
	v_mfma_i32_16x16x64_i8 v[82:85], v[156:159], v[164:167], v[82:85]
	v_mfma_i32_16x16x64_i8 v[106:109], v[148:151], v[172:175], v[106:109]
	v_mfma_i32_16x16x64_i8 v[74:77], v[156:159], v[172:175], v[74:77]
	v_mfma_i32_16x16x64_i8 v[98:101], v[148:151], v[180:183], v[98:101]
	v_mfma_i32_16x16x64_i8 v[42:45], v[156:159], v[180:183], v[42:45]
	v_mfma_i32_16x16x64_i8 v[90:93], v[148:151], v[196:199], v[90:93]
	v_mfma_i32_16x16x64_i8 v[34:37], v[156:159], v[196:199], v[34:37]
	v_mfma_i32_16x16x64_i8 v[114:117], v[152:155], v[168:171], v[114:117]
	v_mfma_i32_16x16x64_i8 v[82:85], v[160:163], v[168:171], v[82:85]
	v_mfma_i32_16x16x64_i8 v[106:109], v[152:155], v[176:179], v[106:109]
	v_mfma_i32_16x16x64_i8 v[74:77], v[160:163], v[176:179], v[74:77]
	v_mfma_i32_16x16x64_i8 v[98:101], v[152:155], v[190:193], v[98:101]
	v_mfma_i32_16x16x64_i8 v[42:45], v[160:163], v[190:193], v[42:45]
	v_mfma_i32_16x16x64_i8 v[90:93], v[152:155], v[200:203], v[90:93]
	v_mfma_i32_16x16x64_i8 v[34:37], v[160:163], v[200:203], v[34:37]
	s_barrier
	s_mov_b32 m0, s41
	v_lshl_add_u64 v[184:185], s[20:21], 0, v[130:131]
	ds_read_b128 v[164:167], v213 offset:16384
	ds_read_b128 v[168:171], v213 offset:17408
	ds_read_b128 v[172:175], v213 offset:18432
	ds_read_b128 v[176:179], v213 offset:19456
	ds_read_b128 v[180:183], v213 offset:20480
	ds_read_b128 v[190:193], v213 offset:21504
	ds_read_b128 v[196:199], v213 offset:22528
	ds_read_b128 v[200:203], v213 offset:23552
	global_load_lds_dwordx4 v[184:185], off
	v_lshl_add_u64 v[204:205], v[184:185], 0, s[70:71]
	s_mov_b32 m0, s64
	s_nop 0
	global_load_lds_dwordx4 v[204:205], off
	v_lshl_add_u64 v[204:205], v[184:185], 0, s[72:73]
	s_mov_b32 m0, s68
	s_nop 0
	global_load_lds_dwordx4 v[204:205], off
	v_lshl_add_u64 v[204:205], v[184:185], 0, s[74:75]
	s_mov_b32 m0, s84
	s_nop 0
	global_load_lds_dwordx4 v[204:205], off
	v_lshl_add_u64 v[204:205], s[22:23], 0, v[130:131]
	s_mov_b32 m0, s85
	v_lshl_add_u64 v[206:207], v[204:205], 0, s[70:71]
	global_load_lds_dwordx4 v[204:205], off
	s_mov_b32 m0, s86
	s_nop 0
	global_load_lds_dwordx4 v[206:207], off
	s_waitcnt vmcnt(8)
	s_waitcnt lgkmcnt(0)
	s_barrier
	v_mfma_i32_16x16x64_i8 v[86:89], v[132:135], v[164:167], v[86:89]
	v_mfma_i32_16x16x64_i8 v[30:33], v[140:143], v[164:167], v[30:33]
	v_mfma_i32_16x16x64_i8 v[78:81], v[132:135], v[172:175], v[78:81]
	v_mfma_i32_16x16x64_i8 v[22:25], v[140:143], v[172:175], v[22:25]
	v_mfma_i32_16x16x64_i8 v[70:73], v[132:135], v[180:183], v[70:73]
	v_mfma_i32_16x16x64_i8 v[14:17], v[140:143], v[180:183], v[14:17]
	v_mfma_i32_16x16x64_i8 v[62:65], v[132:135], v[196:199], v[62:65]
	v_mfma_i32_16x16x64_i8 v[2:5], v[140:143], v[196:199], v[2:5]
	v_mfma_i32_16x16x64_i8 v[86:89], v[136:139], v[168:171], v[86:89]
	v_mfma_i32_16x16x64_i8 v[30:33], v[144:147], v[168:171], v[30:33]
	v_mfma_i32_16x16x64_i8 v[78:81], v[136:139], v[176:179], v[78:81]
	v_mfma_i32_16x16x64_i8 v[22:25], v[144:147], v[176:179], v[22:25]
	v_mfma_i32_16x16x64_i8 v[70:73], v[136:139], v[190:193], v[70:73]
	v_mfma_i32_16x16x64_i8 v[14:17], v[144:147], v[190:193], v[14:17]
	v_mfma_i32_16x16x64_i8 v[62:65], v[136:139], v[200:203], v[62:65]
	v_mfma_i32_16x16x64_i8 v[2:5], v[144:147], v[200:203], v[2:5]
	v_mfma_i32_16x16x64_i8 v[66:69], v[148:151], v[164:167], v[66:69]
	v_mfma_i32_16x16x64_i8 v[26:29], v[156:159], v[164:167], v[26:29]
	v_mfma_i32_16x16x64_i8 v[58:61], v[148:151], v[172:175], v[58:61]
	v_mfma_i32_16x16x64_i8 v[18:21], v[156:159], v[172:175], v[18:21]
	v_mfma_i32_16x16x64_i8 v[54:57], v[148:151], v[180:183], v[54:57]
	v_mfma_i32_16x16x64_i8 v[10:13], v[156:159], v[180:183], v[10:13]
	v_mfma_i32_16x16x64_i8 v[50:53], v[148:151], v[196:199], v[50:53]
	v_mfma_i32_16x16x64_i8 v[6:9], v[156:159], v[196:199], v[6:9]
	v_mfma_i32_16x16x64_i8 v[66:69], v[152:155], v[168:171], v[66:69]
	v_mfma_i32_16x16x64_i8 v[26:29], v[160:163], v[168:171], v[26:29]
	v_mfma_i32_16x16x64_i8 v[58:61], v[152:155], v[176:179], v[58:61]
	v_mfma_i32_16x16x64_i8 v[18:21], v[160:163], v[176:179], v[18:21]
	v_mfma_i32_16x16x64_i8 v[54:57], v[152:155], v[190:193], v[54:57]
	v_mfma_i32_16x16x64_i8 v[10:13], v[160:163], v[190:193], v[10:13]
	v_mfma_i32_16x16x64_i8 v[50:53], v[152:155], v[200:203], v[50:53]
	v_mfma_i32_16x16x64_i8 v[6:9], v[160:163], v[200:203], v[6:9]
	s_barrier
; #define PG8_STAGE(bufoff, gbase, unused) do { _Pragma("unroll") for (int _i = 0; _i < 2; ++_i) \
;         __builtin_amdgcn_global_load_lds((const unsigned*)((const char*)(gbase) + voff + _i * 8192), (LAS unsigned*)(lds + (bufoff) + ldsw + _i * 8192), 16, 0, 0); } while (0)
; #define PG8_LDA(dst, b, h) do { _Pragma("unroll") for (int m = 0; m < 4; ++m) _Pragma("unroll") for (int k = 0; k < 2; ++k) dst[m][k] = *(const LAS bf16x8*)(lds + PG8_SA(b, h) + aoff + m * 2048 + (FP8 ? k * 16 : k * 1024)); } while (0)
; #define PG8_LDB(dst, b, h) do { _Pragma("unroll") for (int n = 0; n < 2; ++n) _Pragma("unroll") for (int k = 0; k < 2; ++k) dst[n][k] = *(const LAS bf16x8*)(lds + PG8_SB(b, h) + boff + n * 2048 + (FP8 ? k * 16 : k * 1024)); } while (0)
; #define PG8_WAIT_V(n) asm volatile("s_waitcnt vmcnt(" #n ")" ::: "memory")
; #define PG8_WAIT_L(n) asm volatile("s_waitcnt lgkmcnt(" #n ")" ::: "memory")
; #define PG8_BAR __builtin_amdgcn_s_barrier()
; #define PG8_SCHED __builtin_amdgcn_sched_barrier(0)
; template <class Epi, class Sched, bool ALIGN_EPI, bool SP2, int MODE  >
; __device__ __forceinline__ void gemm_phase(LAS unsigned char* lds, const Gemm g, const Sched S, const Epi E, unsigned long long& probe_acc, int epi_id, int wv) {
;     ...
;             PG8_WAIT_V(8); PG8_WAIT_L(0); PG8_BAR; PG8_MMA(1, 0, At, B0); PG8_MMA(1, 1, At, B1); PG8_BAR; PG8_SCHED;
;             PG8_LDB(B0, 1, 0); PG8_LDB(B1, 1, 1); PG8_SCHED; PG8_LDA(At, 1, 0); PG8_STAGE(PG8_SA(0, 1), a2 + hA, voffA);
;             PG8_WAIT_V(8); PG8_WAIT_L(0); PG8_BAR; PG8_MMA(0, 0, At, B0); PG8_MMA(0, 1, At, B1); PG8_BAR; PG8_SCHED;
;             PG8_LDA(At, 1, 1); PG8_STAGE(PG8_SB(1, 0), b3, voffB); PG8_STAGE(PG8_SB(1, 1), b3 + hB, voffB); PG8_STAGE(PG8_SA(1, 0), a3, voffA);
;             PG8_WAIT_V(8); PG8_WAIT_L(0); PG8_BAR; PG8_MMA(1, 0, At, B0); PG8_MMA(1, 1, At, B1); PG8_BAR; PG8_SCHED;
	v_add_u32_e32 v0, s90, v212
	ds_read_b128 v[132:135], v0
	ds_read_b128 v[136:139], v0 offset:1024
	ds_read_b128 v[140:143], v0 offset:2048
	ds_read_b128 v[144:147], v0 offset:3072
	v_add_u32_e32 v0, s95, v212
	ds_read_b128 v[148:151], v0
	ds_read_b128 v[152:155], v0 offset:1024
	ds_read_b128 v[156:159], v0 offset:2048
	ds_read_b128 v[160:163], v0 offset:3072
	s_mov_b32 m0, s87
	v_lshl_add_u64 v[206:207], v[204:205], 0, s[72:73]
	ds_read_b128 v[164:167], v213 offset:32768
	ds_read_b128 v[168:171], v213 offset:33792
	ds_read_b128 v[172:175], v213 offset:34816
	ds_read_b128 v[176:179], v213 offset:35840
	ds_read_b128 v[180:183], v213 offset:36864
	ds_read_b128 v[190:193], v213 offset:37888
	ds_read_b128 v[196:199], v213 offset:38912
	ds_read_b128 v[200:203], v213 offset:39936
	global_load_lds_dwordx4 v[206:207], off
	v_lshl_add_u64 v[206:207], v[204:205], 0, s[74:75]
	s_mov_b32 m0, s88
	s_nop 0
	global_load_lds_dwordx4 v[206:207], off
	s_waitcnt vmcnt(8)
	s_waitcnt lgkmcnt(0)
	s_barrier
	v_mfma_i32_16x16x64_i8 v[126:129], v[132:135], v[164:167], v[126:129]
	v_mfma_i32_16x16x64_i8 v[102:105], v[140:143], v[164:167], v[102:105]
	v_mfma_i32_16x16x64_i8 v[122:125], v[132:135], v[172:175], v[122:125]
	v_mfma_i32_16x16x64_i8 v[94:97], v[140:143], v[172:175], v[94:97]
	v_mfma_i32_16x16x64_i8 v[118:121], v[132:135], v[180:183], v[118:121]
	v_mfma_i32_16x16x64_i8 v[46:49], v[140:143], v[180:183], v[46:49]
	v_mfma_i32_16x16x64_i8 v[110:113], v[132:135], v[196:199], v[110:113]
	v_mfma_i32_16x16x64_i8 v[38:41], v[140:143], v[196:199], v[38:41]
	v_mfma_i32_16x16x64_i8 v[126:129], v[136:139], v[168:171], v[126:129]
	v_mfma_i32_16x16x64_i8 v[102:105], v[144:147], v[168:171], v[102:105]
	v_mfma_i32_16x16x64_i8 v[122:125], v[136:139], v[176:179], v[122:125]
	v_mfma_i32_16x16x64_i8 v[94:97], v[144:147], v[176:179], v[94:97]
	v_mfma_i32_16x16x64_i8 v[118:121], v[136:139], v[190:193], v[118:121]
	v_mfma_i32_16x16x64_i8 v[46:49], v[144:147], v[190:193], v[46:49]
	v_mfma_i32_16x16x64_i8 v[110:113], v[136:139], v[200:203], v[110:113]
	v_mfma_i32_16x16x64_i8 v[38:41], v[144:147], v[200:203], v[38:41]
	v_mfma_i32_16x16x64_i8 v[114:117], v[148:151], v[164:167], v[114:117]
	v_mfma_i32_16x16x64_i8 v[82:85], v[156:159], v[164:167], v[82:85]
	v_mfma_i32_16x16x64_i8 v[106:109], v[148:151], v[172:175], v[106:109]
	v_mfma_i32_16x16x64_i8 v[74:77], v[156:159], v[172:175], v[74:77]
	v_mfma_i32_16x16x64_i8 v[98:101], v[148:151], v[180:183], v[98:101]
	v_mfma_i32_16x16x64_i8 v[42:45], v[156:159], v[180:183], v[42:45]
	v_mfma_i32_16x16x64_i8 v[90:93], v[148:151], v[196:199], v[90:93]
	v_mfma_i32_16x16x64_i8 v[34:37], v[156:159], v[196:199], v[34:37]
	v_mfma_i32_16x16x64_i8 v[114:117], v[152:155], v[168:171], v[114:117]
	v_mfma_i32_16x16x64_i8 v[82:85], v[160:163], v[168:171], v[82:85]
	v_mfma_i32_16x16x64_i8 v[106:109], v[152:155], v[176:179], v[106:109]
	v_mfma_i32_16x16x64_i8 v[74:77], v[160:163], v[176:179], v[74:77]
	v_mfma_i32_16x16x64_i8 v[98:101], v[152:155], v[190:193], v[98:101]
	v_mfma_i32_16x16x64_i8 v[42:45], v[160:163], v[190:193], v[42:45]
	v_mfma_i32_16x16x64_i8 v[90:93], v[152:155], v[200:203], v[90:93]
	v_mfma_i32_16x16x64_i8 v[34:37], v[160:163], v[200:203], v[34:37]
	s_barrier
	s_mov_b32 m0, s91
	v_lshl_add_u64 v[206:207], v[184:185], 0, s[76:77]
	ds_read_b128 v[164:167], v213 offset:49152
	ds_read_b128 v[168:171], v213 offset:50176
	ds_read_b128 v[172:175], v213 offset:51200
	ds_read_b128 v[176:179], v213 offset:52224
	ds_read_b128 v[180:183], v213 offset:53248
	ds_read_b128 v[190:193], v213 offset:54272
	ds_read_b128 v[196:199], v213 offset:55296
	ds_read_b128 v[200:203], v213 offset:56320
	global_load_lds_dwordx4 v[206:207], off
	v_lshl_add_u64 v[206:207], v[184:185], 0, s[78:79]
	s_mov_b32 m0, s92
	s_nop 0
	global_load_lds_dwordx4 v[206:207], off
	v_lshl_add_u64 v[206:207], v[184:185], 0, s[80:81]
	s_mov_b32 m0, s2
	v_lshl_add_u64 v[184:185], v[184:185], 0, s[82:83]
	global_load_lds_dwordx4 v[206:207], off
	s_mov_b32 m0, s3
	s_nop 0
	global_load_lds_dwordx4 v[184:185], off
	v_lshl_add_u64 v[184:185], v[204:205], 0, s[76:77]
	s_mov_b32 m0, s93
	s_nop 0
	global_load_lds_dwordx4 v[184:185], off
	v_lshl_add_u64 v[184:185], v[204:205], 0, s[78:79]
	s_mov_b32 m0, s94
	s_nop 0
	global_load_lds_dwordx4 v[184:185], off
	s_waitcnt vmcnt(8)
	s_waitcnt lgkmcnt(0)
	s_barrier
	v_mfma_i32_16x16x64_i8 v[86:89], v[132:135], v[164:167], v[86:89]
	v_mfma_i32_16x16x64_i8 v[30:33], v[140:143], v[164:167], v[30:33]
	v_mfma_i32_16x16x64_i8 v[78:81], v[132:135], v[172:175], v[78:81]
	v_mfma_i32_16x16x64_i8 v[22:25], v[140:143], v[172:175], v[22:25]
	v_mfma_i32_16x16x64_i8 v[70:73], v[132:135], v[180:183], v[70:73]
	v_mfma_i32_16x16x64_i8 v[14:17], v[140:143], v[180:183], v[14:17]
	v_mfma_i32_16x16x64_i8 v[62:65], v[132:135], v[196:199], v[62:65]
	v_mfma_i32_16x16x64_i8 v[2:5], v[140:143], v[196:199], v[2:5]
	v_mfma_i32_16x16x64_i8 v[86:89], v[136:139], v[168:171], v[86:89]
	v_mfma_i32_16x16x64_i8 v[30:33], v[144:147], v[168:171], v[30:33]
	v_mfma_i32_16x16x64_i8 v[78:81], v[136:139], v[176:179], v[78:81]
	v_mfma_i32_16x16x64_i8 v[22:25], v[144:147], v[176:179], v[22:25]
	v_mfma_i32_16x16x64_i8 v[70:73], v[136:139], v[190:193], v[70:73]
	v_mfma_i32_16x16x64_i8 v[14:17], v[144:147], v[190:193], v[14:17]
	v_mfma_i32_16x16x64_i8 v[62:65], v[136:139], v[200:203], v[62:65]
	v_mfma_i32_16x16x64_i8 v[2:5], v[144:147], v[200:203], v[2:5]
	v_mfma_i32_16x16x64_i8 v[66:69], v[148:151], v[164:167], v[66:69]
	v_mfma_i32_16x16x64_i8 v[26:29], v[156:159], v[164:167], v[26:29]
	v_mfma_i32_16x16x64_i8 v[58:61], v[148:151], v[172:175], v[58:61]
	v_mfma_i32_16x16x64_i8 v[18:21], v[156:159], v[172:175], v[18:21]
	v_mfma_i32_16x16x64_i8 v[54:57], v[148:151], v[180:183], v[54:57]
	v_mfma_i32_16x16x64_i8 v[10:13], v[156:159], v[180:183], v[10:13]
	v_mfma_i32_16x16x64_i8 v[50:53], v[148:151], v[196:199], v[50:53]
	v_mfma_i32_16x16x64_i8 v[6:9], v[156:159], v[196:199], v[6:9]
	v_mfma_i32_16x16x64_i8 v[66:69], v[152:155], v[168:171], v[66:69]
	v_mfma_i32_16x16x64_i8 v[26:29], v[160:163], v[168:171], v[26:29]
	v_mfma_i32_16x16x64_i8 v[58:61], v[152:155], v[176:179], v[58:61]
	v_mfma_i32_16x16x64_i8 v[18:21], v[160:163], v[176:179], v[18:21]
	v_mfma_i32_16x16x64_i8 v[54:57], v[152:155], v[190:193], v[54:57]
	v_mfma_i32_16x16x64_i8 v[10:13], v[160:163], v[190:193], v[10:13]
	v_mfma_i32_16x16x64_i8 v[50:53], v[152:155], v[200:203], v[50:53]
	v_mfma_i32_16x16x64_i8 v[6:9], v[160:163], v[200:203], v[6:9]
	s_barrier
	s_add_i32 s14, s14, 2
	s_add_u32 s16, s16, 0x8000
	s_addc_u32 s17, s17, 0
	s_cmp_gt_u32 s14, 13
	s_mov_b64 s[28:29], s[30:31]
	s_cbranch_scc0 .LBB0_326
	v_readlane_b32 s14, v255, 11
	v_readlane_b32 s15, v255, 12
	s_and_b64 vcc, exec, s[14:15]
	s_cbranch_vccz .LBB0_329
	s_barrier

;     __device__ __forceinline__ bool next(int i, Unit& u) const { const int off = i * H + (r >> 1); if (off >= 8 * nN) return false; u.pm = 16 * g + 8 * (r & 1) + (off & 7); u.pn = off >> 3; return true; }
; #define PG8_STAGE(bufoff, gbase, unused) do { _Pragma("unroll") for (int _i = 0; _i < 2; ++_i) \
;         __builtin_amdgcn_global_load_lds((const unsigned*)((const char*)(gbase) + voff + _i * 8192), (LAS unsigned*)(lds + (bufoff) + ldsw + _i * 8192), 16, 0, 0); } while (0)
; #define PG8_LDA(dst, b, h) do { _Pragma("unroll") for (int m = 0; m < 4; ++m) _Pragma("unroll") for (int k = 0; k < 2; ++k) dst[m][k] = *(const LAS bf16x8*)(lds + PG8_SA(b, h) + aoff + m * 2048 + (FP8 ? k * 16 : k * 1024)); } while (0)
; #define PG8_LDB(dst, b, h) do { _Pragma("unroll") for (int n = 0; n < 2; ++n) _Pragma("unroll") for (int k = 0; k < 2; ++k) dst[n][k] = *(const LAS bf16x8*)(lds + PG8_SB(b, h) + boff + n * 2048 + (FP8 ? k * 16 : k * 1024)); } while (0)
; #define PG8_BAR __builtin_amdgcn_s_barrier()
; template <class Epi, class Sched, bool ALIGN_EPI, bool SP2, int MODE  >
; __device__ __forceinline__ void gemm_phase(LAS unsigned char* lds, const Gemm g, const Sched S, const Epi E, unsigned long long& probe_acc, int epi_id, int wv) {
;     ...
;         const bool has_next = S.next(ui + 1, nxt);
;         const char* nA = has_next ? (const char*)g.A + (size_t)nxt.pm * tA + (g.gt ? (size_t)(nxt.pn / g.gt) * gK2 : 0) : cA; const char* nB = has_next ? (const char*)g.Bt + (size_t)nxt.pn * tB : cB;
;         for (int t = 0; t < nt; t += 2) {
;             const bool last = (t == nt - 2);
;             const char* a1 = cA + (size_t)(t + 1) * kstep;
;             const char* a2 = last ? nA : cA + (size_t)(t + 2) * kstep; const char* b2 = last ? nB : cB + (size_t)(t + 2) * kstep;
;             const char* a3 = a2 + kstep; const char* b3 = b2 + kstep;
;             if constexpr (SP2) {
;             PG8_LDB(B0, 0, 0); PG8_LDB(B1, 0, 1); PG8_SCHED; PG8_LDA(At, 0, 0); PG8_STAGE(PG8_SA(1, 1), a1 + hA, voffA);
;             PG8_WAIT_V(8); PG8_WAIT_L(0); PG8_BAR; PG8_MMA(0, 0, At, B0); PG8_MMA(0, 1, At, B1); PG8_BAR; PG8_SCHED;
;             PG8_LDA(At, 0, 1); PG8_STAGE(PG8_SB(0, 0), b2, voffB); PG8_STAGE(PG8_SB(0, 1), b2 + hB, voffB); PG8_STAGE(PG8_SA(0, 0), a2, voffA);
;             PG8_WAIT_V(8); PG8_WAIT_L(0); PG8_BAR; PG8_MMA(1, 0, At, B0); PG8_MMA(1, 1, At, B1); PG8_BAR; PG8_SCHED;
.LBB0_364:
	s_mov_b64 s[20:21], s[4:5]
	s_add_i32 s84, s84, 1
	v_readlane_b32 s4, v254, 6
	s_mul_i32 s4, s84, s4
	v_readlane_b32 s5, v254, 35
	s_add_i32 s4, s4, s5
	s_cmpk_lt_i32 s4, 0xc0
	s_mov_b64 s[18:19], s[10:11]
	s_cselect_b64 s[16:17], -1, 0
	s_and_b32 s5, s4, 7
	v_readlane_b32 s10, v254, 18
	s_mov_b32 s8, s87
	s_mov_b32 s9, s86
	s_mov_b32 s88, s87
	s_mov_b32 s89, s86
	s_or_b32 s87, s5, s10
	s_ashr_i32 s86, s4, 3
	s_and_b64 s[4:5], s[16:17], exec
	s_cselect_b32 s10, s87, s8
	s_cselect_b32 s4, s86, s9
	s_ashr_i32 s11, s10, 31
	s_lshl_b64 s[10:11], s[10:11], 20
	s_add_u32 s10, s58, s10
	s_addc_u32 s11, s59, s11
	s_and_b64 s[90:91], s[16:17], exec
	s_cselect_b32 s46, s11, s19
	s_cselect_b32 s90, s10, s18
	s_ashr_i32 s5, s4, 31
	s_lshl_b64 s[4:5], s[4:5], 20
	s_add_u32 s4, s0, s4
	s_addc_u32 s5, s1, s5
	s_and_b64 s[92:93], s[16:17], exec
	s_cselect_b32 s91, s5, s21
	s_cselect_b32 s92, s4, s20
	s_add_u32 s93, s20, 0x8000
	s_addc_u32 s94, s21, 0
	s_mov_b32 s95, -2
	v_add_u32_e32 v0, s2, v166
	s_waitcnt vmcnt(0)
	ds_read_b128 v[130:133], v0
	ds_read_b128 v[134:137], v0 offset:1024
	ds_read_b128 v[138:141], v0 offset:2048
	ds_read_b128 v[142:145], v0 offset:3072
	v_add_u32_e32 v0, s23, v166
	ds_read_b128 v[146:149], v0
	ds_read_b128 v[150:153], v0 offset:1024
	s_waitcnt lgkmcnt(0)
	ds_read_b128 v[156:159], v0 offset:2048
	ds_read_b128 v[160:163], v0 offset:3072
	s_add_u32 s20, s18, 0x8000
	s_addc_u32 s21, s19, 0
	s_cmp_eq_u32 s95, 28
	s_cselect_b32 vcc_hi, s46, s21
	s_cselect_b32 vcc_lo, s90, s20
	s_cselect_b32 s9, s91, s94
	s_cselect_b32 s8, s92, s93
	v_lshl_add_u64 v[184:185], s[18:19], 0, v[154:155]
	v_lshl_add_u64 v[204:205], v[184:185], 0, s[52:53]
	s_add_i32 m0, s26, 0xc000
	ds_read_b128 v[168:171], v167
	ds_read_b128 v[172:175], v167 offset:1024
	ds_read_b128 v[176:179], v167 offset:2048
	ds_read_b128 v[180:183], v167 offset:3072
	ds_read_b128 v[188:191], v167 offset:4096
	ds_read_b128 v[192:195], v167 offset:5120
	ds_read_b128 v[196:199], v167 offset:6144
	ds_read_b128 v[200:203], v167 offset:7168
	global_load_lds_dwordx4 v[204:205], off
	v_lshl_add_u64 v[184:185], v[184:185], 0, s[54:55]
	s_add_i32 m0, s26, 0xe000
	s_nop 0
	global_load_lds_dwordx4 v[184:185], off
	s_waitcnt vmcnt(8)
	s_waitcnt lgkmcnt(0)
	s_barrier
	v_mfma_f32_16x16x32_bf16 v[126:129], v[130:133], v[168:171], 0
	v_mfma_f32_16x16x32_bf16 v[122:125], v[138:141], v[168:171], 0
	v_mfma_f32_16x16x32_bf16 v[110:113], v[130:133], v[176:179], 0
	v_mfma_f32_16x16x32_bf16 v[106:109], v[138:141], v[176:179], 0
	v_mfma_f32_16x16x32_bf16 v[94:97], v[130:133], v[188:191], 0
	v_mfma_f32_16x16x32_bf16 v[90:93], v[138:141], v[188:191], 0
	v_mfma_f32_16x16x32_bf16 v[78:81], v[130:133], v[196:199], 0
	v_mfma_f32_16x16x32_bf16 v[74:77], v[138:141], v[196:199], 0
	v_mfma_f32_16x16x32_bf16 v[126:129], v[134:137], v[172:175], v[126:129]
	v_mfma_f32_16x16x32_bf16 v[122:125], v[142:145], v[172:175], v[122:125]
	v_mfma_f32_16x16x32_bf16 v[110:113], v[134:137], v[180:183], v[110:113]
	v_mfma_f32_16x16x32_bf16 v[106:109], v[142:145], v[180:183], v[106:109]
	v_mfma_f32_16x16x32_bf16 v[94:97], v[134:137], v[192:195], v[94:97]
	v_mfma_f32_16x16x32_bf16 v[90:93], v[142:145], v[192:195], v[90:93]
	v_mfma_f32_16x16x32_bf16 v[78:81], v[134:137], v[200:203], v[78:81]
	v_mfma_f32_16x16x32_bf16 v[74:77], v[142:145], v[200:203], v[74:77]
	v_mfma_f32_16x16x32_bf16 v[118:121], v[146:149], v[168:171], 0
	v_mfma_f32_16x16x32_bf16 v[114:117], v[156:159], v[168:171], 0
	v_mfma_f32_16x16x32_bf16 v[102:105], v[146:149], v[176:179], 0
	v_mfma_f32_16x16x32_bf16 v[98:101], v[156:159], v[176:179], 0
	v_mfma_f32_16x16x32_bf16 v[86:89], v[146:149], v[188:191], 0
	v_mfma_f32_16x16x32_bf16 v[82:85], v[156:159], v[188:191], 0
	v_mfma_f32_16x16x32_bf16 v[70:73], v[146:149], v[196:199], 0
	v_mfma_f32_16x16x32_bf16 v[66:69], v[156:159], v[196:199], 0
	v_mfma_f32_16x16x32_bf16 v[118:121], v[150:153], v[172:175], v[118:121]
	v_mfma_f32_16x16x32_bf16 v[114:117], v[160:163], v[172:175], v[114:117]
	v_mfma_f32_16x16x32_bf16 v[102:105], v[150:153], v[180:183], v[102:105]
	v_mfma_f32_16x16x32_bf16 v[98:101], v[160:163], v[180:183], v[98:101]
	v_mfma_f32_16x16x32_bf16 v[86:89], v[150:153], v[192:195], v[86:89]
	v_mfma_f32_16x16x32_bf16 v[82:85], v[160:163], v[192:195], v[82:85]
	v_mfma_f32_16x16x32_bf16 v[70:73], v[150:153], v[200:203], v[70:73]
	v_mfma_f32_16x16x32_bf16 v[66:69], v[160:163], v[200:203], v[66:69]
	s_barrier
	s_mov_b32 m0, s3
	v_lshl_add_u64 v[184:185], s[8:9], 0, v[154:155]
	ds_read_b128 v[168:171], v167 offset:16384
	ds_read_b128 v[172:175], v167 offset:17408
	ds_read_b128 v[176:179], v167 offset:18432
	ds_read_b128 v[180:183], v167 offset:19456
	ds_read_b128 v[188:191], v167 offset:20480
	ds_read_b128 v[192:195], v167 offset:21504
	ds_read_b128 v[196:199], v167 offset:22528
	ds_read_b128 v[200:203], v167 offset:23552
	global_load_lds_dwordx4 v[184:185], off
	v_lshl_add_u64 v[204:205], v[184:185], 0, s[70:71]
	s_mov_b32 m0, s22
	s_nop 0
	global_load_lds_dwordx4 v[204:205], off
	v_lshl_add_u64 v[204:205], v[184:185], 0, s[96:97]
	s_mov_b32 m0, s24
	s_nop 0
	global_load_lds_dwordx4 v[204:205], off
	v_lshl_add_u64 v[204:205], v[184:185], 0, s[60:61]
	s_mov_b32 m0, s25
	s_nop 0
	global_load_lds_dwordx4 v[204:205], off
	v_lshl_add_u64 v[204:205], vcc, 0, v[154:155]
	s_mov_b32 m0, s26
	v_lshl_add_u64 v[206:207], v[204:205], 0, s[70:71]
	global_load_lds_dwordx4 v[204:205], off
	s_mov_b32 m0, s27
	s_nop 0
	global_load_lds_dwordx4 v[206:207], off
	s_waitcnt vmcnt(8)
	s_waitcnt lgkmcnt(0)
	s_barrier
; #define PG8_STAGE(bufoff, gbase, unused) do { _Pragma("unroll") for (int _i = 0; _i < 2; ++_i) \
;         __builtin_amdgcn_global_load_lds((const unsigned*)((const char*)(gbase) + voff + _i * 8192), (LAS unsigned*)(lds + (bufoff) + ldsw + _i * 8192), 16, 0, 0); } while (0)
; #define PG8_LDA(dst, b, h) do { _Pragma("unroll") for (int m = 0; m < 4; ++m) _Pragma("unroll") for (int k = 0; k < 2; ++k) dst[m][k] = *(const LAS bf16x8*)(lds + PG8_SA(b, h) + aoff + m * 2048 + (FP8 ? k * 16 : k * 1024)); } while (0)
; #define PG8_LDB(dst, b, h) do { _Pragma("unroll") for (int n = 0; n < 2; ++n) _Pragma("unroll") for (int k = 0; k < 2; ++k) dst[n][k] = *(const LAS bf16x8*)(lds + PG8_SB(b, h) + boff + n * 2048 + (FP8 ? k * 16 : k * 1024)); } while (0)
; #define PG8_WAIT_V(n) asm volatile("s_waitcnt vmcnt(" #n ")" ::: "memory")
; #define PG8_WAIT_L(n) asm volatile("s_waitcnt lgkmcnt(" #n ")" ::: "memory")
; #define PG8_BAR __builtin_amdgcn_s_barrier()
; #define PG8_SCHED __builtin_amdgcn_sched_barrier(0)
; template <class Epi, class Sched, bool ALIGN_EPI, bool SP2, int MODE  >
; __device__ __forceinline__ void gemm_phase(LAS unsigned char* lds, const Gemm g, const Sched S, const Epi E, unsigned long long& probe_acc, int epi_id, int wv) {
;     ...
;             PG8_WAIT_V(8); PG8_WAIT_L(0); PG8_BAR; PG8_MMA(1, 0, At, B0); PG8_MMA(1, 1, At, B1); PG8_BAR; PG8_SCHED;
;             PG8_LDB(B0, 1, 0); PG8_LDB(B1, 1, 1); PG8_SCHED; PG8_LDA(At, 1, 0); PG8_STAGE(PG8_SA(0, 1), a2 + hA, voffA);
;             PG8_WAIT_V(8); PG8_WAIT_L(0); PG8_BAR; PG8_MMA(0, 0, At, B0); PG8_MMA(0, 1, At, B1); PG8_BAR; PG8_SCHED;
	v_mfma_f32_16x16x32_bf16 v[62:65], v[130:133], v[168:171], 0
	v_mfma_f32_16x16x32_bf16 v[58:61], v[138:141], v[168:171], 0
	v_mfma_f32_16x16x32_bf16 v[46:49], v[130:133], v[176:179], 0
	v_mfma_f32_16x16x32_bf16 v[42:45], v[138:141], v[176:179], 0
	v_mfma_f32_16x16x32_bf16 v[30:33], v[130:133], v[188:191], 0
	v_mfma_f32_16x16x32_bf16 v[26:29], v[138:141], v[188:191], 0
	v_mfma_f32_16x16x32_bf16 v[14:17], v[130:133], v[196:199], 0
	v_mfma_f32_16x16x32_bf16 v[10:13], v[138:141], v[196:199], 0
	v_mfma_f32_16x16x32_bf16 v[62:65], v[134:137], v[172:175], v[62:65]
	v_mfma_f32_16x16x32_bf16 v[58:61], v[142:145], v[172:175], v[58:61]
	v_mfma_f32_16x16x32_bf16 v[46:49], v[134:137], v[180:183], v[46:49]
	v_mfma_f32_16x16x32_bf16 v[42:45], v[142:145], v[180:183], v[42:45]
	v_mfma_f32_16x16x32_bf16 v[30:33], v[134:137], v[192:195], v[30:33]
	v_mfma_f32_16x16x32_bf16 v[26:29], v[142:145], v[192:195], v[26:29]
	v_mfma_f32_16x16x32_bf16 v[14:17], v[134:137], v[200:203], v[14:17]
	v_mfma_f32_16x16x32_bf16 v[10:13], v[142:145], v[200:203], v[10:13]
	v_mfma_f32_16x16x32_bf16 v[54:57], v[146:149], v[168:171], 0
	v_mfma_f32_16x16x32_bf16 v[50:53], v[156:159], v[168:171], 0
	v_mfma_f32_16x16x32_bf16 v[38:41], v[146:149], v[176:179], 0
	v_mfma_f32_16x16x32_bf16 v[34:37], v[156:159], v[176:179], 0
	v_mfma_f32_16x16x32_bf16 v[22:25], v[146:149], v[188:191], 0
	v_mfma_f32_16x16x32_bf16 v[18:21], v[156:159], v[188:191], 0
	v_mfma_f32_16x16x32_bf16 v[6:9], v[146:149], v[196:199], 0
	v_mfma_f32_16x16x32_bf16 v[2:5], v[156:159], v[196:199], 0
	v_mfma_f32_16x16x32_bf16 v[54:57], v[150:153], v[172:175], v[54:57]
	v_mfma_f32_16x16x32_bf16 v[50:53], v[160:163], v[172:175], v[50:53]
	v_mfma_f32_16x16x32_bf16 v[38:41], v[150:153], v[180:183], v[38:41]
	v_mfma_f32_16x16x32_bf16 v[34:37], v[160:163], v[180:183], v[34:37]
	v_mfma_f32_16x16x32_bf16 v[22:25], v[150:153], v[192:195], v[22:25]
	v_mfma_f32_16x16x32_bf16 v[18:21], v[160:163], v[192:195], v[18:21]
	v_mfma_f32_16x16x32_bf16 v[6:9], v[150:153], v[200:203], v[6:9]
	v_mfma_f32_16x16x32_bf16 v[2:5], v[160:163], v[200:203], v[2:5]
	s_barrier
	v_add_u32_e32 v0, s31, v166
	ds_read_b128 v[130:133], v0
	ds_read_b128 v[134:137], v0 offset:1024
	ds_read_b128 v[138:141], v0 offset:2048
	ds_read_b128 v[142:145], v0 offset:3072
	v_add_u32_e32 v0, s39, v166
	ds_read_b128 v[146:149], v0
	ds_read_b128 v[150:153], v0 offset:1024
	ds_read_b128 v[156:159], v0 offset:2048
	ds_read_b128 v[160:163], v0 offset:3072
	s_mov_b32 m0, s28
	v_lshl_add_u64 v[206:207], v[204:205], 0, s[96:97]
	ds_read_b128 v[168:171], v167 offset:32768
	ds_read_b128 v[172:175], v167 offset:33792
	ds_read_b128 v[176:179], v167 offset:34816
	ds_read_b128 v[180:183], v167 offset:35840
	ds_read_b128 v[188:191], v167 offset:36864
	ds_read_b128 v[192:195], v167 offset:37888
	ds_read_b128 v[196:199], v167 offset:38912
	ds_read_b128 v[200:203], v167 offset:39936
	global_load_lds_dwordx4 v[206:207], off
	v_lshl_add_u64 v[206:207], v[204:205], 0, s[60:61]
	s_mov_b32 m0, s29
	s_nop 0
	global_load_lds_dwordx4 v[206:207], off
	s_waitcnt vmcnt(8)
	s_waitcnt lgkmcnt(0)
	s_barrier
	v_mfma_f32_16x16x32_bf16 v[126:129], v[130:133], v[168:171], v[126:129]
	v_mfma_f32_16x16x32_bf16 v[122:125], v[138:141], v[168:171], v[122:125]
	v_mfma_f32_16x16x32_bf16 v[110:113], v[130:133], v[176:179], v[110:113]
	v_mfma_f32_16x16x32_bf16 v[106:109], v[138:141], v[176:179], v[106:109]
	v_mfma_f32_16x16x32_bf16 v[94:97], v[130:133], v[188:191], v[94:97]
	v_mfma_f32_16x16x32_bf16 v[90:93], v[138:141], v[188:191], v[90:93]
	v_mfma_f32_16x16x32_bf16 v[78:81], v[130:133], v[196:199], v[78:81]
	v_mfma_f32_16x16x32_bf16 v[74:77], v[138:141], v[196:199], v[74:77]
	v_mfma_f32_16x16x32_bf16 v[126:129], v[134:137], v[172:175], v[126:129]
	v_mfma_f32_16x16x32_bf16 v[122:125], v[142:145], v[172:175], v[122:125]
	v_mfma_f32_16x16x32_bf16 v[110:113], v[134:137], v[180:183], v[110:113]
	v_mfma_f32_16x16x32_bf16 v[106:109], v[142:145], v[180:183], v[106:109]
	v_mfma_f32_16x16x32_bf16 v[94:97], v[134:137], v[192:195], v[94:97]
	v_mfma_f32_16x16x32_bf16 v[90:93], v[142:145], v[192:195], v[90:93]
	v_mfma_f32_16x16x32_bf16 v[78:81], v[134:137], v[200:203], v[78:81]
	v_mfma_f32_16x16x32_bf16 v[74:77], v[142:145], v[200:203], v[74:77]
	v_mfma_f32_16x16x32_bf16 v[118:121], v[146:149], v[168:171], v[118:121]
	v_mfma_f32_16x16x32_bf16 v[114:117], v[156:159], v[168:171], v[114:117]
	v_mfma_f32_16x16x32_bf16 v[102:105], v[146:149], v[176:179], v[102:105]
	v_mfma_f32_16x16x32_bf16 v[98:101], v[156:159], v[176:179], v[98:101]
	v_mfma_f32_16x16x32_bf16 v[86:89], v[146:149], v[188:191], v[86:89]
	v_mfma_f32_16x16x32_bf16 v[82:85], v[156:159], v[188:191], v[82:85]
	v_mfma_f32_16x16x32_bf16 v[70:73], v[146:149], v[196:199], v[70:73]
	v_mfma_f32_16x16x32_bf16 v[66:69], v[156:159], v[196:199], v[66:69]
	v_mfma_f32_16x16x32_bf16 v[118:121], v[150:153], v[172:175], v[118:121]
	v_mfma_f32_16x16x32_bf16 v[114:117], v[160:163], v[172:175], v[114:117]
	v_mfma_f32_16x16x32_bf16 v[102:105], v[150:153], v[180:183], v[102:105]
	v_mfma_f32_16x16x32_bf16 v[98:101], v[160:163], v[180:183], v[98:101]
	v_mfma_f32_16x16x32_bf16 v[86:89], v[150:153], v[192:195], v[86:89]
	v_mfma_f32_16x16x32_bf16 v[82:85], v[160:163], v[192:195], v[82:85]
	v_mfma_f32_16x16x32_bf16 v[70:73], v[150:153], v[200:203], v[70:73]
	v_mfma_f32_16x16x32_bf16 v[66:69], v[160:163], v[200:203], v[66:69]
	s_barrier
; #define PG8_STAGE(bufoff, gbase, unused) do { _Pragma("unroll") for (int _i = 0; _i < 2; ++_i) \
;         __builtin_amdgcn_global_load_lds((const unsigned*)((const char*)(gbase) + voff + _i * 8192), (LAS unsigned*)(lds + (bufoff) + ldsw + _i * 8192), 16, 0, 0); } while (0)
; #define PG8_LDA(dst, b, h) do { _Pragma("unroll") for (int m = 0; m < 4; ++m) _Pragma("unroll") for (int k = 0; k < 2; ++k) dst[m][k] = *(const LAS bf16x8*)(lds + PG8_SA(b, h) + aoff + m * 2048 + (FP8 ? k * 16 : k * 1024)); } while (0)
; #define PG8_LDB(dst, b, h) do { _Pragma("unroll") for (int n = 0; n < 2; ++n) _Pragma("unroll") for (int k = 0; k < 2; ++k) dst[n][k] = *(const LAS bf16x8*)(lds + PG8_SB(b, h) + boff + n * 2048 + (FP8 ? k * 16 : k * 1024)); } while (0)
; template <class Epi, class Sched, bool ALIGN_EPI, bool SP2, int MODE  >
; __device__ __forceinline__ void gemm_phase(LAS unsigned char* lds, const Gemm g, const Sched S, const Epi E, unsigned long long& probe_acc, int epi_id, int wv) {
;     ...
;         for (int t = 0; t < nt; t += 2) {
;             const bool last = (t == nt - 2);
;             const char* a1 = cA + (size_t)(t + 1) * kstep;
;             const char* a2 = last ? nA : cA + (size_t)(t + 2) * kstep; const char* b2 = last ? nB : cB + (size_t)(t + 2) * kstep;
;             const char* a3 = a2 + kstep; const char* b3 = b2 + kstep;
;             if constexpr (SP2) {
;             PG8_LDB(B0, 0, 0); PG8_LDB(B1, 0, 1); PG8_SCHED; PG8_LDA(At, 0, 0); PG8_STAGE(PG8_SA(1, 1), a1 + hA, voffA);
;             PG8_WAIT_V(8); PG8_WAIT_L(0); PG8_BAR; PG8_MMA(0, 0, At, B0); PG8_MMA(0, 1, At, B1); PG8_BAR; PG8_SCHED;
;             PG8_LDA(At, 0, 1); PG8_STAGE(PG8_SB(0, 0), b2, voffB); PG8_STAGE(PG8_SB(0, 1), b2 + hB, voffB); PG8_STAGE(PG8_SA(0, 0), a2, voffA);
;             PG8_WAIT_V(8); PG8_WAIT_L(0); PG8_BAR; PG8_MMA(1, 0, At, B0); PG8_MMA(1, 1, At, B1); PG8_BAR; PG8_SCHED;
;             PG8_LDB(B0, 1, 0); PG8_LDB(B1, 1, 1); PG8_SCHED; PG8_LDA(At, 1, 0); PG8_STAGE(PG8_SA(0, 1), a2 + hA, voffA);
;             PG8_WAIT_V(8); PG8_WAIT_L(0); PG8_BAR; PG8_MMA(0, 0, At, B0); PG8_MMA(0, 1, At, B1); PG8_BAR; PG8_SCHED;
;             PG8_LDA(At, 1, 1); PG8_STAGE(PG8_SB(1, 0), b3, voffB); PG8_STAGE(PG8_SB(1, 1), b3 + hB, voffB); PG8_STAGE(PG8_SA(1, 0), a3, voffA);
;             PG8_WAIT_V(8); PG8_WAIT_L(0); PG8_BAR; PG8_MMA(1, 0, At, B0); PG8_MMA(1, 1, At, B1); PG8_BAR; PG8_SCHED;
	s_mov_b32 m0, s34
	v_lshl_add_u64 v[206:207], v[184:185], 0, s[76:77]
	ds_read_b128 v[168:171], v167 offset:49152
	ds_read_b128 v[172:175], v167 offset:50176
	ds_read_b128 v[176:179], v167 offset:51200
	ds_read_b128 v[180:183], v167 offset:52224
	ds_read_b128 v[188:191], v167 offset:53248
	ds_read_b128 v[192:195], v167 offset:54272
	ds_read_b128 v[196:199], v167 offset:55296
	ds_read_b128 v[200:203], v167 offset:56320
	global_load_lds_dwordx4 v[206:207], off
	v_lshl_add_u64 v[206:207], v[184:185], 0, s[78:79]
	s_mov_b32 m0, s35
	s_nop 0
	global_load_lds_dwordx4 v[206:207], off
	v_lshl_add_u64 v[206:207], v[184:185], 0, s[52:53]
	s_mov_b32 m0, s40
	v_lshl_add_u64 v[184:185], v[184:185], 0, s[54:55]
	global_load_lds_dwordx4 v[206:207], off
	s_mov_b32 m0, s41
	s_nop 0
	global_load_lds_dwordx4 v[184:185], off
	v_lshl_add_u64 v[184:185], v[204:205], 0, s[76:77]
	s_mov_b32 m0, s36
	s_nop 0
	global_load_lds_dwordx4 v[184:185], off
	v_lshl_add_u64 v[184:185], v[204:205], 0, s[78:79]
	s_mov_b32 m0, s37
	s_nop 0
	global_load_lds_dwordx4 v[184:185], off
	s_waitcnt vmcnt(8)
	s_waitcnt lgkmcnt(0)
	s_barrier
	v_mfma_f32_16x16x32_bf16 v[62:65], v[130:133], v[168:171], v[62:65]
	v_mfma_f32_16x16x32_bf16 v[58:61], v[138:141], v[168:171], v[58:61]
	v_mfma_f32_16x16x32_bf16 v[46:49], v[130:133], v[176:179], v[46:49]
	v_mfma_f32_16x16x32_bf16 v[42:45], v[138:141], v[176:179], v[42:45]
	v_mfma_f32_16x16x32_bf16 v[30:33], v[130:133], v[188:191], v[30:33]
	v_mfma_f32_16x16x32_bf16 v[26:29], v[138:141], v[188:191], v[26:29]
	v_mfma_f32_16x16x32_bf16 v[14:17], v[130:133], v[196:199], v[14:17]
	v_mfma_f32_16x16x32_bf16 v[10:13], v[138:141], v[196:199], v[10:13]
	v_mfma_f32_16x16x32_bf16 v[62:65], v[134:137], v[172:175], v[62:65]
	v_mfma_f32_16x16x32_bf16 v[58:61], v[142:145], v[172:175], v[58:61]
	v_mfma_f32_16x16x32_bf16 v[46:49], v[134:137], v[180:183], v[46:49]
	v_mfma_f32_16x16x32_bf16 v[42:45], v[142:145], v[180:183], v[42:45]
	v_mfma_f32_16x16x32_bf16 v[30:33], v[134:137], v[192:195], v[30:33]
	v_mfma_f32_16x16x32_bf16 v[26:29], v[142:145], v[192:195], v[26:29]
	v_mfma_f32_16x16x32_bf16 v[14:17], v[134:137], v[200:203], v[14:17]
	v_mfma_f32_16x16x32_bf16 v[10:13], v[142:145], v[200:203], v[10:13]
	v_mfma_f32_16x16x32_bf16 v[54:57], v[146:149], v[168:171], v[54:57]
	v_mfma_f32_16x16x32_bf16 v[50:53], v[156:159], v[168:171], v[50:53]
	v_mfma_f32_16x16x32_bf16 v[38:41], v[146:149], v[176:179], v[38:41]
	v_mfma_f32_16x16x32_bf16 v[34:37], v[156:159], v[176:179], v[34:37]
	v_mfma_f32_16x16x32_bf16 v[22:25], v[146:149], v[188:191], v[22:25]
	v_mfma_f32_16x16x32_bf16 v[18:21], v[156:159], v[188:191], v[18:21]
	v_mfma_f32_16x16x32_bf16 v[6:9], v[146:149], v[196:199], v[6:9]
	v_mfma_f32_16x16x32_bf16 v[2:5], v[156:159], v[196:199], v[2:5]
	v_mfma_f32_16x16x32_bf16 v[54:57], v[150:153], v[172:175], v[54:57]
	v_mfma_f32_16x16x32_bf16 v[50:53], v[160:163], v[172:175], v[50:53]
	v_mfma_f32_16x16x32_bf16 v[38:41], v[150:153], v[180:183], v[38:41]
	v_mfma_f32_16x16x32_bf16 v[34:37], v[160:163], v[180:183], v[34:37]
	v_mfma_f32_16x16x32_bf16 v[22:25], v[150:153], v[192:195], v[22:25]
	v_mfma_f32_16x16x32_bf16 v[18:21], v[160:163], v[192:195], v[18:21]
	v_mfma_f32_16x16x32_bf16 v[6:9], v[150:153], v[200:203], v[6:9]
	v_mfma_f32_16x16x32_bf16 v[2:5], v[160:163], v[200:203], v[2:5]
	s_barrier
	s_add_i32 s95, s95, 2
	s_add_u32 s93, s93, 0x8000
	s_addc_u32 s94, s94, 0
	s_cmp_gt_u32 s95, 29
	s_mov_b64 s[18:19], s[20:21]
	v_readlane_b32 s98, v254, 1
	s_nop 3
	s_cmp_ge_u32 s98, 4
	s_cbranch_scc0 .Lprio_skip_1
	s_setprio 1
.Lprio_skip_1:
.LBB0_365:
	v_add_u32_e32 v0, s2, v166
	s_waitcnt vmcnt(0)
	ds_read_b128 v[130:133], v0
	ds_read_b128 v[134:137], v0 offset:1024
	ds_read_b128 v[138:141], v0 offset:2048
	ds_read_b128 v[142:145], v0 offset:3072
	v_add_u32_e32 v0, s23, v166
	ds_read_b128 v[146:149], v0
	ds_read_b128 v[150:153], v0 offset:1024
	s_waitcnt lgkmcnt(0)
	ds_read_b128 v[156:159], v0 offset:2048
	ds_read_b128 v[160:163], v0 offset:3072
	s_add_u32 s20, s18, 0x8000
	s_addc_u32 s21, s19, 0
	s_cmp_eq_u32 s95, 28
	s_cselect_b32 vcc_hi, s46, s21
	s_cselect_b32 vcc_lo, s90, s20
	s_cselect_b32 s9, s91, s94
	s_cselect_b32 s8, s92, s93
	v_lshl_add_u64 v[184:185], s[18:19], 0, v[154:155]
	v_lshl_add_u64 v[204:205], v[184:185], 0, s[52:53]
	s_add_i32 m0, s26, 0xc000
	ds_read_b128 v[168:171], v167
	ds_read_b128 v[172:175], v167 offset:1024
	ds_read_b128 v[176:179], v167 offset:2048
	ds_read_b128 v[180:183], v167 offset:3072
	ds_read_b128 v[188:191], v167 offset:4096
	ds_read_b128 v[192:195], v167 offset:5120
	ds_read_b128 v[196:199], v167 offset:6144
	ds_read_b128 v[200:203], v167 offset:7168
	global_load_lds_dwordx4 v[204:205], off
	v_lshl_add_u64 v[184:185], v[184:185], 0, s[54:55]
	s_add_i32 m0, s26, 0xe000
	s_nop 0
	global_load_lds_dwordx4 v[184:185], off
	s_waitcnt vmcnt(8)
	s_waitcnt lgkmcnt(0)
	s_barrier
; #define PG8_STAGE(bufoff, gbase, unused) do { _Pragma("unroll") for (int _i = 0; _i < 2; ++_i) \
;         __builtin_amdgcn_global_load_lds((const unsigned*)((const char*)(gbase) + voff + _i * 8192), (LAS unsigned*)(lds + (bufoff) + ldsw + _i * 8192), 16, 0, 0); } while (0)
; #define PG8_LDA(dst, b, h) do { _Pragma("unroll") for (int m = 0; m < 4; ++m) _Pragma("unroll") for (int k = 0; k < 2; ++k) dst[m][k] = *(const LAS bf16x8*)(lds + PG8_SA(b, h) + aoff + m * 2048 + (FP8 ? k * 16 : k * 1024)); } while (0)
; #define PG8_WAIT_V(n) asm volatile("s_waitcnt vmcnt(" #n ")" ::: "memory")
; #define PG8_WAIT_L(n) asm volatile("s_waitcnt lgkmcnt(" #n ")" ::: "memory")
; #define PG8_BAR __builtin_amdgcn_s_barrier()
; #define PG8_SCHED __builtin_amdgcn_sched_barrier(0)
; template <class Epi, class Sched, bool ALIGN_EPI, bool SP2, int MODE  >
; __device__ __forceinline__ void gemm_phase(LAS unsigned char* lds, const Gemm g, const Sched S, const Epi E, unsigned long long& probe_acc, int epi_id, int wv) {
;     ...
;             PG8_WAIT_V(8); PG8_WAIT_L(0); PG8_BAR; PG8_MMA(0, 0, At, B0); PG8_MMA(0, 1, At, B1); PG8_BAR; PG8_SCHED;
;             PG8_LDA(At, 0, 1); PG8_STAGE(PG8_SB(0, 0), b2, voffB); PG8_STAGE(PG8_SB(0, 1), b2 + hB, voffB); PG8_STAGE(PG8_SA(0, 0), a2, voffA);
;             PG8_WAIT_V(8); PG8_WAIT_L(0); PG8_BAR; PG8_MMA(1, 0, At, B0); PG8_MMA(1, 1, At, B1); PG8_BAR; PG8_SCHED;
	v_mfma_f32_16x16x32_bf16 v[126:129], v[130:133], v[168:171], v[126:129]
	v_mfma_f32_16x16x32_bf16 v[122:125], v[138:141], v[168:171], v[122:125]
	v_mfma_f32_16x16x32_bf16 v[110:113], v[130:133], v[176:179], v[110:113]
	v_mfma_f32_16x16x32_bf16 v[106:109], v[138:141], v[176:179], v[106:109]
	v_mfma_f32_16x16x32_bf16 v[94:97], v[130:133], v[188:191], v[94:97]
	v_mfma_f32_16x16x32_bf16 v[90:93], v[138:141], v[188:191], v[90:93]
	v_mfma_f32_16x16x32_bf16 v[78:81], v[130:133], v[196:199], v[78:81]
	v_mfma_f32_16x16x32_bf16 v[74:77], v[138:141], v[196:199], v[74:77]
	v_mfma_f32_16x16x32_bf16 v[126:129], v[134:137], v[172:175], v[126:129]
	v_mfma_f32_16x16x32_bf16 v[122:125], v[142:145], v[172:175], v[122:125]
	v_mfma_f32_16x16x32_bf16 v[110:113], v[134:137], v[180:183], v[110:113]
	v_mfma_f32_16x16x32_bf16 v[106:109], v[142:145], v[180:183], v[106:109]
	v_mfma_f32_16x16x32_bf16 v[94:97], v[134:137], v[192:195], v[94:97]
	v_mfma_f32_16x16x32_bf16 v[90:93], v[142:145], v[192:195], v[90:93]
	v_mfma_f32_16x16x32_bf16 v[78:81], v[134:137], v[200:203], v[78:81]
	v_mfma_f32_16x16x32_bf16 v[74:77], v[142:145], v[200:203], v[74:77]
	v_mfma_f32_16x16x32_bf16 v[118:121], v[146:149], v[168:171], v[118:121]
	v_mfma_f32_16x16x32_bf16 v[114:117], v[156:159], v[168:171], v[114:117]
	v_mfma_f32_16x16x32_bf16 v[102:105], v[146:149], v[176:179], v[102:105]
	v_mfma_f32_16x16x32_bf16 v[98:101], v[156:159], v[176:179], v[98:101]
	v_mfma_f32_16x16x32_bf16 v[86:89], v[146:149], v[188:191], v[86:89]
	v_mfma_f32_16x16x32_bf16 v[82:85], v[156:159], v[188:191], v[82:85]
	v_mfma_f32_16x16x32_bf16 v[70:73], v[146:149], v[196:199], v[70:73]
	v_mfma_f32_16x16x32_bf16 v[66:69], v[156:159], v[196:199], v[66:69]
	v_mfma_f32_16x16x32_bf16 v[118:121], v[150:153], v[172:175], v[118:121]
	v_mfma_f32_16x16x32_bf16 v[114:117], v[160:163], v[172:175], v[114:117]
	v_mfma_f32_16x16x32_bf16 v[102:105], v[150:153], v[180:183], v[102:105]
	v_mfma_f32_16x16x32_bf16 v[98:101], v[160:163], v[180:183], v[98:101]
	v_mfma_f32_16x16x32_bf16 v[86:89], v[150:153], v[192:195], v[86:89]
	v_mfma_f32_16x16x32_bf16 v[82:85], v[160:163], v[192:195], v[82:85]
	v_mfma_f32_16x16x32_bf16 v[70:73], v[150:153], v[200:203], v[70:73]
	v_mfma_f32_16x16x32_bf16 v[66:69], v[160:163], v[200:203], v[66:69]
	s_barrier
	s_mov_b32 m0, s3
	v_lshl_add_u64 v[184:185], s[8:9], 0, v[154:155]
	ds_read_b128 v[168:171], v167 offset:16384
	ds_read_b128 v[172:175], v167 offset:17408
	ds_read_b128 v[176:179], v167 offset:18432
	ds_read_b128 v[180:183], v167 offset:19456
	ds_read_b128 v[188:191], v167 offset:20480
	ds_read_b128 v[192:195], v167 offset:21504
	ds_read_b128 v[196:199], v167 offset:22528
	ds_read_b128 v[200:203], v167 offset:23552
	global_load_lds_dwordx4 v[184:185], off
	v_lshl_add_u64 v[204:205], v[184:185], 0, s[70:71]
	s_mov_b32 m0, s22
	s_nop 0
	global_load_lds_dwordx4 v[204:205], off
	v_lshl_add_u64 v[204:205], v[184:185], 0, s[96:97]
	s_mov_b32 m0, s24
	s_nop 0
	global_load_lds_dwordx4 v[204:205], off
	v_lshl_add_u64 v[204:205], v[184:185], 0, s[60:61]
	s_mov_b32 m0, s25
	s_nop 0
	global_load_lds_dwordx4 v[204:205], off
	v_lshl_add_u64 v[204:205], vcc, 0, v[154:155]
	s_mov_b32 m0, s26
	v_lshl_add_u64 v[206:207], v[204:205], 0, s[70:71]
	global_load_lds_dwordx4 v[204:205], off
	s_mov_b32 m0, s27
	s_nop 0
	global_load_lds_dwordx4 v[206:207], off
	s_waitcnt vmcnt(8)
	s_waitcnt lgkmcnt(0)
	s_barrier
	v_mfma_f32_16x16x32_bf16 v[62:65], v[130:133], v[168:171], v[62:65]
	v_mfma_f32_16x16x32_bf16 v[58:61], v[138:141], v[168:171], v[58:61]
	v_mfma_f32_16x16x32_bf16 v[46:49], v[130:133], v[176:179], v[46:49]
	v_mfma_f32_16x16x32_bf16 v[42:45], v[138:141], v[176:179], v[42:45]
	v_mfma_f32_16x16x32_bf16 v[30:33], v[130:133], v[188:191], v[30:33]
	v_mfma_f32_16x16x32_bf16 v[26:29], v[138:141], v[188:191], v[26:29]
	v_mfma_f32_16x16x32_bf16 v[14:17], v[130:133], v[196:199], v[14:17]
	v_mfma_f32_16x16x32_bf16 v[10:13], v[138:141], v[196:199], v[10:13]
	v_mfma_f32_16x16x32_bf16 v[62:65], v[134:137], v[172:175], v[62:65]
	v_mfma_f32_16x16x32_bf16 v[58:61], v[142:145], v[172:175], v[58:61]
	v_mfma_f32_16x16x32_bf16 v[46:49], v[134:137], v[180:183], v[46:49]
	v_mfma_f32_16x16x32_bf16 v[42:45], v[142:145], v[180:183], v[42:45]
	v_mfma_f32_16x16x32_bf16 v[30:33], v[134:137], v[192:195], v[30:33]
	v_mfma_f32_16x16x32_bf16 v[26:29], v[142:145], v[192:195], v[26:29]
	v_mfma_f32_16x16x32_bf16 v[14:17], v[134:137], v[200:203], v[14:17]
	v_mfma_f32_16x16x32_bf16 v[10:13], v[142:145], v[200:203], v[10:13]
	v_mfma_f32_16x16x32_bf16 v[54:57], v[146:149], v[168:171], v[54:57]
	v_mfma_f32_16x16x32_bf16 v[50:53], v[156:159], v[168:171], v[50:53]
	v_mfma_f32_16x16x32_bf16 v[38:41], v[146:149], v[176:179], v[38:41]
	v_mfma_f32_16x16x32_bf16 v[34:37], v[156:159], v[176:179], v[34:37]
	v_mfma_f32_16x16x32_bf16 v[22:25], v[146:149], v[188:191], v[22:25]
	v_mfma_f32_16x16x32_bf16 v[18:21], v[156:159], v[188:191], v[18:21]
	v_mfma_f32_16x16x32_bf16 v[6:9], v[146:149], v[196:199], v[6:9]
	v_mfma_f32_16x16x32_bf16 v[2:5], v[156:159], v[196:199], v[2:5]
	v_mfma_f32_16x16x32_bf16 v[54:57], v[150:153], v[172:175], v[54:57]
	v_mfma_f32_16x16x32_bf16 v[50:53], v[160:163], v[172:175], v[50:53]
	v_mfma_f32_16x16x32_bf16 v[38:41], v[150:153], v[180:183], v[38:41]
	v_mfma_f32_16x16x32_bf16 v[34:37], v[160:163], v[180:183], v[34:37]
	v_mfma_f32_16x16x32_bf16 v[22:25], v[150:153], v[192:195], v[22:25]
	v_mfma_f32_16x16x32_bf16 v[18:21], v[160:163], v[192:195], v[18:21]
	v_mfma_f32_16x16x32_bf16 v[6:9], v[150:153], v[200:203], v[6:9]
	v_mfma_f32_16x16x32_bf16 v[2:5], v[160:163], v[200:203], v[2:5]
	s_barrier
; #define PG8_STAGE(bufoff, gbase, unused) do { _Pragma("unroll") for (int _i = 0; _i < 2; ++_i) \
;         __builtin_amdgcn_global_load_lds((const unsigned*)((const char*)(gbase) + voff + _i * 8192), (LAS unsigned*)(lds + (bufoff) + ldsw + _i * 8192), 16, 0, 0); } while (0)
; #define PG8_LDA(dst, b, h) do { _Pragma("unroll") for (int m = 0; m < 4; ++m) _Pragma("unroll") for (int k = 0; k < 2; ++k) dst[m][k] = *(const LAS bf16x8*)(lds + PG8_SA(b, h) + aoff + m * 2048 + (FP8 ? k * 16 : k * 1024)); } while (0)
; #define PG8_LDB(dst, b, h) do { _Pragma("unroll") for (int n = 0; n < 2; ++n) _Pragma("unroll") for (int k = 0; k < 2; ++k) dst[n][k] = *(const LAS bf16x8*)(lds + PG8_SB(b, h) + boff + n * 2048 + (FP8 ? k * 16 : k * 1024)); } while (0)
; #define PG8_WAIT_V(n) asm volatile("s_waitcnt vmcnt(" #n ")" ::: "memory")
; #define PG8_WAIT_L(n) asm volatile("s_waitcnt lgkmcnt(" #n ")" ::: "memory")
; #define PG8_BAR __builtin_amdgcn_s_barrier()
; #define PG8_SCHED __builtin_amdgcn_sched_barrier(0)
; template <class Epi, class Sched, bool ALIGN_EPI, bool SP2, int MODE  >
; __device__ __forceinline__ void gemm_phase(LAS unsigned char* lds, const Gemm g, const Sched S, const Epi E, unsigned long long& probe_acc, int epi_id, int wv) {
;     ...
;             PG8_WAIT_V(8); PG8_WAIT_L(0); PG8_BAR; PG8_MMA(1, 0, At, B0); PG8_MMA(1, 1, At, B1); PG8_BAR; PG8_SCHED;
;             PG8_LDB(B0, 1, 0); PG8_LDB(B1, 1, 1); PG8_SCHED; PG8_LDA(At, 1, 0); PG8_STAGE(PG8_SA(0, 1), a2 + hA, voffA);
;             PG8_WAIT_V(8); PG8_WAIT_L(0); PG8_BAR; PG8_MMA(0, 0, At, B0); PG8_MMA(0, 1, At, B1); PG8_BAR; PG8_SCHED;
;             PG8_LDA(At, 1, 1); PG8_STAGE(PG8_SB(1, 0), b3, voffB); PG8_STAGE(PG8_SB(1, 1), b3 + hB, voffB); PG8_STAGE(PG8_SA(1, 0), a3, voffA);
;             PG8_WAIT_V(8); PG8_WAIT_L(0); PG8_BAR; PG8_MMA(1, 0, At, B0); PG8_MMA(1, 1, At, B1); PG8_BAR; PG8_SCHED;
	v_add_u32_e32 v0, s31, v166
	ds_read_b128 v[130:133], v0
	ds_read_b128 v[134:137], v0 offset:1024
	ds_read_b128 v[138:141], v0 offset:2048
	ds_read_b128 v[142:145], v0 offset:3072
	v_add_u32_e32 v0, s39, v166
	ds_read_b128 v[146:149], v0
	ds_read_b128 v[150:153], v0 offset:1024
	ds_read_b128 v[156:159], v0 offset:2048
	ds_read_b128 v[160:163], v0 offset:3072
	s_mov_b32 m0, s28
	v_lshl_add_u64 v[206:207], v[204:205], 0, s[96:97]
	ds_read_b128 v[168:171], v167 offset:32768
	ds_read_b128 v[172:175], v167 offset:33792
	ds_read_b128 v[176:179], v167 offset:34816
	ds_read_b128 v[180:183], v167 offset:35840
	ds_read_b128 v[188:191], v167 offset:36864
	ds_read_b128 v[192:195], v167 offset:37888
	ds_read_b128 v[196:199], v167 offset:38912
	ds_read_b128 v[200:203], v167 offset:39936
	global_load_lds_dwordx4 v[206:207], off
	v_lshl_add_u64 v[206:207], v[204:205], 0, s[60:61]
	s_mov_b32 m0, s29
	s_nop 0
	global_load_lds_dwordx4 v[206:207], off
	s_waitcnt vmcnt(8)
	s_waitcnt lgkmcnt(0)
	s_barrier
	v_mfma_f32_16x16x32_bf16 v[126:129], v[130:133], v[168:171], v[126:129]
	v_mfma_f32_16x16x32_bf16 v[122:125], v[138:141], v[168:171], v[122:125]
	v_mfma_f32_16x16x32_bf16 v[110:113], v[130:133], v[176:179], v[110:113]
	v_mfma_f32_16x16x32_bf16 v[106:109], v[138:141], v[176:179], v[106:109]
	v_mfma_f32_16x16x32_bf16 v[94:97], v[130:133], v[188:191], v[94:97]
	v_mfma_f32_16x16x32_bf16 v[90:93], v[138:141], v[188:191], v[90:93]
	v_mfma_f32_16x16x32_bf16 v[78:81], v[130:133], v[196:199], v[78:81]
	v_mfma_f32_16x16x32_bf16 v[74:77], v[138:141], v[196:199], v[74:77]
	v_mfma_f32_16x16x32_bf16 v[126:129], v[134:137], v[172:175], v[126:129]
	v_mfma_f32_16x16x32_bf16 v[122:125], v[142:145], v[172:175], v[122:125]
	v_mfma_f32_16x16x32_bf16 v[110:113], v[134:137], v[180:183], v[110:113]
	v_mfma_f32_16x16x32_bf16 v[106:109], v[142:145], v[180:183], v[106:109]
	v_mfma_f32_16x16x32_bf16 v[94:97], v[134:137], v[192:195], v[94:97]
	v_mfma_f32_16x16x32_bf16 v[90:93], v[142:145], v[192:195], v[90:93]
	v_mfma_f32_16x16x32_bf16 v[78:81], v[134:137], v[200:203], v[78:81]
	v_mfma_f32_16x16x32_bf16 v[74:77], v[142:145], v[200:203], v[74:77]
	v_mfma_f32_16x16x32_bf16 v[118:121], v[146:149], v[168:171], v[118:121]
	v_mfma_f32_16x16x32_bf16 v[114:117], v[156:159], v[168:171], v[114:117]
	v_mfma_f32_16x16x32_bf16 v[102:105], v[146:149], v[176:179], v[102:105]
	v_mfma_f32_16x16x32_bf16 v[98:101], v[156:159], v[176:179], v[98:101]
	v_mfma_f32_16x16x32_bf16 v[86:89], v[146:149], v[188:191], v[86:89]
	v_mfma_f32_16x16x32_bf16 v[82:85], v[156:159], v[188:191], v[82:85]
	v_mfma_f32_16x16x32_bf16 v[70:73], v[146:149], v[196:199], v[70:73]
	v_mfma_f32_16x16x32_bf16 v[66:69], v[156:159], v[196:199], v[66:69]
	v_mfma_f32_16x16x32_bf16 v[118:121], v[150:153], v[172:175], v[118:121]
	v_mfma_f32_16x16x32_bf16 v[114:117], v[160:163], v[172:175], v[114:117]
	v_mfma_f32_16x16x32_bf16 v[102:105], v[150:153], v[180:183], v[102:105]
	v_mfma_f32_16x16x32_bf16 v[98:101], v[160:163], v[180:183], v[98:101]
	v_mfma_f32_16x16x32_bf16 v[86:89], v[150:153], v[192:195], v[86:89]
	v_mfma_f32_16x16x32_bf16 v[82:85], v[160:163], v[192:195], v[82:85]
	v_mfma_f32_16x16x32_bf16 v[70:73], v[150:153], v[200:203], v[70:73]
	v_mfma_f32_16x16x32_bf16 v[66:69], v[160:163], v[200:203], v[66:69]
	s_barrier
	s_mov_b32 m0, s34
	v_lshl_add_u64 v[206:207], v[184:185], 0, s[76:77]
	ds_read_b128 v[168:171], v167 offset:49152
	ds_read_b128 v[172:175], v167 offset:50176
	ds_read_b128 v[176:179], v167 offset:51200
	ds_read_b128 v[180:183], v167 offset:52224
	ds_read_b128 v[188:191], v167 offset:53248
	ds_read_b128 v[192:195], v167 offset:54272
	ds_read_b128 v[196:199], v167 offset:55296
	ds_read_b128 v[200:203], v167 offset:56320
	global_load_lds_dwordx4 v[206:207], off
	v_lshl_add_u64 v[206:207], v[184:185], 0, s[78:79]
	s_mov_b32 m0, s35
	s_nop 0
	global_load_lds_dwordx4 v[206:207], off
	v_lshl_add_u64 v[206:207], v[184:185], 0, s[52:53]
	s_mov_b32 m0, s40
	v_lshl_add_u64 v[184:185], v[184:185], 0, s[54:55]
	global_load_lds_dwordx4 v[206:207], off
	s_mov_b32 m0, s41
	s_nop 0
	global_load_lds_dwordx4 v[184:185], off
	v_lshl_add_u64 v[184:185], v[204:205], 0, s[76:77]
	s_mov_b32 m0, s36
	s_nop 0
	global_load_lds_dwordx4 v[184:185], off
	v_lshl_add_u64 v[184:185], v[204:205], 0, s[78:79]
	s_mov_b32 m0, s37
	s_nop 0
	global_load_lds_dwordx4 v[184:185], off
	s_waitcnt vmcnt(8)
	s_waitcnt lgkmcnt(0)
	s_barrier
	v_mfma_f32_16x16x32_bf16 v[62:65], v[130:133], v[168:171], v[62:65]
	v_mfma_f32_16x16x32_bf16 v[58:61], v[138:141], v[168:171], v[58:61]
	v_mfma_f32_16x16x32_bf16 v[46:49], v[130:133], v[176:179], v[46:49]
	v_mfma_f32_16x16x32_bf16 v[42:45], v[138:141], v[176:179], v[42:45]
	v_mfma_f32_16x16x32_bf16 v[30:33], v[130:133], v[188:191], v[30:33]
	v_mfma_f32_16x16x32_bf16 v[26:29], v[138:141], v[188:191], v[26:29]
	v_mfma_f32_16x16x32_bf16 v[14:17], v[130:133], v[196:199], v[14:17]
	v_mfma_f32_16x16x32_bf16 v[10:13], v[138:141], v[196:199], v[10:13]
	v_mfma_f32_16x16x32_bf16 v[62:65], v[134:137], v[172:175], v[62:65]
	v_mfma_f32_16x16x32_bf16 v[58:61], v[142:145], v[172:175], v[58:61]
	v_mfma_f32_16x16x32_bf16 v[46:49], v[134:137], v[180:183], v[46:49]
	v_mfma_f32_16x16x32_bf16 v[42:45], v[142:145], v[180:183], v[42:45]
	v_mfma_f32_16x16x32_bf16 v[30:33], v[134:137], v[192:195], v[30:33]
	v_mfma_f32_16x16x32_bf16 v[26:29], v[142:145], v[192:195], v[26:29]
	v_mfma_f32_16x16x32_bf16 v[14:17], v[134:137], v[200:203], v[14:17]
	v_mfma_f32_16x16x32_bf16 v[10:13], v[142:145], v[200:203], v[10:13]
	v_mfma_f32_16x16x32_bf16 v[54:57], v[146:149], v[168:171], v[54:57]
	v_mfma_f32_16x16x32_bf16 v[50:53], v[156:159], v[168:171], v[50:53]
	v_mfma_f32_16x16x32_bf16 v[38:41], v[146:149], v[176:179], v[38:41]
	v_mfma_f32_16x16x32_bf16 v[34:37], v[156:159], v[176:179], v[34:37]
	v_mfma_f32_16x16x32_bf16 v[22:25], v[146:149], v[188:191], v[22:25]
	v_mfma_f32_16x16x32_bf16 v[18:21], v[156:159], v[188:191], v[18:21]
	v_mfma_f32_16x16x32_bf16 v[6:9], v[146:149], v[196:199], v[6:9]
	v_mfma_f32_16x16x32_bf16 v[2:5], v[156:159], v[196:199], v[2:5]
	v_mfma_f32_16x16x32_bf16 v[54:57], v[150:153], v[172:175], v[54:57]
	v_mfma_f32_16x16x32_bf16 v[50:53], v[160:163], v[172:175], v[50:53]
	v_mfma_f32_16x16x32_bf16 v[38:41], v[150:153], v[180:183], v[38:41]
	v_mfma_f32_16x16x32_bf16 v[34:37], v[160:163], v[180:183], v[34:37]
	v_mfma_f32_16x16x32_bf16 v[22:25], v[150:153], v[192:195], v[22:25]
	v_mfma_f32_16x16x32_bf16 v[18:21], v[160:163], v[192:195], v[18:21]
	v_mfma_f32_16x16x32_bf16 v[6:9], v[150:153], v[200:203], v[6:9]
	v_mfma_f32_16x16x32_bf16 v[2:5], v[160:163], v[200:203], v[2:5]
	s_barrier
	s_add_i32 s95, s95, 2
	s_add_u32 s93, s93, 0x8000
	s_addc_u32 s94, s94, 0
	s_cmp_gt_u32 s95, 29
	s_mov_b64 s[18:19], s[20:21]
	s_cbranch_scc0 .LBB0_365
	s_and_b64 vcc, exec, s[14:15]
	s_cbranch_vccz .LBB0_368
	s_barrier

; #define PG8_STAGE(bufoff, gbase, unused) do { _Pragma("unroll") for (int _i = 0; _i < 2; ++_i) \
;         __builtin_amdgcn_global_load_lds((const unsigned*)((const char*)(gbase) + voff + _i * 8192), (LAS unsigned*)(lds + (bufoff) + ldsw + _i * 8192), 16, 0, 0); } while (0)
; #define PG8_LDA(dst, b, h) do { _Pragma("unroll") for (int m = 0; m < 4; ++m) _Pragma("unroll") for (int k = 0; k < 2; ++k) dst[m][k] = *(const LAS bf16x8*)(lds + PG8_SA(b, h) + aoff + m * 2048 + (FP8 ? k * 16 : k * 1024)); } while (0)
; #define PG8_LDB(dst, b, h) do { _Pragma("unroll") for (int n = 0; n < 2; ++n) _Pragma("unroll") for (int k = 0; k < 2; ++k) dst[n][k] = *(const LAS bf16x8*)(lds + PG8_SB(b, h) + boff + n * 2048 + (FP8 ? k * 16 : k * 1024)); } while (0)
; #define PG8_WAIT_V(n) asm volatile("s_waitcnt vmcnt(" #n ")" ::: "memory")
; #define PG8_WAIT_L(n) asm volatile("s_waitcnt lgkmcnt(" #n ")" ::: "memory")
; #define PG8_BAR __builtin_amdgcn_s_barrier()
; #define PG8_SCHED __builtin_amdgcn_sched_barrier(0)
; template <class Epi, class Sched, bool ALIGN_EPI, bool SP2, int MODE  >
; __device__ __forceinline__ void gemm_phase(LAS unsigned char* lds, const Gemm g, const Sched S, const Epi E, unsigned long long& probe_acc, int epi_id, int wv) {
;     ...
;         for (int t = 0; t < nt; t += 2) {
;             const bool last = (t == nt - 2);
;             const char* a1 = cA + (size_t)(t + 1) * kstep;
;             const char* a2 = last ? nA : cA + (size_t)(t + 2) * kstep; const char* b2 = last ? nB : cB + (size_t)(t + 2) * kstep;
;             const char* a3 = a2 + kstep; const char* b3 = b2 + kstep;
;             if constexpr (SP2) {
;             PG8_LDB(B0, 0, 0); PG8_LDB(B1, 0, 1); PG8_SCHED; PG8_LDA(At, 0, 0); PG8_STAGE(PG8_SA(1, 1), a1 + hA, voffA);
;             PG8_WAIT_V(8); PG8_WAIT_L(0); PG8_BAR; PG8_MMA(0, 0, At, B0); PG8_MMA(0, 1, At, B1); PG8_BAR; PG8_SCHED;
;             PG8_LDA(At, 0, 1); PG8_STAGE(PG8_SB(0, 0), b2, voffB); PG8_STAGE(PG8_SB(0, 1), b2 + hB, voffB); PG8_STAGE(PG8_SA(0, 0), a2, voffA);
;             PG8_WAIT_V(8); PG8_WAIT_L(0); PG8_BAR; PG8_MMA(1, 0, At, B0); PG8_MMA(1, 1, At, B1); PG8_BAR; PG8_SCHED;
.LBB0_673:
	s_add_u32 s10, s4, 0x8000
	s_addc_u32 s11, s5, 0
	s_add_u32 s4, s6, 0x8000
	s_addc_u32 s5, s7, 0
	s_mov_b32 s6, 0
	s_waitcnt lgkmcnt(0)
	s_waitcnt vmcnt(0)
	v_add_u32_e32 v142, s15, v193
	v_add_u32_e32 v156, s39, v193
	ds_read_b128 v[130:133], v142
	ds_read_b128 v[134:137], v142 offset:1024
	ds_read_b128 v[138:141], v142 offset:2048
	ds_read_b128 v[142:145], v142 offset:3072
	ds_read_b128 v[146:149], v156
	ds_read_b128 v[150:153], v156 offset:1024
	ds_read_b128 v[158:161], v156 offset:2048
	ds_read_b128 v[162:165], v156 offset:3072
	s_add_i32 s40, s6, 2
	s_cmp_eq_u32 s93, s6
	s_cselect_b32 s6, s34, s10
	s_cselect_b32 s9, s87, s5
	s_cselect_b32 s8, s86, s4
	s_cselect_b32 s7, s35, s11
	s_movk_i32 vcc_lo, 0xc000
	v_lshl_add_u64 v[190:191], s[4:5], 0, v[154:155]
	s_mov_b32 vcc_hi, -1
	v_lshl_add_u64 v[196:197], v[190:191], 0, vcc
	s_movk_i32 vcc_lo, 0xe000
	s_add_i32 m0, s88, 0xc000
	s_mov_b32 vcc_hi, -1
	ds_read_b128 v[166:169], v194
	ds_read_b128 v[170:173], v194 offset:1024
	ds_read_b128 v[174:177], v194 offset:2048
	ds_read_b128 v[178:181], v194 offset:3072
	ds_read_b128 v[182:185], v194 offset:4096
	ds_read_b128 v[186:189], v194 offset:5120
	ds_read_b128 v[200:203], v194 offset:6144
	ds_read_b128 v[204:207], v194 offset:7168
	global_load_lds_dwordx4 v[196:197], off
	v_lshl_add_u64 v[190:191], v[190:191], 0, vcc
	s_add_i32 m0, s88, 0xe000
	s_nop 0
	global_load_lds_dwordx4 v[190:191], off
	s_waitcnt vmcnt(8)
	s_waitcnt lgkmcnt(0)
	s_barrier
	v_mfma_f32_16x16x32_bf16 v[126:129], v[130:133], v[166:169], 0
	v_mfma_f32_16x16x32_bf16 v[122:125], v[138:141], v[166:169], 0
	v_mfma_f32_16x16x32_bf16 v[118:121], v[130:133], v[174:177], 0
	v_mfma_f32_16x16x32_bf16 v[114:117], v[138:141], v[174:177], 0
	v_mfma_f32_16x16x32_bf16 v[110:113], v[130:133], v[182:185], 0
	v_mfma_f32_16x16x32_bf16 v[106:109], v[138:141], v[182:185], 0
	v_mfma_f32_16x16x32_bf16 v[102:105], v[130:133], v[200:203], 0
	v_mfma_f32_16x16x32_bf16 v[98:101], v[138:141], v[200:203], 0
	v_mfma_f32_16x16x32_bf16 v[126:129], v[134:137], v[170:173], v[126:129]
	v_mfma_f32_16x16x32_bf16 v[122:125], v[142:145], v[170:173], v[122:125]
	v_mfma_f32_16x16x32_bf16 v[118:121], v[134:137], v[178:181], v[118:121]
	v_mfma_f32_16x16x32_bf16 v[114:117], v[142:145], v[178:181], v[114:117]
	v_mfma_f32_16x16x32_bf16 v[110:113], v[134:137], v[186:189], v[110:113]
	v_mfma_f32_16x16x32_bf16 v[106:109], v[142:145], v[186:189], v[106:109]
	v_mfma_f32_16x16x32_bf16 v[102:105], v[134:137], v[204:207], v[102:105]
	v_mfma_f32_16x16x32_bf16 v[98:101], v[142:145], v[204:207], v[98:101]
	v_mfma_f32_16x16x32_bf16 v[62:65], v[146:149], v[166:169], 0
	v_mfma_f32_16x16x32_bf16 v[58:61], v[158:161], v[166:169], 0
	v_mfma_f32_16x16x32_bf16 v[54:57], v[146:149], v[174:177], 0
	v_mfma_f32_16x16x32_bf16 v[50:53], v[158:161], v[174:177], 0
	v_mfma_f32_16x16x32_bf16 v[46:49], v[146:149], v[182:185], 0
	v_mfma_f32_16x16x32_bf16 v[42:45], v[158:161], v[182:185], 0
	v_mfma_f32_16x16x32_bf16 v[38:41], v[146:149], v[200:203], 0
	v_mfma_f32_16x16x32_bf16 v[34:37], v[158:161], v[200:203], 0
	v_mfma_f32_16x16x32_bf16 v[62:65], v[150:153], v[170:173], v[62:65]
	v_mfma_f32_16x16x32_bf16 v[58:61], v[162:165], v[170:173], v[58:61]
	v_mfma_f32_16x16x32_bf16 v[54:57], v[150:153], v[178:181], v[54:57]
	v_mfma_f32_16x16x32_bf16 v[50:53], v[162:165], v[178:181], v[50:53]
	v_mfma_f32_16x16x32_bf16 v[46:49], v[150:153], v[186:189], v[46:49]
	v_mfma_f32_16x16x32_bf16 v[42:45], v[162:165], v[186:189], v[42:45]
	v_mfma_f32_16x16x32_bf16 v[38:41], v[150:153], v[204:207], v[38:41]
	v_mfma_f32_16x16x32_bf16 v[34:37], v[162:165], v[204:207], v[34:37]
	s_barrier
	s_mov_b32 m0, s26
	v_lshl_add_u64 v[190:191], s[6:7], 0, v[0:1]
	s_add_u32 vcc_lo, s6, s13
	ds_read_b128 v[166:169], v194 offset:16384
	ds_read_b128 v[170:173], v194 offset:17408
	ds_read_b128 v[174:177], v194 offset:18432
	ds_read_b128 v[178:181], v194 offset:19456
	ds_read_b128 v[182:185], v194 offset:20480
	ds_read_b128 v[186:189], v194 offset:21504
	ds_read_b128 v[200:203], v194 offset:22528
	ds_read_b128 v[204:207], v194 offset:23552
	global_load_lds_dwordx4 v[190:191], off
	v_lshl_add_u64 v[190:191], v[190:191], 0, s[70:71]
	s_mov_b32 m0, s27
	s_addc_u32 vcc_hi, s7, 0
	global_load_lds_dwordx4 v[190:191], off
	v_lshl_add_u64 v[190:191], vcc, 0, v[0:1]
	s_mov_b32 m0, s84
	s_nop 0
	global_load_lds_dwordx4 v[190:191], off
	v_lshl_add_u64 v[190:191], v[190:191], 0, s[70:71]
	s_mov_b32 m0, s85
	s_nop 0
	global_load_lds_dwordx4 v[190:191], off
	v_lshl_add_u64 v[190:191], s[8:9], 0, v[0:1]
	s_mov_b32 m0, s88
	v_lshl_add_u64 v[196:197], v[190:191], 0, s[70:71]
	global_load_lds_dwordx4 v[190:191], off
	s_mov_b32 m0, s89
	s_nop 0
	global_load_lds_dwordx4 v[196:197], off
	s_waitcnt vmcnt(8)
	s_waitcnt lgkmcnt(0)
	s_barrier
; #define PG8_STAGE(bufoff, gbase, unused) do { _Pragma("unroll") for (int _i = 0; _i < 2; ++_i) \
;         __builtin_amdgcn_global_load_lds((const unsigned*)((const char*)(gbase) + voff + _i * 8192), (LAS unsigned*)(lds + (bufoff) + ldsw + _i * 8192), 16, 0, 0); } while (0)
; #define PG8_LDA(dst, b, h) do { _Pragma("unroll") for (int m = 0; m < 4; ++m) _Pragma("unroll") for (int k = 0; k < 2; ++k) dst[m][k] = *(const LAS bf16x8*)(lds + PG8_SA(b, h) + aoff + m * 2048 + (FP8 ? k * 16 : k * 1024)); } while (0)
; #define PG8_LDB(dst, b, h) do { _Pragma("unroll") for (int n = 0; n < 2; ++n) _Pragma("unroll") for (int k = 0; k < 2; ++k) dst[n][k] = *(const LAS bf16x8*)(lds + PG8_SB(b, h) + boff + n * 2048 + (FP8 ? k * 16 : k * 1024)); } while (0)
; #define PG8_WAIT_V(n) asm volatile("s_waitcnt vmcnt(" #n ")" ::: "memory")
; #define PG8_WAIT_L(n) asm volatile("s_waitcnt lgkmcnt(" #n ")" ::: "memory")
; #define PG8_BAR __builtin_amdgcn_s_barrier()
; #define PG8_SCHED __builtin_amdgcn_sched_barrier(0)
; template <class Epi, class Sched, bool ALIGN_EPI, bool SP2, int MODE  >
; __device__ __forceinline__ void gemm_phase(LAS unsigned char* lds, const Gemm g, const Sched S, const Epi E, unsigned long long& probe_acc, int epi_id, int wv) {
;     ...
;             PG8_WAIT_V(8); PG8_WAIT_L(0); PG8_BAR; PG8_MMA(1, 0, At, B0); PG8_MMA(1, 1, At, B1); PG8_BAR; PG8_SCHED;
;             PG8_LDB(B0, 1, 0); PG8_LDB(B1, 1, 1); PG8_SCHED; PG8_LDA(At, 1, 0); PG8_STAGE(PG8_SA(0, 1), a2 + hA, voffA);
;             PG8_WAIT_V(8); PG8_WAIT_L(0); PG8_BAR; PG8_MMA(0, 0, At, B0); PG8_MMA(0, 1, At, B1); PG8_BAR; PG8_SCHED;
	v_mfma_f32_16x16x32_bf16 v[94:97], v[130:133], v[166:169], 0
	v_mfma_f32_16x16x32_bf16 v[90:93], v[138:141], v[166:169], 0
	v_mfma_f32_16x16x32_bf16 v[86:89], v[130:133], v[174:177], 0
	v_mfma_f32_16x16x32_bf16 v[82:85], v[138:141], v[174:177], 0
	v_mfma_f32_16x16x32_bf16 v[78:81], v[130:133], v[182:185], 0
	v_mfma_f32_16x16x32_bf16 v[74:77], v[138:141], v[182:185], 0
	v_mfma_f32_16x16x32_bf16 v[70:73], v[130:133], v[200:203], 0
	v_mfma_f32_16x16x32_bf16 v[66:69], v[138:141], v[200:203], 0
	v_mfma_f32_16x16x32_bf16 v[94:97], v[134:137], v[170:173], v[94:97]
	v_mfma_f32_16x16x32_bf16 v[90:93], v[142:145], v[170:173], v[90:93]
	v_mfma_f32_16x16x32_bf16 v[86:89], v[134:137], v[178:181], v[86:89]
	v_mfma_f32_16x16x32_bf16 v[82:85], v[142:145], v[178:181], v[82:85]
	v_mfma_f32_16x16x32_bf16 v[78:81], v[134:137], v[186:189], v[78:81]
	v_mfma_f32_16x16x32_bf16 v[74:77], v[142:145], v[186:189], v[74:77]
	v_mfma_f32_16x16x32_bf16 v[70:73], v[134:137], v[204:207], v[70:73]
	v_mfma_f32_16x16x32_bf16 v[66:69], v[142:145], v[204:207], v[66:69]
	v_mfma_f32_16x16x32_bf16 v[30:33], v[146:149], v[166:169], 0
	v_mfma_f32_16x16x32_bf16 v[26:29], v[158:161], v[166:169], 0
	v_mfma_f32_16x16x32_bf16 v[22:25], v[146:149], v[174:177], 0
	v_mfma_f32_16x16x32_bf16 v[18:21], v[158:161], v[174:177], 0
	v_mfma_f32_16x16x32_bf16 v[14:17], v[146:149], v[182:185], 0
	v_mfma_f32_16x16x32_bf16 v[10:13], v[158:161], v[182:185], 0
	v_mfma_f32_16x16x32_bf16 v[6:9], v[146:149], v[200:203], 0
	v_mfma_f32_16x16x32_bf16 v[2:5], v[158:161], v[200:203], 0
	v_mfma_f32_16x16x32_bf16 v[30:33], v[150:153], v[170:173], v[30:33]
	v_mfma_f32_16x16x32_bf16 v[26:29], v[162:165], v[170:173], v[26:29]
	v_mfma_f32_16x16x32_bf16 v[22:25], v[150:153], v[178:181], v[22:25]
	v_mfma_f32_16x16x32_bf16 v[18:21], v[162:165], v[178:181], v[18:21]
	v_mfma_f32_16x16x32_bf16 v[14:17], v[150:153], v[186:189], v[14:17]
	v_mfma_f32_16x16x32_bf16 v[10:13], v[162:165], v[186:189], v[10:13]
	v_mfma_f32_16x16x32_bf16 v[6:9], v[150:153], v[204:207], v[6:9]
	v_mfma_f32_16x16x32_bf16 v[2:5], v[162:165], v[204:207], v[2:5]
	s_barrier
	v_add_u32_e32 v142, s28, v193
	v_add_u32_e32 v156, s94, v193
	ds_read_b128 v[130:133], v142
	ds_read_b128 v[134:137], v142 offset:1024
	ds_read_b128 v[138:141], v142 offset:2048
	ds_read_b128 v[142:145], v142 offset:3072
	ds_read_b128 v[146:149], v156
	ds_read_b128 v[150:153], v156 offset:1024
	ds_read_b128 v[158:161], v156 offset:2048
	ds_read_b128 v[162:165], v156 offset:3072
	s_add_u32 s8, s8, s36
	s_addc_u32 s9, s9, 0
	s_mov_b32 m0, s29
	v_lshl_add_u64 v[196:197], s[8:9], 0, v[0:1]
	ds_read_b128 v[166:169], v194 offset:32768
	ds_read_b128 v[170:173], v194 offset:33792
	ds_read_b128 v[174:177], v194 offset:34816
	ds_read_b128 v[178:181], v194 offset:35840
	ds_read_b128 v[182:185], v194 offset:36864
	ds_read_b128 v[186:189], v194 offset:37888
	ds_read_b128 v[200:203], v194 offset:38912
	ds_read_b128 v[204:207], v194 offset:39936
	global_load_lds_dwordx4 v[196:197], off
	v_lshl_add_u64 v[196:197], v[196:197], 0, s[70:71]
	s_mov_b32 m0, s92
	s_nop 0
	global_load_lds_dwordx4 v[196:197], off
	s_waitcnt vmcnt(8)
	s_waitcnt lgkmcnt(0)
	s_barrier
	v_mfma_f32_16x16x32_bf16 v[126:129], v[130:133], v[166:169], v[126:129]
	v_mfma_f32_16x16x32_bf16 v[122:125], v[138:141], v[166:169], v[122:125]
	v_mfma_f32_16x16x32_bf16 v[118:121], v[130:133], v[174:177], v[118:121]
	v_mfma_f32_16x16x32_bf16 v[114:117], v[138:141], v[174:177], v[114:117]
	v_mfma_f32_16x16x32_bf16 v[110:113], v[130:133], v[182:185], v[110:113]
	v_mfma_f32_16x16x32_bf16 v[106:109], v[138:141], v[182:185], v[106:109]
	v_mfma_f32_16x16x32_bf16 v[102:105], v[130:133], v[200:203], v[102:105]
	v_mfma_f32_16x16x32_bf16 v[98:101], v[138:141], v[200:203], v[98:101]
	v_mfma_f32_16x16x32_bf16 v[126:129], v[134:137], v[170:173], v[126:129]
	v_mfma_f32_16x16x32_bf16 v[122:125], v[142:145], v[170:173], v[122:125]
	v_mfma_f32_16x16x32_bf16 v[118:121], v[134:137], v[178:181], v[118:121]
	v_mfma_f32_16x16x32_bf16 v[114:117], v[142:145], v[178:181], v[114:117]
	v_mfma_f32_16x16x32_bf16 v[110:113], v[134:137], v[186:189], v[110:113]
	v_mfma_f32_16x16x32_bf16 v[106:109], v[142:145], v[186:189], v[106:109]
	v_mfma_f32_16x16x32_bf16 v[102:105], v[134:137], v[204:207], v[102:105]
	v_mfma_f32_16x16x32_bf16 v[98:101], v[142:145], v[204:207], v[98:101]
	v_mfma_f32_16x16x32_bf16 v[62:65], v[146:149], v[166:169], v[62:65]
	v_mfma_f32_16x16x32_bf16 v[58:61], v[158:161], v[166:169], v[58:61]
	v_mfma_f32_16x16x32_bf16 v[54:57], v[146:149], v[174:177], v[54:57]
	v_mfma_f32_16x16x32_bf16 v[50:53], v[158:161], v[174:177], v[50:53]
	v_mfma_f32_16x16x32_bf16 v[46:49], v[146:149], v[182:185], v[46:49]
	v_mfma_f32_16x16x32_bf16 v[42:45], v[158:161], v[182:185], v[42:45]
	v_mfma_f32_16x16x32_bf16 v[38:41], v[146:149], v[200:203], v[38:41]
	v_mfma_f32_16x16x32_bf16 v[34:37], v[158:161], v[200:203], v[34:37]
	v_mfma_f32_16x16x32_bf16 v[62:65], v[150:153], v[170:173], v[62:65]
	v_mfma_f32_16x16x32_bf16 v[58:61], v[162:165], v[170:173], v[58:61]
	v_mfma_f32_16x16x32_bf16 v[54:57], v[150:153], v[178:181], v[54:57]
	v_mfma_f32_16x16x32_bf16 v[50:53], v[162:165], v[178:181], v[50:53]
	v_mfma_f32_16x16x32_bf16 v[46:49], v[150:153], v[186:189], v[46:49]
	v_mfma_f32_16x16x32_bf16 v[42:45], v[162:165], v[186:189], v[42:45]
	v_mfma_f32_16x16x32_bf16 v[38:41], v[150:153], v[204:207], v[38:41]
	v_mfma_f32_16x16x32_bf16 v[34:37], v[162:165], v[204:207], v[34:37]
	s_barrier
; #define PG8_STAGE(bufoff, gbase, unused) do { _Pragma("unroll") for (int _i = 0; _i < 2; ++_i) \
;         __builtin_amdgcn_global_load_lds((const unsigned*)((const char*)(gbase) + voff + _i * 8192), (LAS unsigned*)(lds + (bufoff) + ldsw + _i * 8192), 16, 0, 0); } while (0)
; #define PG8_LDA(dst, b, h) do { _Pragma("unroll") for (int m = 0; m < 4; ++m) _Pragma("unroll") for (int k = 0; k < 2; ++k) dst[m][k] = *(const LAS bf16x8*)(lds + PG8_SA(b, h) + aoff + m * 2048 + (FP8 ? k * 16 : k * 1024)); } while (0)
; #define PG8_LDB(dst, b, h) do { _Pragma("unroll") for (int n = 0; n < 2; ++n) _Pragma("unroll") for (int k = 0; k < 2; ++k) dst[n][k] = *(const LAS bf16x8*)(lds + PG8_SB(b, h) + boff + n * 2048 + (FP8 ? k * 16 : k * 1024)); } while (0)
; template <class Epi, class Sched, bool ALIGN_EPI, bool SP2, int MODE  >
; __device__ __forceinline__ void gemm_phase(LAS unsigned char* lds, const Gemm g, const Sched S, const Epi E, unsigned long long& probe_acc, int epi_id, int wv) {
;     ...
;         for (int t = 0; t < nt; t += 2) {
;             const bool last = (t == nt - 2);
;             const char* a1 = cA + (size_t)(t + 1) * kstep;
;             const char* a2 = last ? nA : cA + (size_t)(t + 2) * kstep; const char* b2 = last ? nB : cB + (size_t)(t + 2) * kstep;
;             const char* a3 = a2 + kstep; const char* b3 = b2 + kstep;
;             if constexpr (SP2) {
;             PG8_LDB(B0, 0, 0); PG8_LDB(B1, 0, 1); PG8_SCHED; PG8_LDA(At, 0, 0); PG8_STAGE(PG8_SA(1, 1), a1 + hA, voffA);
;             PG8_WAIT_V(8); PG8_WAIT_L(0); PG8_BAR; PG8_MMA(0, 0, At, B0); PG8_MMA(0, 1, At, B1); PG8_BAR; PG8_SCHED;
;             PG8_LDA(At, 0, 1); PG8_STAGE(PG8_SB(0, 0), b2, voffB); PG8_STAGE(PG8_SB(0, 1), b2 + hB, voffB); PG8_STAGE(PG8_SA(0, 0), a2, voffA);
;             PG8_WAIT_V(8); PG8_WAIT_L(0); PG8_BAR; PG8_MMA(1, 0, At, B0); PG8_MMA(1, 1, At, B1); PG8_BAR; PG8_SCHED;
;             PG8_LDB(B0, 1, 0); PG8_LDB(B1, 1, 1); PG8_SCHED; PG8_LDA(At, 1, 0); PG8_STAGE(PG8_SA(0, 1), a2 + hA, voffA);
;             PG8_WAIT_V(8); PG8_WAIT_L(0); PG8_BAR; PG8_MMA(0, 0, At, B0); PG8_MMA(0, 1, At, B1); PG8_BAR; PG8_SCHED;
;             PG8_LDA(At, 1, 1); PG8_STAGE(PG8_SB(1, 0), b3, voffB); PG8_STAGE(PG8_SB(1, 1), b3 + hB, voffB); PG8_STAGE(PG8_SA(1, 0), a3, voffA);
;             PG8_WAIT_V(8); PG8_WAIT_L(0); PG8_BAR; PG8_MMA(1, 0, At, B0); PG8_MMA(1, 1, At, B1); PG8_BAR; PG8_SCHED;
	s_add_u32 s6, s6, 0x4000
	s_addc_u32 s7, s7, 0
	s_mov_b32 m0, s2
	v_lshl_add_u64 v[196:197], s[6:7], 0, v[0:1]
	s_add_u32 s6, s6, s13
	ds_read_b128 v[166:169], v194 offset:49152
	ds_read_b128 v[170:173], v194 offset:50176
	ds_read_b128 v[174:177], v194 offset:51200
	ds_read_b128 v[178:181], v194 offset:52224
	ds_read_b128 v[182:185], v194 offset:53248
	ds_read_b128 v[186:189], v194 offset:54272
	ds_read_b128 v[200:203], v194 offset:55296
	ds_read_b128 v[204:207], v194 offset:56320
	global_load_lds_dwordx4 v[196:197], off
	v_lshl_add_u64 v[196:197], v[196:197], 0, s[70:71]
	s_mov_b32 m0, s3
	s_addc_u32 s7, s7, 0
	global_load_lds_dwordx4 v[196:197], off
	v_lshl_add_u64 v[196:197], s[6:7], 0, v[0:1]
	s_mov_b32 m0, s12
	s_nop 0
	global_load_lds_dwordx4 v[196:197], off
	v_lshl_add_u64 v[196:197], v[196:197], 0, s[70:71]
	s_mov_b32 m0, s95
	s_nop 0
	global_load_lds_dwordx4 v[196:197], off
	v_lshl_add_u64 v[196:197], v[190:191], 0, s[76:77]
	s_mov_b32 m0, s50
	v_lshl_add_u64 v[190:191], v[190:191], 0, s[78:79]
	global_load_lds_dwordx4 v[196:197], off
	s_mov_b32 m0, s51
	s_nop 0
	global_load_lds_dwordx4 v[190:191], off
	s_waitcnt vmcnt(8)
	s_waitcnt lgkmcnt(0)
	s_barrier
	v_mfma_f32_16x16x32_bf16 v[94:97], v[130:133], v[166:169], v[94:97]
	v_mfma_f32_16x16x32_bf16 v[90:93], v[138:141], v[166:169], v[90:93]
	v_mfma_f32_16x16x32_bf16 v[86:89], v[130:133], v[174:177], v[86:89]
	v_mfma_f32_16x16x32_bf16 v[82:85], v[138:141], v[174:177], v[82:85]
	v_mfma_f32_16x16x32_bf16 v[78:81], v[130:133], v[182:185], v[78:81]
	v_mfma_f32_16x16x32_bf16 v[74:77], v[138:141], v[182:185], v[74:77]
	v_mfma_f32_16x16x32_bf16 v[70:73], v[130:133], v[200:203], v[70:73]
	v_mfma_f32_16x16x32_bf16 v[66:69], v[138:141], v[200:203], v[66:69]
	v_mfma_f32_16x16x32_bf16 v[94:97], v[134:137], v[170:173], v[94:97]
	v_mfma_f32_16x16x32_bf16 v[90:93], v[142:145], v[170:173], v[90:93]
	v_mfma_f32_16x16x32_bf16 v[86:89], v[134:137], v[178:181], v[86:89]
	v_mfma_f32_16x16x32_bf16 v[82:85], v[142:145], v[178:181], v[82:85]
	v_mfma_f32_16x16x32_bf16 v[78:81], v[134:137], v[186:189], v[78:81]
	v_mfma_f32_16x16x32_bf16 v[74:77], v[142:145], v[186:189], v[74:77]
	v_mfma_f32_16x16x32_bf16 v[70:73], v[134:137], v[204:207], v[70:73]
	v_mfma_f32_16x16x32_bf16 v[66:69], v[142:145], v[204:207], v[66:69]
	v_mfma_f32_16x16x32_bf16 v[30:33], v[146:149], v[166:169], v[30:33]
	v_mfma_f32_16x16x32_bf16 v[26:29], v[158:161], v[166:169], v[26:29]
	v_mfma_f32_16x16x32_bf16 v[22:25], v[146:149], v[174:177], v[22:25]
	v_mfma_f32_16x16x32_bf16 v[18:21], v[158:161], v[174:177], v[18:21]
	v_mfma_f32_16x16x32_bf16 v[14:17], v[146:149], v[182:185], v[14:17]
	v_mfma_f32_16x16x32_bf16 v[10:13], v[158:161], v[182:185], v[10:13]
	v_mfma_f32_16x16x32_bf16 v[6:9], v[146:149], v[200:203], v[6:9]
	v_mfma_f32_16x16x32_bf16 v[2:5], v[158:161], v[200:203], v[2:5]
	v_mfma_f32_16x16x32_bf16 v[30:33], v[150:153], v[170:173], v[30:33]
	v_mfma_f32_16x16x32_bf16 v[26:29], v[162:165], v[170:173], v[26:29]
	v_mfma_f32_16x16x32_bf16 v[22:25], v[150:153], v[178:181], v[22:25]
	v_mfma_f32_16x16x32_bf16 v[18:21], v[162:165], v[178:181], v[18:21]
	v_mfma_f32_16x16x32_bf16 v[14:17], v[150:153], v[186:189], v[14:17]
	v_mfma_f32_16x16x32_bf16 v[10:13], v[162:165], v[186:189], v[10:13]
	v_mfma_f32_16x16x32_bf16 v[6:9], v[150:153], v[204:207], v[6:9]
	v_mfma_f32_16x16x32_bf16 v[2:5], v[162:165], v[204:207], v[2:5]
	s_barrier
	s_add_u32 s10, s10, 0x8000
	s_addc_u32 s11, s11, 0
	s_add_u32 s4, s4, 0x8000
	s_addc_u32 s5, s5, 0
	s_cmp_ge_u32 s40, s58
	s_mov_b32 s6, s40
	v_readlane_b32 s98, v254, 1
	s_nop 3
	s_cmp_ge_u32 s98, 4
	s_cbranch_scc0 .Lprio_skip_2
	s_setprio 1
.Lprio_skip_2:
.LBB0_674:
	v_add_u32_e32 v142, s15, v193
	v_add_u32_e32 v156, s39, v193
	ds_read_b128 v[130:133], v142
	ds_read_b128 v[134:137], v142 offset:1024
	ds_read_b128 v[138:141], v142 offset:2048
	ds_read_b128 v[142:145], v142 offset:3072
	ds_read_b128 v[146:149], v156
	ds_read_b128 v[150:153], v156 offset:1024
	ds_read_b128 v[158:161], v156 offset:2048
	ds_read_b128 v[162:165], v156 offset:3072
	s_add_i32 s40, s6, 2
	s_cmp_eq_u32 s93, s6
	s_cselect_b32 s6, s34, s10
	s_cselect_b32 s9, s87, s5
	s_cselect_b32 s8, s86, s4
	s_cselect_b32 s7, s35, s11
	s_movk_i32 vcc_lo, 0xc000
	v_lshl_add_u64 v[190:191], s[4:5], 0, v[154:155]
	s_mov_b32 vcc_hi, -1
	v_lshl_add_u64 v[196:197], v[190:191], 0, vcc
	s_movk_i32 vcc_lo, 0xe000
	s_add_i32 m0, s88, 0xc000
	s_mov_b32 vcc_hi, -1
	ds_read_b128 v[166:169], v194
	ds_read_b128 v[170:173], v194 offset:1024
	ds_read_b128 v[174:177], v194 offset:2048
	ds_read_b128 v[178:181], v194 offset:3072
	ds_read_b128 v[182:185], v194 offset:4096
	ds_read_b128 v[186:189], v194 offset:5120
	ds_read_b128 v[200:203], v194 offset:6144
	ds_read_b128 v[204:207], v194 offset:7168
	global_load_lds_dwordx4 v[196:197], off
	v_lshl_add_u64 v[190:191], v[190:191], 0, vcc
	s_add_i32 m0, s88, 0xe000
	s_nop 0
	global_load_lds_dwordx4 v[190:191], off
	s_waitcnt vmcnt(8)
	s_waitcnt lgkmcnt(0)
	s_barrier
; #define PG8_STAGE(bufoff, gbase, unused) do { _Pragma("unroll") for (int _i = 0; _i < 2; ++_i) \
;         __builtin_amdgcn_global_load_lds((const unsigned*)((const char*)(gbase) + voff + _i * 8192), (LAS unsigned*)(lds + (bufoff) + ldsw + _i * 8192), 16, 0, 0); } while (0)
; #define PG8_LDA(dst, b, h) do { _Pragma("unroll") for (int m = 0; m < 4; ++m) _Pragma("unroll") for (int k = 0; k < 2; ++k) dst[m][k] = *(const LAS bf16x8*)(lds + PG8_SA(b, h) + aoff + m * 2048 + (FP8 ? k * 16 : k * 1024)); } while (0)
; #define PG8_WAIT_V(n) asm volatile("s_waitcnt vmcnt(" #n ")" ::: "memory")
; #define PG8_WAIT_L(n) asm volatile("s_waitcnt lgkmcnt(" #n ")" ::: "memory")
; #define PG8_BAR __builtin_amdgcn_s_barrier()
; #define PG8_SCHED __builtin_amdgcn_sched_barrier(0)
; template <class Epi, class Sched, bool ALIGN_EPI, bool SP2, int MODE  >
; __device__ __forceinline__ void gemm_phase(LAS unsigned char* lds, const Gemm g, const Sched S, const Epi E, unsigned long long& probe_acc, int epi_id, int wv) {
;     ...
;             PG8_WAIT_V(8); PG8_WAIT_L(0); PG8_BAR; PG8_MMA(0, 0, At, B0); PG8_MMA(0, 1, At, B1); PG8_BAR; PG8_SCHED;
;             PG8_LDA(At, 0, 1); PG8_STAGE(PG8_SB(0, 0), b2, voffB); PG8_STAGE(PG8_SB(0, 1), b2 + hB, voffB); PG8_STAGE(PG8_SA(0, 0), a2, voffA);
;             PG8_WAIT_V(8); PG8_WAIT_L(0); PG8_BAR; PG8_MMA(1, 0, At, B0); PG8_MMA(1, 1, At, B1); PG8_BAR; PG8_SCHED;
	v_mfma_f32_16x16x32_bf16 v[126:129], v[130:133], v[166:169], v[126:129]
	v_mfma_f32_16x16x32_bf16 v[122:125], v[138:141], v[166:169], v[122:125]
	v_mfma_f32_16x16x32_bf16 v[118:121], v[130:133], v[174:177], v[118:121]
	v_mfma_f32_16x16x32_bf16 v[114:117], v[138:141], v[174:177], v[114:117]
	v_mfma_f32_16x16x32_bf16 v[110:113], v[130:133], v[182:185], v[110:113]
	v_mfma_f32_16x16x32_bf16 v[106:109], v[138:141], v[182:185], v[106:109]
	v_mfma_f32_16x16x32_bf16 v[102:105], v[130:133], v[200:203], v[102:105]
	v_mfma_f32_16x16x32_bf16 v[98:101], v[138:141], v[200:203], v[98:101]
	v_mfma_f32_16x16x32_bf16 v[126:129], v[134:137], v[170:173], v[126:129]
	v_mfma_f32_16x16x32_bf16 v[122:125], v[142:145], v[170:173], v[122:125]
	v_mfma_f32_16x16x32_bf16 v[118:121], v[134:137], v[178:181], v[118:121]
	v_mfma_f32_16x16x32_bf16 v[114:117], v[142:145], v[178:181], v[114:117]
	v_mfma_f32_16x16x32_bf16 v[110:113], v[134:137], v[186:189], v[110:113]
	v_mfma_f32_16x16x32_bf16 v[106:109], v[142:145], v[186:189], v[106:109]
	v_mfma_f32_16x16x32_bf16 v[102:105], v[134:137], v[204:207], v[102:105]
	v_mfma_f32_16x16x32_bf16 v[98:101], v[142:145], v[204:207], v[98:101]
	v_mfma_f32_16x16x32_bf16 v[62:65], v[146:149], v[166:169], v[62:65]
	v_mfma_f32_16x16x32_bf16 v[58:61], v[158:161], v[166:169], v[58:61]
	v_mfma_f32_16x16x32_bf16 v[54:57], v[146:149], v[174:177], v[54:57]
	v_mfma_f32_16x16x32_bf16 v[50:53], v[158:161], v[174:177], v[50:53]
	v_mfma_f32_16x16x32_bf16 v[46:49], v[146:149], v[182:185], v[46:49]
	v_mfma_f32_16x16x32_bf16 v[42:45], v[158:161], v[182:185], v[42:45]
	v_mfma_f32_16x16x32_bf16 v[38:41], v[146:149], v[200:203], v[38:41]
	v_mfma_f32_16x16x32_bf16 v[34:37], v[158:161], v[200:203], v[34:37]
	v_mfma_f32_16x16x32_bf16 v[62:65], v[150:153], v[170:173], v[62:65]
	v_mfma_f32_16x16x32_bf16 v[58:61], v[162:165], v[170:173], v[58:61]
	v_mfma_f32_16x16x32_bf16 v[54:57], v[150:153], v[178:181], v[54:57]
	v_mfma_f32_16x16x32_bf16 v[50:53], v[162:165], v[178:181], v[50:53]
	v_mfma_f32_16x16x32_bf16 v[46:49], v[150:153], v[186:189], v[46:49]
	v_mfma_f32_16x16x32_bf16 v[42:45], v[162:165], v[186:189], v[42:45]
	v_mfma_f32_16x16x32_bf16 v[38:41], v[150:153], v[204:207], v[38:41]
	v_mfma_f32_16x16x32_bf16 v[34:37], v[162:165], v[204:207], v[34:37]
	s_barrier
	s_mov_b32 m0, s26
	v_lshl_add_u64 v[190:191], s[6:7], 0, v[0:1]
	s_add_u32 vcc_lo, s6, s13
	ds_read_b128 v[166:169], v194 offset:16384
	ds_read_b128 v[170:173], v194 offset:17408
	ds_read_b128 v[174:177], v194 offset:18432
	ds_read_b128 v[178:181], v194 offset:19456
	ds_read_b128 v[182:185], v194 offset:20480
	ds_read_b128 v[186:189], v194 offset:21504
	ds_read_b128 v[200:203], v194 offset:22528
	ds_read_b128 v[204:207], v194 offset:23552
	global_load_lds_dwordx4 v[190:191], off
	v_lshl_add_u64 v[190:191], v[190:191], 0, s[70:71]
	s_mov_b32 m0, s27
	s_addc_u32 vcc_hi, s7, 0
	global_load_lds_dwordx4 v[190:191], off
	v_lshl_add_u64 v[190:191], vcc, 0, v[0:1]
	s_mov_b32 m0, s84
	s_nop 0
	global_load_lds_dwordx4 v[190:191], off
	v_lshl_add_u64 v[190:191], v[190:191], 0, s[70:71]
	s_mov_b32 m0, s85
	s_nop 0
	global_load_lds_dwordx4 v[190:191], off
	v_lshl_add_u64 v[190:191], s[8:9], 0, v[0:1]
	s_mov_b32 m0, s88
	v_lshl_add_u64 v[196:197], v[190:191], 0, s[70:71]
	global_load_lds_dwordx4 v[190:191], off
	s_mov_b32 m0, s89
	s_nop 0
	global_load_lds_dwordx4 v[196:197], off
	s_waitcnt vmcnt(8)
	s_waitcnt lgkmcnt(0)
	s_barrier
	v_mfma_f32_16x16x32_bf16 v[94:97], v[130:133], v[166:169], v[94:97]
	v_mfma_f32_16x16x32_bf16 v[90:93], v[138:141], v[166:169], v[90:93]
	v_mfma_f32_16x16x32_bf16 v[86:89], v[130:133], v[174:177], v[86:89]
	v_mfma_f32_16x16x32_bf16 v[82:85], v[138:141], v[174:177], v[82:85]
	v_mfma_f32_16x16x32_bf16 v[78:81], v[130:133], v[182:185], v[78:81]
	v_mfma_f32_16x16x32_bf16 v[74:77], v[138:141], v[182:185], v[74:77]
	v_mfma_f32_16x16x32_bf16 v[70:73], v[130:133], v[200:203], v[70:73]
	v_mfma_f32_16x16x32_bf16 v[66:69], v[138:141], v[200:203], v[66:69]
	v_mfma_f32_16x16x32_bf16 v[94:97], v[134:137], v[170:173], v[94:97]
	v_mfma_f32_16x16x32_bf16 v[90:93], v[142:145], v[170:173], v[90:93]
	v_mfma_f32_16x16x32_bf16 v[86:89], v[134:137], v[178:181], v[86:89]
	v_mfma_f32_16x16x32_bf16 v[82:85], v[142:145], v[178:181], v[82:85]
	v_mfma_f32_16x16x32_bf16 v[78:81], v[134:137], v[186:189], v[78:81]
	v_mfma_f32_16x16x32_bf16 v[74:77], v[142:145], v[186:189], v[74:77]
	v_mfma_f32_16x16x32_bf16 v[70:73], v[134:137], v[204:207], v[70:73]
	v_mfma_f32_16x16x32_bf16 v[66:69], v[142:145], v[204:207], v[66:69]
	v_mfma_f32_16x16x32_bf16 v[30:33], v[146:149], v[166:169], v[30:33]
	v_mfma_f32_16x16x32_bf16 v[26:29], v[158:161], v[166:169], v[26:29]
	v_mfma_f32_16x16x32_bf16 v[22:25], v[146:149], v[174:177], v[22:25]
	v_mfma_f32_16x16x32_bf16 v[18:21], v[158:161], v[174:177], v[18:21]
	v_mfma_f32_16x16x32_bf16 v[14:17], v[146:149], v[182:185], v[14:17]
	v_mfma_f32_16x16x32_bf16 v[10:13], v[158:161], v[182:185], v[10:13]
	v_mfma_f32_16x16x32_bf16 v[6:9], v[146:149], v[200:203], v[6:9]
	v_mfma_f32_16x16x32_bf16 v[2:5], v[158:161], v[200:203], v[2:5]
	v_mfma_f32_16x16x32_bf16 v[30:33], v[150:153], v[170:173], v[30:33]
	v_mfma_f32_16x16x32_bf16 v[26:29], v[162:165], v[170:173], v[26:29]
	v_mfma_f32_16x16x32_bf16 v[22:25], v[150:153], v[178:181], v[22:25]
	v_mfma_f32_16x16x32_bf16 v[18:21], v[162:165], v[178:181], v[18:21]
	v_mfma_f32_16x16x32_bf16 v[14:17], v[150:153], v[186:189], v[14:17]
	v_mfma_f32_16x16x32_bf16 v[10:13], v[162:165], v[186:189], v[10:13]
	v_mfma_f32_16x16x32_bf16 v[6:9], v[150:153], v[204:207], v[6:9]
	v_mfma_f32_16x16x32_bf16 v[2:5], v[162:165], v[204:207], v[2:5]
	s_barrier
; #define PG8_STAGE(bufoff, gbase, unused) do { _Pragma("unroll") for (int _i = 0; _i < 2; ++_i) \
;         __builtin_amdgcn_global_load_lds((const unsigned*)((const char*)(gbase) + voff + _i * 8192), (LAS unsigned*)(lds + (bufoff) + ldsw + _i * 8192), 16, 0, 0); } while (0)
; #define PG8_LDA(dst, b, h) do { _Pragma("unroll") for (int m = 0; m < 4; ++m) _Pragma("unroll") for (int k = 0; k < 2; ++k) dst[m][k] = *(const LAS bf16x8*)(lds + PG8_SA(b, h) + aoff + m * 2048 + (FP8 ? k * 16 : k * 1024)); } while (0)
; #define PG8_LDB(dst, b, h) do { _Pragma("unroll") for (int n = 0; n < 2; ++n) _Pragma("unroll") for (int k = 0; k < 2; ++k) dst[n][k] = *(const LAS bf16x8*)(lds + PG8_SB(b, h) + boff + n * 2048 + (FP8 ? k * 16 : k * 1024)); } while (0)
; #define PG8_WAIT_V(n) asm volatile("s_waitcnt vmcnt(" #n ")" ::: "memory")
; #define PG8_WAIT_L(n) asm volatile("s_waitcnt lgkmcnt(" #n ")" ::: "memory")
; #define PG8_BAR __builtin_amdgcn_s_barrier()
; #define PG8_SCHED __builtin_amdgcn_sched_barrier(0)
; template <class Epi, class Sched, bool ALIGN_EPI, bool SP2, int MODE  >
; __device__ __forceinline__ void gemm_phase(LAS unsigned char* lds, const Gemm g, const Sched S, const Epi E, unsigned long long& probe_acc, int epi_id, int wv) {
;     ...
;             PG8_LDB(B0, 0, 0); PG8_LDB(B1, 0, 1); PG8_SCHED; PG8_LDA(At, 0, 0); PG8_STAGE(PG8_SA(1, 1), a1 + hA, voffA);
;             PG8_WAIT_V(8); PG8_WAIT_L(0); PG8_BAR; PG8_MMA(0, 0, At, B0); PG8_MMA(0, 1, At, B1); PG8_BAR; PG8_SCHED;
;             PG8_LDA(At, 0, 1); PG8_STAGE(PG8_SB(0, 0), b2, voffB); PG8_STAGE(PG8_SB(0, 1), b2 + hB, voffB); PG8_STAGE(PG8_SA(0, 0), a2, voffA);
;             PG8_WAIT_V(8); PG8_WAIT_L(0); PG8_BAR; PG8_MMA(1, 0, At, B0); PG8_MMA(1, 1, At, B1); PG8_BAR; PG8_SCHED;
;             PG8_LDB(B0, 1, 0); PG8_LDB(B1, 1, 1); PG8_SCHED; PG8_LDA(At, 1, 0); PG8_STAGE(PG8_SA(0, 1), a2 + hA, voffA);
;             PG8_WAIT_V(8); PG8_WAIT_L(0); PG8_BAR; PG8_MMA(0, 0, At, B0); PG8_MMA(0, 1, At, B1); PG8_BAR; PG8_SCHED;
;             PG8_LDA(At, 1, 1); PG8_STAGE(PG8_SB(1, 0), b3, voffB); PG8_STAGE(PG8_SB(1, 1), b3 + hB, voffB); PG8_STAGE(PG8_SA(1, 0), a3, voffA);
;             PG8_WAIT_V(8); PG8_WAIT_L(0); PG8_BAR; PG8_MMA(1, 0, At, B0); PG8_MMA(1, 1, At, B1); PG8_BAR; PG8_SCHED;
;     ...
;         if constexpr (ALIGN_EPI) { if (wr == 0) PG8_BAR; }
	v_add_u32_e32 v142, s28, v193
	v_add_u32_e32 v156, s94, v193
	ds_read_b128 v[130:133], v142
	ds_read_b128 v[134:137], v142 offset:1024
	ds_read_b128 v[138:141], v142 offset:2048
	ds_read_b128 v[142:145], v142 offset:3072
	ds_read_b128 v[146:149], v156
	ds_read_b128 v[150:153], v156 offset:1024
	ds_read_b128 v[158:161], v156 offset:2048
	ds_read_b128 v[162:165], v156 offset:3072
	s_add_u32 s8, s8, s36
	s_addc_u32 s9, s9, 0
	s_mov_b32 m0, s29
	v_lshl_add_u64 v[196:197], s[8:9], 0, v[0:1]
	ds_read_b128 v[166:169], v194 offset:32768
	ds_read_b128 v[170:173], v194 offset:33792
	ds_read_b128 v[174:177], v194 offset:34816
	ds_read_b128 v[178:181], v194 offset:35840
	ds_read_b128 v[182:185], v194 offset:36864
	ds_read_b128 v[186:189], v194 offset:37888
	ds_read_b128 v[200:203], v194 offset:38912
	ds_read_b128 v[204:207], v194 offset:39936
	global_load_lds_dwordx4 v[196:197], off
	v_lshl_add_u64 v[196:197], v[196:197], 0, s[70:71]
	s_mov_b32 m0, s92
	s_nop 0
	global_load_lds_dwordx4 v[196:197], off
	s_waitcnt vmcnt(8)
	s_waitcnt lgkmcnt(0)
	s_barrier
	v_mfma_f32_16x16x32_bf16 v[126:129], v[130:133], v[166:169], v[126:129]
	v_mfma_f32_16x16x32_bf16 v[122:125], v[138:141], v[166:169], v[122:125]
	v_mfma_f32_16x16x32_bf16 v[118:121], v[130:133], v[174:177], v[118:121]
	v_mfma_f32_16x16x32_bf16 v[114:117], v[138:141], v[174:177], v[114:117]
	v_mfma_f32_16x16x32_bf16 v[110:113], v[130:133], v[182:185], v[110:113]
	v_mfma_f32_16x16x32_bf16 v[106:109], v[138:141], v[182:185], v[106:109]
	v_mfma_f32_16x16x32_bf16 v[102:105], v[130:133], v[200:203], v[102:105]
	v_mfma_f32_16x16x32_bf16 v[98:101], v[138:141], v[200:203], v[98:101]
	v_mfma_f32_16x16x32_bf16 v[126:129], v[134:137], v[170:173], v[126:129]
	v_mfma_f32_16x16x32_bf16 v[122:125], v[142:145], v[170:173], v[122:125]
	v_mfma_f32_16x16x32_bf16 v[118:121], v[134:137], v[178:181], v[118:121]
	v_mfma_f32_16x16x32_bf16 v[114:117], v[142:145], v[178:181], v[114:117]
	v_mfma_f32_16x16x32_bf16 v[110:113], v[134:137], v[186:189], v[110:113]
	v_mfma_f32_16x16x32_bf16 v[106:109], v[142:145], v[186:189], v[106:109]
	v_mfma_f32_16x16x32_bf16 v[102:105], v[134:137], v[204:207], v[102:105]
	v_mfma_f32_16x16x32_bf16 v[98:101], v[142:145], v[204:207], v[98:101]
	v_mfma_f32_16x16x32_bf16 v[62:65], v[146:149], v[166:169], v[62:65]
	v_mfma_f32_16x16x32_bf16 v[58:61], v[158:161], v[166:169], v[58:61]
	v_mfma_f32_16x16x32_bf16 v[54:57], v[146:149], v[174:177], v[54:57]
	v_mfma_f32_16x16x32_bf16 v[50:53], v[158:161], v[174:177], v[50:53]
	v_mfma_f32_16x16x32_bf16 v[46:49], v[146:149], v[182:185], v[46:49]
	v_mfma_f32_16x16x32_bf16 v[42:45], v[158:161], v[182:185], v[42:45]
	v_mfma_f32_16x16x32_bf16 v[38:41], v[146:149], v[200:203], v[38:41]
	v_mfma_f32_16x16x32_bf16 v[34:37], v[158:161], v[200:203], v[34:37]
	v_mfma_f32_16x16x32_bf16 v[62:65], v[150:153], v[170:173], v[62:65]
	v_mfma_f32_16x16x32_bf16 v[58:61], v[162:165], v[170:173], v[58:61]
	v_mfma_f32_16x16x32_bf16 v[54:57], v[150:153], v[178:181], v[54:57]
	v_mfma_f32_16x16x32_bf16 v[50:53], v[162:165], v[178:181], v[50:53]
	v_mfma_f32_16x16x32_bf16 v[46:49], v[150:153], v[186:189], v[46:49]
	v_mfma_f32_16x16x32_bf16 v[42:45], v[162:165], v[186:189], v[42:45]
	v_mfma_f32_16x16x32_bf16 v[38:41], v[150:153], v[204:207], v[38:41]
	v_mfma_f32_16x16x32_bf16 v[34:37], v[162:165], v[204:207], v[34:37]
	s_barrier
	s_add_u32 s6, s6, 0x4000
	s_addc_u32 s7, s7, 0
	s_mov_b32 m0, s2
	v_lshl_add_u64 v[196:197], s[6:7], 0, v[0:1]
	s_add_u32 s6, s6, s13
	ds_read_b128 v[166:169], v194 offset:49152
	ds_read_b128 v[170:173], v194 offset:50176
	ds_read_b128 v[174:177], v194 offset:51200
	ds_read_b128 v[178:181], v194 offset:52224
	ds_read_b128 v[182:185], v194 offset:53248
	ds_read_b128 v[186:189], v194 offset:54272
	ds_read_b128 v[200:203], v194 offset:55296
	ds_read_b128 v[204:207], v194 offset:56320
	global_load_lds_dwordx4 v[196:197], off
	v_lshl_add_u64 v[196:197], v[196:197], 0, s[70:71]
	s_mov_b32 m0, s3
	s_addc_u32 s7, s7, 0
	global_load_lds_dwordx4 v[196:197], off
	v_lshl_add_u64 v[196:197], s[6:7], 0, v[0:1]
	s_mov_b32 m0, s12
	s_nop 0
	global_load_lds_dwordx4 v[196:197], off
	v_lshl_add_u64 v[196:197], v[196:197], 0, s[70:71]
	s_mov_b32 m0, s95
	s_nop 0
	global_load_lds_dwordx4 v[196:197], off
	v_lshl_add_u64 v[196:197], v[190:191], 0, s[76:77]
	s_mov_b32 m0, s50
	v_lshl_add_u64 v[190:191], v[190:191], 0, s[78:79]
	global_load_lds_dwordx4 v[196:197], off
	s_mov_b32 m0, s51
	s_nop 0
	global_load_lds_dwordx4 v[190:191], off
	s_waitcnt vmcnt(8)
	s_waitcnt lgkmcnt(0)
	s_barrier
	v_mfma_f32_16x16x32_bf16 v[94:97], v[130:133], v[166:169], v[94:97]
	v_mfma_f32_16x16x32_bf16 v[90:93], v[138:141], v[166:169], v[90:93]
	v_mfma_f32_16x16x32_bf16 v[86:89], v[130:133], v[174:177], v[86:89]
	v_mfma_f32_16x16x32_bf16 v[82:85], v[138:141], v[174:177], v[82:85]
	v_mfma_f32_16x16x32_bf16 v[78:81], v[130:133], v[182:185], v[78:81]
	v_mfma_f32_16x16x32_bf16 v[74:77], v[138:141], v[182:185], v[74:77]
	v_mfma_f32_16x16x32_bf16 v[70:73], v[130:133], v[200:203], v[70:73]
	v_mfma_f32_16x16x32_bf16 v[66:69], v[138:141], v[200:203], v[66:69]
	v_mfma_f32_16x16x32_bf16 v[94:97], v[134:137], v[170:173], v[94:97]
	v_mfma_f32_16x16x32_bf16 v[90:93], v[142:145], v[170:173], v[90:93]
	v_mfma_f32_16x16x32_bf16 v[86:89], v[134:137], v[178:181], v[86:89]
	v_mfma_f32_16x16x32_bf16 v[82:85], v[142:145], v[178:181], v[82:85]
	v_mfma_f32_16x16x32_bf16 v[78:81], v[134:137], v[186:189], v[78:81]
	v_mfma_f32_16x16x32_bf16 v[74:77], v[142:145], v[186:189], v[74:77]
	v_mfma_f32_16x16x32_bf16 v[70:73], v[134:137], v[204:207], v[70:73]
	v_mfma_f32_16x16x32_bf16 v[66:69], v[142:145], v[204:207], v[66:69]
	v_mfma_f32_16x16x32_bf16 v[30:33], v[146:149], v[166:169], v[30:33]
	v_mfma_f32_16x16x32_bf16 v[26:29], v[158:161], v[166:169], v[26:29]
	v_mfma_f32_16x16x32_bf16 v[22:25], v[146:149], v[174:177], v[22:25]
	v_mfma_f32_16x16x32_bf16 v[18:21], v[158:161], v[174:177], v[18:21]
	v_mfma_f32_16x16x32_bf16 v[14:17], v[146:149], v[182:185], v[14:17]
	v_mfma_f32_16x16x32_bf16 v[10:13], v[158:161], v[182:185], v[10:13]
	v_mfma_f32_16x16x32_bf16 v[6:9], v[146:149], v[200:203], v[6:9]
	v_mfma_f32_16x16x32_bf16 v[2:5], v[158:161], v[200:203], v[2:5]
	v_mfma_f32_16x16x32_bf16 v[30:33], v[150:153], v[170:173], v[30:33]
	v_mfma_f32_16x16x32_bf16 v[26:29], v[162:165], v[170:173], v[26:29]
	v_mfma_f32_16x16x32_bf16 v[22:25], v[150:153], v[178:181], v[22:25]
	v_mfma_f32_16x16x32_bf16 v[18:21], v[162:165], v[178:181], v[18:21]
	v_mfma_f32_16x16x32_bf16 v[14:17], v[150:153], v[186:189], v[14:17]
	v_mfma_f32_16x16x32_bf16 v[10:13], v[162:165], v[186:189], v[10:13]
	v_mfma_f32_16x16x32_bf16 v[6:9], v[150:153], v[204:207], v[6:9]
	v_mfma_f32_16x16x32_bf16 v[2:5], v[162:165], v[204:207], v[2:5]
	s_barrier
	s_add_u32 s10, s10, 0x8000
	s_addc_u32 s11, s11, 0
	s_add_u32 s4, s4, 0x8000
	s_addc_u32 s5, s5, 0
	s_cmp_ge_u32 s40, s58
	s_mov_b32 s6, s40
	s_cbranch_scc0 .LBB0_674
	v_readlane_b32 s4, v255, 30
	v_readlane_b32 s5, v255, 31
	s_and_b64 vcc, exec, s[4:5]
	s_cbranch_vccz .LBB0_677
	s_barrier

; #define PG8_STAGE(bufoff, gbase, unused) do { _Pragma("unroll") for (int _i = 0; _i < 2; ++_i) \
;         __builtin_amdgcn_global_load_lds((const unsigned*)((const char*)(gbase) + voff + _i * 8192), (LAS unsigned*)(lds + (bufoff) + ldsw + _i * 8192), 16, 0, 0); } while (0)
; #define PG8_LDA(dst, b, h) do { _Pragma("unroll") for (int m = 0; m < 4; ++m) _Pragma("unroll") for (int k = 0; k < 2; ++k) dst[m][k] = *(const LAS bf16x8*)(lds + PG8_SA(b, h) + aoff + m * 2048 + (FP8 ? k * 16 : k * 1024)); } while (0)
; #define PG8_LDB(dst, b, h) do { _Pragma("unroll") for (int n = 0; n < 2; ++n) _Pragma("unroll") for (int k = 0; k < 2; ++k) dst[n][k] = *(const LAS bf16x8*)(lds + PG8_SB(b, h) + boff + n * 2048 + (FP8 ? k * 16 : k * 1024)); } while (0)
; #define PG8_WAIT_V(n) asm volatile("s_waitcnt vmcnt(" #n ")" ::: "memory")
; #define PG8_WAIT_L(n) asm volatile("s_waitcnt lgkmcnt(" #n ")" ::: "memory")
; #define PG8_BAR __builtin_amdgcn_s_barrier()
; template <class Epi, class Sched, bool ALIGN_EPI, bool SP2, int MODE  >
; __device__ __forceinline__ void gemm_phase(LAS unsigned char* lds, const Gemm g, const Sched S, const Epi E, unsigned long long& probe_acc, int epi_id, int wv) {
;     ...
;         for (int t = 0; t < nt; t += 2) {
;             const bool last = (t == nt - 2);
;             const char* a1 = cA + (size_t)(t + 1) * kstep;
;             const char* a2 = last ? nA : cA + (size_t)(t + 2) * kstep; const char* b2 = last ? nB : cB + (size_t)(t + 2) * kstep;
;             const char* a3 = a2 + kstep; const char* b3 = b2 + kstep;
;             if constexpr (SP2) {
;             PG8_LDB(B0, 0, 0); PG8_LDB(B1, 0, 1); PG8_SCHED; PG8_LDA(At, 0, 0); PG8_STAGE(PG8_SA(1, 1), a1 + hA, voffA);
;             PG8_WAIT_V(8); PG8_WAIT_L(0); PG8_BAR; PG8_MMA(0, 0, At, B0); PG8_MMA(0, 1, At, B1); PG8_BAR; PG8_SCHED;
;             PG8_LDA(At, 0, 1); PG8_STAGE(PG8_SB(0, 0), b2, voffB); PG8_STAGE(PG8_SB(0, 1), b2 + hB, voffB); PG8_STAGE(PG8_SA(0, 0), a2, voffA);
;             PG8_WAIT_V(8); PG8_WAIT_L(0); PG8_BAR; PG8_MMA(1, 0, At, B0); PG8_MMA(1, 1, At, B1); PG8_BAR; PG8_SCHED;
;     ...
;         for (int a = 0; a < 2; ++a)
; #pragma unroll
;             for (int b = 0; b < 2; ++b)
; #pragma unroll
;                 for (int m = 0; m < 4; ++m)
; #pragma unroll
;                     for (int n = 0; n < 2; ++n) acc[a][b][m][n] = (f32x4){0.f, 0.f, 0.f, 0.f};
.LBB0_913:
	s_add_u32 s8, s4, s12
	s_addc_u32 s9, s5, 0
	s_add_u32 s34, s6, 0x8000
	v_mov_b32_e32 v2, 0
	s_waitcnt vmcnt(0)
	v_lshl_add_u64 v[130:131], s[8:9], 0, v[0:1]
	s_addc_u32 s35, s7, 0
	s_mov_b32 s46, -2
	s_mov_b64 s[6:7], 0
	s_waitcnt lgkmcnt(0)
	v_mov_b32_e32 v3, v2
	v_mov_b32_e32 v4, v2
	v_mov_b32_e32 v5, v2
	v_mov_b32_e32 v6, v2
	v_mov_b32_e32 v7, v2
	v_mov_b32_e32 v8, v2
	v_mov_b32_e32 v9, v2
	v_mov_b32_e32 v10, v2
	v_mov_b32_e32 v11, v2
	v_mov_b32_e32 v12, v2
	v_mov_b32_e32 v13, v2
	v_mov_b32_e32 v14, v2
	v_mov_b32_e32 v15, v2
	v_mov_b32_e32 v16, v2
	v_mov_b32_e32 v17, v2
	v_mov_b32_e32 v18, v2
	v_mov_b32_e32 v19, v2
	v_mov_b32_e32 v20, v2
	v_mov_b32_e32 v21, v2
	v_mov_b32_e32 v22, v2
	v_mov_b32_e32 v23, v2
	v_mov_b32_e32 v24, v2
	v_mov_b32_e32 v25, v2
	v_mov_b32_e32 v26, v2
	v_mov_b32_e32 v27, v2
	v_mov_b32_e32 v28, v2
	v_mov_b32_e32 v29, v2
	v_mov_b32_e32 v30, v2
	v_mov_b32_e32 v31, v2
	v_mov_b32_e32 v32, v2
	v_mov_b32_e32 v33, v2
	v_mov_b32_e32 v66, v2
	v_mov_b32_e32 v67, v2
	v_mov_b32_e32 v68, v2
	v_mov_b32_e32 v69, v2
	v_mov_b32_e32 v70, v2
	v_mov_b32_e32 v71, v2
	v_mov_b32_e32 v72, v2
	v_mov_b32_e32 v73, v2
	v_mov_b32_e32 v74, v2
	v_mov_b32_e32 v75, v2
	v_mov_b32_e32 v76, v2
	v_mov_b32_e32 v77, v2
	v_mov_b32_e32 v78, v2
	v_mov_b32_e32 v79, v2
	v_mov_b32_e32 v80, v2
	v_mov_b32_e32 v81, v2
	v_mov_b32_e32 v82, v2
	v_mov_b32_e32 v83, v2
	v_mov_b32_e32 v84, v2
	v_mov_b32_e32 v85, v2
	v_mov_b32_e32 v86, v2
	v_mov_b32_e32 v87, v2
	v_mov_b32_e32 v88, v2
	v_mov_b32_e32 v89, v2
	v_mov_b32_e32 v90, v2
	v_mov_b32_e32 v91, v2
	v_mov_b32_e32 v92, v2
	v_mov_b32_e32 v93, v2
	v_mov_b32_e32 v94, v2
	v_mov_b32_e32 v95, v2
	v_mov_b32_e32 v96, v2
	v_mov_b32_e32 v97, v2
	v_mov_b32_e32 v34, v2
	v_mov_b32_e32 v35, v2
	v_mov_b32_e32 v36, v2
	v_mov_b32_e32 v37, v2
	v_mov_b32_e32 v38, v2
	v_mov_b32_e32 v39, v2
	v_mov_b32_e32 v40, v2
	v_mov_b32_e32 v41, v2
	v_mov_b32_e32 v42, v2
	v_mov_b32_e32 v43, v2
	v_mov_b32_e32 v44, v2
	v_mov_b32_e32 v45, v2
	v_mov_b32_e32 v46, v2
	v_mov_b32_e32 v47, v2
	v_mov_b32_e32 v48, v2
	v_mov_b32_e32 v49, v2
	v_mov_b32_e32 v50, v2
	v_mov_b32_e32 v51, v2
	v_mov_b32_e32 v52, v2
	v_mov_b32_e32 v53, v2
	v_mov_b32_e32 v54, v2
	v_mov_b32_e32 v55, v2
	v_mov_b32_e32 v56, v2
	v_mov_b32_e32 v57, v2
	v_mov_b32_e32 v58, v2
	v_mov_b32_e32 v59, v2
	v_mov_b32_e32 v60, v2
	v_mov_b32_e32 v61, v2
	v_mov_b32_e32 v62, v2
	v_mov_b32_e32 v63, v2
	v_mov_b32_e32 v64, v2
	v_mov_b32_e32 v65, v2
	v_mov_b32_e32 v98, v2
	v_mov_b32_e32 v99, v2
	v_mov_b32_e32 v100, v2
	v_mov_b32_e32 v101, v2
	v_mov_b32_e32 v102, v2
	v_mov_b32_e32 v103, v2
	v_mov_b32_e32 v104, v2
	v_mov_b32_e32 v105, v2
	v_mov_b32_e32 v106, v2
	v_mov_b32_e32 v107, v2
	v_mov_b32_e32 v108, v2
	v_mov_b32_e32 v109, v2
	v_mov_b32_e32 v110, v2
	v_mov_b32_e32 v111, v2
	v_mov_b32_e32 v112, v2
	v_mov_b32_e32 v113, v2
	v_mov_b32_e32 v114, v2
	v_mov_b32_e32 v115, v2
	v_mov_b32_e32 v116, v2
	v_mov_b32_e32 v117, v2
	v_mov_b32_e32 v118, v2
	v_mov_b32_e32 v119, v2
	v_mov_b32_e32 v120, v2
	v_mov_b32_e32 v121, v2
	v_mov_b32_e32 v122, v2
	v_mov_b32_e32 v123, v2
	v_mov_b32_e32 v124, v2
	v_mov_b32_e32 v125, v2
	v_mov_b32_e32 v126, v2
	v_mov_b32_e32 v127, v2
	v_mov_b32_e32 v128, v2
	v_mov_b32_e32 v129, v2
	s_mov_b64 s[42:43], 0xb0000
	v_xor_b32_e32 v193, 16, v192
	v_readlane_b32 s98, v254, 1
	s_nop 3
	s_cmp_ge_u32 s98, 4
	s_cbranch_scc0 .Lprio_skip_3
	s_setprio 1
.Lprio_skip_3:
.LBB0_914:
	v_add_u32_e32 v144, s14, v191
	v_add_u32_e32 v148, s27, v191
	s_add_u32 s8, s4, s6
	ds_read_b128 v[132:135], v144
	v_xor_b32_e32 v154, 16, v144
	ds_read_b128 v[136:139], v154
	ds_read_b128 v[140:143], v144 offset:2048
	ds_read_b128 v[144:147], v154 offset:2048
	ds_read_b128 v[156:159], v148
	v_xor_b32_e32 v154, 16, v148
	ds_read_b128 v[160:163], v154
	ds_read_b128 v[164:167], v148 offset:2048
	ds_read_b128 v[168:171], v154 offset:2048
	s_addc_u32 s9, s5, s7
	s_add_u32 s8, s8, 0x8000
	s_addc_u32 s9, s9, 0
	s_add_u32 s10, s34, s6
	s_addc_u32 s11, s35, s7
	s_cmp_eq_u32 s6, 0xa8000
	s_cselect_b32 s9, s69, s9
	s_cselect_b32 s8, s68, s8
	s_cselect_b32 s11, s91, s11
	s_cselect_b32 s10, s90, s10
	v_lshl_add_u64 v[148:149], v[130:131], 0, s[6:7]
	v_lshl_add_u64 v[150:151], v[148:149], 0, s[76:77]
	s_add_i32 m0, s41, 0xc000
	ds_read_b128 v[172:175], v192
	ds_read_b128 v[176:179], v193
	ds_read_b128 v[180:183], v192 offset:2048
	ds_read_b128 v[184:187], v193 offset:2048
	ds_read_b128 v[212:215], v192 offset:4096
	ds_read_b128 v[216:219], v193 offset:4096
	ds_read_b128 v[220:223], v192 offset:6144
	ds_read_b128 v[224:227], v193 offset:6144
	global_load_lds_dwordx4 v[150:151], off
	v_lshl_add_u64 v[148:149], v[148:149], 0, s[78:79]
	s_add_i32 m0, s41, 0xe000
	s_nop 0
	global_load_lds_dwordx4 v[148:149], off
	s_waitcnt vmcnt(8)
	s_waitcnt lgkmcnt(0)
	s_barrier
; #define PG8_STAGE(bufoff, gbase, unused) do { _Pragma("unroll") for (int _i = 0; _i < 2; ++_i) \
;         __builtin_amdgcn_global_load_lds((const unsigned*)((const char*)(gbase) + voff + _i * 8192), (LAS unsigned*)(lds + (bufoff) + ldsw + _i * 8192), 16, 0, 0); } while (0)
; #define PG8_LDA(dst, b, h) do { _Pragma("unroll") for (int m = 0; m < 4; ++m) _Pragma("unroll") for (int k = 0; k < 2; ++k) dst[m][k] = *(const LAS bf16x8*)(lds + PG8_SA(b, h) + aoff + m * 2048 + (FP8 ? k * 16 : k * 1024)); } while (0)
; #define PG8_LDB(dst, b, h) do { _Pragma("unroll") for (int n = 0; n < 2; ++n) _Pragma("unroll") for (int k = 0; k < 2; ++k) dst[n][k] = *(const LAS bf16x8*)(lds + PG8_SB(b, h) + boff + n * 2048 + (FP8 ? k * 16 : k * 1024)); } while (0)
; #define PG8_WAIT_V(n) asm volatile("s_waitcnt vmcnt(" #n ")" ::: "memory")
; #define PG8_WAIT_L(n) asm volatile("s_waitcnt lgkmcnt(" #n ")" ::: "memory")
; #define PG8_BAR __builtin_amdgcn_s_barrier()
; #define PG8_SCHED __builtin_amdgcn_sched_barrier(0)
; template <class Epi, class Sched, bool ALIGN_EPI, bool SP2, int MODE  >
; __device__ __forceinline__ void gemm_phase(LAS unsigned char* lds, const Gemm g, const Sched S, const Epi E, unsigned long long& probe_acc, int epi_id, int wv) {
;     ...
;             PG8_LDB(B0, 0, 0); PG8_LDB(B1, 0, 1); PG8_SCHED; PG8_LDA(At, 0, 0); PG8_STAGE(PG8_SA(1, 1), a1 + hA, voffA);
;             PG8_WAIT_V(8); PG8_WAIT_L(0); PG8_BAR; PG8_MMA(0, 0, At, B0); PG8_MMA(0, 1, At, B1); PG8_BAR; PG8_SCHED;
;             PG8_LDA(At, 0, 1); PG8_STAGE(PG8_SB(0, 0), b2, voffB); PG8_STAGE(PG8_SB(0, 1), b2 + hB, voffB); PG8_STAGE(PG8_SA(0, 0), a2, voffA);
;             PG8_WAIT_V(8); PG8_WAIT_L(0); PG8_BAR; PG8_MMA(1, 0, At, B0); PG8_MMA(1, 1, At, B1); PG8_BAR; PG8_SCHED;
;             PG8_LDB(B0, 1, 0); PG8_LDB(B1, 1, 1); PG8_SCHED; PG8_LDA(At, 1, 0); PG8_STAGE(PG8_SA(0, 1), a2 + hA, voffA);
;             PG8_WAIT_V(8); PG8_WAIT_L(0); PG8_BAR; PG8_MMA(0, 0, At, B0); PG8_MMA(0, 1, At, B1); PG8_BAR; PG8_SCHED;
	v_mfma_scale_f32_16x16x128_f8f6f4 v[126:129], v[132:139], v[172:179], v[126:129], v208, v208 op_sel_hi:[0,0,0]
	v_mfma_scale_f32_16x16x128_f8f6f4 v[122:125], v[140:147], v[172:179], v[122:125], v208, v208 op_sel_hi:[0,0,0]
	v_mfma_scale_f32_16x16x128_f8f6f4 v[118:121], v[132:139], v[180:187], v[118:121], v208, v208 op_sel_hi:[0,0,0]
	v_mfma_scale_f32_16x16x128_f8f6f4 v[114:117], v[140:147], v[180:187], v[114:117], v208, v208 op_sel_hi:[0,0,0]
	v_mfma_scale_f32_16x16x128_f8f6f4 v[110:113], v[132:139], v[212:219], v[110:113], v208, v208 op_sel_hi:[0,0,0]
	v_mfma_scale_f32_16x16x128_f8f6f4 v[106:109], v[140:147], v[212:219], v[106:109], v208, v208 op_sel_hi:[0,0,0]
	v_mfma_scale_f32_16x16x128_f8f6f4 v[102:105], v[132:139], v[220:227], v[102:105], v208, v208 op_sel_hi:[0,0,0]
	v_mfma_scale_f32_16x16x128_f8f6f4 v[98:101], v[140:147], v[220:227], v[98:101], v208, v208 op_sel_hi:[0,0,0]
	v_mfma_scale_f32_16x16x128_f8f6f4 v[148:151], v[156:163], v[172:179], v[62:65], v208, v208 op_sel_hi:[0,0,0]
	v_mfma_scale_f32_16x16x128_f8f6f4 v[172:175], v[164:171], v[172:179], v[58:61], v208, v208 op_sel_hi:[0,0,0]
	v_mfma_scale_f32_16x16x128_f8f6f4 v[176:179], v[156:163], v[180:187], v[54:57], v208, v208 op_sel_hi:[0,0,0]
	v_mfma_scale_f32_16x16x128_f8f6f4 v[180:183], v[164:171], v[180:187], v[50:53], v208, v208 op_sel_hi:[0,0,0]
	v_mfma_scale_f32_16x16x128_f8f6f4 v[184:187], v[156:163], v[212:219], v[46:49], v208, v208 op_sel_hi:[0,0,0]
	v_mfma_scale_f32_16x16x128_f8f6f4 v[194:197], v[164:171], v[212:219], v[42:45], v208, v208 op_sel_hi:[0,0,0]
	v_mfma_scale_f32_16x16x128_f8f6f4 v[200:203], v[156:163], v[220:227], v[38:41], v208, v208 op_sel_hi:[0,0,0]
	v_mfma_scale_f32_16x16x128_f8f6f4 v[212:215], v[164:171], v[220:227], v[34:37], v208, v208 op_sel_hi:[0,0,0]
	s_barrier
	s_mov_b32 m0, s15
	v_lshl_add_u64 v[152:153], s[10:11], 0, v[0:1]
	s_nop 2
	ds_read_b128 v[34:37], v192 offset:16384
	ds_read_b128 v[38:41], v193 offset:16384
	ds_read_b128 v[42:45], v192 offset:18432
	ds_read_b128 v[46:49], v193 offset:18432
	ds_read_b128 v[50:53], v192 offset:20480
	ds_read_b128 v[54:57], v193 offset:20480
	ds_read_b128 v[58:61], v192 offset:22528
	ds_read_b128 v[62:65], v193 offset:22528
	global_load_lds_dwordx4 v[152:153], off
	v_lshl_add_u64 v[188:189], v[152:153], 0, s[70:71]
	s_mov_b32 m0, s26
	s_nop 0
	global_load_lds_dwordx4 v[188:189], off
	v_lshl_add_u64 v[188:189], v[152:153], 0, s[42:43]
	s_mov_b32 m0, s39
	s_nop 0
	global_load_lds_dwordx4 v[188:189], off
	v_lshl_add_u64 v[188:189], v[152:153], 0, s[48:49]
	s_mov_b32 m0, s40
	s_nop 0
	global_load_lds_dwordx4 v[188:189], off
	v_lshl_add_u64 v[188:189], s[8:9], 0, v[0:1]
	s_mov_b32 m0, s41
	v_lshl_add_u64 v[204:205], v[188:189], 0, s[70:71]
	global_load_lds_dwordx4 v[188:189], off
	s_mov_b32 m0, s84
	s_nop 0
	global_load_lds_dwordx4 v[204:205], off
	s_waitcnt vmcnt(8)
	s_waitcnt lgkmcnt(0)
	s_barrier
	v_mfma_scale_f32_16x16x128_f8f6f4 v[94:97], v[132:139], v[34:41], v[94:97], v208, v208 op_sel_hi:[0,0,0]
	v_mfma_scale_f32_16x16x128_f8f6f4 v[90:93], v[140:147], v[34:41], v[90:93], v208, v208 op_sel_hi:[0,0,0]
	v_mfma_scale_f32_16x16x128_f8f6f4 v[86:89], v[132:139], v[42:49], v[86:89], v208, v208 op_sel_hi:[0,0,0]
	v_mfma_scale_f32_16x16x128_f8f6f4 v[82:85], v[140:147], v[42:49], v[82:85], v208, v208 op_sel_hi:[0,0,0]
	v_mfma_scale_f32_16x16x128_f8f6f4 v[78:81], v[132:139], v[50:57], v[78:81], v208, v208 op_sel_hi:[0,0,0]
	v_mfma_scale_f32_16x16x128_f8f6f4 v[74:77], v[140:147], v[50:57], v[74:77], v208, v208 op_sel_hi:[0,0,0]
	v_mfma_scale_f32_16x16x128_f8f6f4 v[216:219], v[132:139], v[58:65], v[70:73], v208, v208 op_sel_hi:[0,0,0]
	v_mfma_scale_f32_16x16x128_f8f6f4 v[220:223], v[140:147], v[58:65], v[66:69], v208, v208 op_sel_hi:[0,0,0]
	v_mfma_scale_f32_16x16x128_f8f6f4 v[224:227], v[156:163], v[34:41], v[30:33], v208, v208 op_sel_hi:[0,0,0]
	v_mfma_scale_f32_16x16x128_f8f6f4 v[228:231], v[164:171], v[34:41], v[26:29], v208, v208 op_sel_hi:[0,0,0]
	v_mfma_scale_f32_16x16x128_f8f6f4 v[232:235], v[156:163], v[42:49], v[22:25], v208, v208 op_sel_hi:[0,0,0]
	v_mfma_scale_f32_16x16x128_f8f6f4 v[236:239], v[164:171], v[42:49], v[18:21], v208, v208 op_sel_hi:[0,0,0]
	v_mfma_scale_f32_16x16x128_f8f6f4 v[240:243], v[156:163], v[50:57], v[14:17], v208, v208 op_sel_hi:[0,0,0]
	v_mfma_scale_f32_16x16x128_f8f6f4 v[244:247], v[164:171], v[50:57], v[10:13], v208, v208 op_sel_hi:[0,0,0]
	v_mfma_scale_f32_16x16x128_f8f6f4 v[248:251], v[156:163], v[58:65], v[6:9], v208, v208 op_sel_hi:[0,0,0]
	v_mfma_scale_f32_16x16x128_f8f6f4 v[204:207], v[164:171], v[58:65], v[2:5], v208, v208 op_sel_hi:[0,0,0]
	s_barrier
	s_nop 1
	v_add_u32_e32 v14, s89, v191
	v_add_u32_e32 v18, s29, v191
	s_nop 0
	ds_read_b128 v[2:5], v14
	v_xor_b32_e32 v154, 16, v14
	ds_read_b128 v[6:9], v154
	ds_read_b128 v[10:13], v14 offset:2048
	ds_read_b128 v[14:17], v154 offset:2048
	ds_read_b128 v[132:135], v18
	v_xor_b32_e32 v154, 16, v18
	ds_read_b128 v[136:139], v154
	ds_read_b128 v[140:143], v18 offset:2048
	ds_read_b128 v[144:147], v154 offset:2048
	s_add_u32 s8, s8, s12
	s_addc_u32 s9, s9, 0
	s_mov_b32 m0, s85
	v_lshl_add_u64 v[42:43], s[8:9], 0, v[0:1]
	ds_read_b128 v[18:21], v192 offset:32768
	ds_read_b128 v[22:25], v193 offset:32768
	ds_read_b128 v[26:29], v192 offset:34816
	ds_read_b128 v[30:33], v193 offset:34816
	ds_read_b128 v[34:37], v192 offset:36864
	ds_read_b128 v[38:41], v193 offset:36864
	ds_read_b128 v[66:69], v192 offset:38912
	ds_read_b128 v[70:73], v193 offset:38912
	global_load_lds_dwordx4 v[42:43], off
	v_lshl_add_u64 v[42:43], v[42:43], 0, s[70:71]
	s_mov_b32 m0, s88
	s_nop 0
	global_load_lds_dwordx4 v[42:43], off
	s_waitcnt vmcnt(8)
	s_waitcnt lgkmcnt(0)
	s_barrier
; #define PG8_STAGE(bufoff, gbase, unused) do { _Pragma("unroll") for (int _i = 0; _i < 2; ++_i) \
;         __builtin_amdgcn_global_load_lds((const unsigned*)((const char*)(gbase) + voff + _i * 8192), (LAS unsigned*)(lds + (bufoff) + ldsw + _i * 8192), 16, 0, 0); } while (0)
; #define PG8_LDA(dst, b, h) do { _Pragma("unroll") for (int m = 0; m < 4; ++m) _Pragma("unroll") for (int k = 0; k < 2; ++k) dst[m][k] = *(const LAS bf16x8*)(lds + PG8_SA(b, h) + aoff + m * 2048 + (FP8 ? k * 16 : k * 1024)); } while (0)
; #define PG8_WAIT_V(n) asm volatile("s_waitcnt vmcnt(" #n ")" ::: "memory")
; #define PG8_WAIT_L(n) asm volatile("s_waitcnt lgkmcnt(" #n ")" ::: "memory")
; #define PG8_BAR __builtin_amdgcn_s_barrier()
; #define PG8_SCHED __builtin_amdgcn_sched_barrier(0)
; template <class Epi, class Sched, bool ALIGN_EPI, bool SP2, int MODE  >
; __device__ __forceinline__ void gemm_phase(LAS unsigned char* lds, const Gemm g, const Sched S, const Epi E, unsigned long long& probe_acc, int epi_id, int wv) {
;     ...
;             PG8_WAIT_V(8); PG8_WAIT_L(0); PG8_BAR; PG8_MMA(0, 0, At, B0); PG8_MMA(0, 1, At, B1); PG8_BAR; PG8_SCHED;
;             PG8_LDA(At, 1, 1); PG8_STAGE(PG8_SB(1, 0), b3, voffB); PG8_STAGE(PG8_SB(1, 1), b3 + hB, voffB); PG8_STAGE(PG8_SA(1, 0), a3, voffA);
;             PG8_WAIT_V(8); PG8_WAIT_L(0); PG8_BAR; PG8_MMA(1, 0, At, B0); PG8_MMA(1, 1, At, B1); PG8_BAR; PG8_SCHED;
;     ...
;         if constexpr (ALIGN_EPI) { if (wr == 0) PG8_BAR; }
	v_mfma_scale_f32_16x16x128_f8f6f4 v[126:129], v[2:9], v[18:25], v[126:129], v208, v208 op_sel_hi:[0,0,0]
	v_mfma_scale_f32_16x16x128_f8f6f4 v[122:125], v[10:17], v[18:25], v[122:125], v208, v208 op_sel_hi:[0,0,0]
	v_mfma_scale_f32_16x16x128_f8f6f4 v[118:121], v[2:9], v[26:33], v[118:121], v208, v208 op_sel_hi:[0,0,0]
	v_mfma_scale_f32_16x16x128_f8f6f4 v[114:117], v[10:17], v[26:33], v[114:117], v208, v208 op_sel_hi:[0,0,0]
	v_mfma_scale_f32_16x16x128_f8f6f4 v[110:113], v[2:9], v[34:41], v[110:113], v208, v208 op_sel_hi:[0,0,0]
	v_mfma_scale_f32_16x16x128_f8f6f4 v[106:109], v[10:17], v[34:41], v[106:109], v208, v208 op_sel_hi:[0,0,0]
	v_mfma_scale_f32_16x16x128_f8f6f4 v[102:105], v[2:9], v[66:73], v[102:105], v208, v208 op_sel_hi:[0,0,0]
	v_mfma_scale_f32_16x16x128_f8f6f4 v[98:101], v[10:17], v[66:73], v[98:101], v208, v208 op_sel_hi:[0,0,0]
	v_mfma_scale_f32_16x16x128_f8f6f4 v[62:65], v[132:139], v[18:25], v[148:151], v208, v208 op_sel_hi:[0,0,0]
	v_mfma_scale_f32_16x16x128_f8f6f4 v[58:61], v[140:147], v[18:25], v[172:175], v208, v208 op_sel_hi:[0,0,0]
	v_mfma_scale_f32_16x16x128_f8f6f4 v[54:57], v[132:139], v[26:33], v[176:179], v208, v208 op_sel_hi:[0,0,0]
	v_mfma_scale_f32_16x16x128_f8f6f4 v[50:53], v[140:147], v[26:33], v[180:183], v208, v208 op_sel_hi:[0,0,0]
	v_mfma_scale_f32_16x16x128_f8f6f4 v[46:49], v[132:139], v[34:41], v[184:187], v208, v208 op_sel_hi:[0,0,0]
	v_mfma_scale_f32_16x16x128_f8f6f4 v[42:45], v[140:147], v[34:41], v[194:197], v208, v208 op_sel_hi:[0,0,0]
	v_mfma_scale_f32_16x16x128_f8f6f4 v[38:41], v[132:139], v[66:73], v[200:203], v208, v208 op_sel_hi:[0,0,0]
	v_mfma_scale_f32_16x16x128_f8f6f4 v[34:37], v[140:147], v[66:73], v[212:215], v208, v208 op_sel_hi:[0,0,0]
	s_barrier
	s_mov_b32 m0, s92
	v_lshl_add_u64 v[26:27], v[152:153], 0, s[76:77]
	ds_read_b128 v[18:21], v192 offset:49152
	ds_read_b128 v[22:25], v193 offset:49152
	ds_read_b128 v[156:159], v192 offset:51200
	ds_read_b128 v[160:163], v193 offset:51200
	ds_read_b128 v[164:167], v192 offset:53248
	ds_read_b128 v[168:171], v193 offset:53248
	ds_read_b128 v[172:175], v192 offset:55296
	ds_read_b128 v[176:179], v193 offset:55296
	global_load_lds_dwordx4 v[26:27], off
	v_lshl_add_u64 v[26:27], v[152:153], 0, s[78:79]
	s_mov_b32 m0, s93
	s_nop 0
	global_load_lds_dwordx4 v[26:27], off
	v_lshl_add_u64 v[26:27], v[152:153], 0, s[44:45]
	s_mov_b32 m0, s0
	s_nop 0
	global_load_lds_dwordx4 v[26:27], off
	v_lshl_add_u64 v[26:27], v[152:153], 0, s[56:57]
	s_mov_b32 m0, s1
	s_nop 0
	global_load_lds_dwordx4 v[26:27], off
	v_lshl_add_u64 v[26:27], v[188:189], 0, s[76:77]
	s_mov_b32 m0, s94
	s_nop 0
	global_load_lds_dwordx4 v[26:27], off
	v_lshl_add_u64 v[26:27], v[188:189], 0, s[78:79]
	s_mov_b32 m0, s95
	s_nop 0
	global_load_lds_dwordx4 v[26:27], off
	s_waitcnt vmcnt(8)
	s_waitcnt lgkmcnt(0)
	s_barrier
	v_mfma_scale_f32_16x16x128_f8f6f4 v[94:97], v[2:9], v[18:25], v[94:97], v208, v208 op_sel_hi:[0,0,0]
	v_mfma_scale_f32_16x16x128_f8f6f4 v[90:93], v[10:17], v[18:25], v[90:93], v208, v208 op_sel_hi:[0,0,0]
	v_mfma_scale_f32_16x16x128_f8f6f4 v[86:89], v[2:9], v[156:163], v[86:89], v208, v208 op_sel_hi:[0,0,0]
	v_mfma_scale_f32_16x16x128_f8f6f4 v[82:85], v[10:17], v[156:163], v[82:85], v208, v208 op_sel_hi:[0,0,0]
	v_mfma_scale_f32_16x16x128_f8f6f4 v[78:81], v[2:9], v[164:171], v[78:81], v208, v208 op_sel_hi:[0,0,0]
	v_mfma_scale_f32_16x16x128_f8f6f4 v[74:77], v[10:17], v[164:171], v[74:77], v208, v208 op_sel_hi:[0,0,0]
	v_mfma_scale_f32_16x16x128_f8f6f4 v[70:73], v[2:9], v[172:179], v[216:219], v208, v208 op_sel_hi:[0,0,0]
	v_mfma_scale_f32_16x16x128_f8f6f4 v[66:69], v[10:17], v[172:179], v[220:223], v208, v208 op_sel_hi:[0,0,0]
	v_mfma_scale_f32_16x16x128_f8f6f4 v[30:33], v[132:139], v[18:25], v[224:227], v208, v208 op_sel_hi:[0,0,0]
	v_mfma_scale_f32_16x16x128_f8f6f4 v[26:29], v[140:147], v[18:25], v[228:231], v208, v208 op_sel_hi:[0,0,0]
	v_mfma_scale_f32_16x16x128_f8f6f4 v[22:25], v[132:139], v[156:163], v[232:235], v208, v208 op_sel_hi:[0,0,0]
	v_mfma_scale_f32_16x16x128_f8f6f4 v[18:21], v[140:147], v[156:163], v[236:239], v208, v208 op_sel_hi:[0,0,0]
	v_mfma_scale_f32_16x16x128_f8f6f4 v[14:17], v[132:139], v[164:171], v[240:243], v208, v208 op_sel_hi:[0,0,0]
	v_mfma_scale_f32_16x16x128_f8f6f4 v[10:13], v[140:147], v[164:171], v[244:247], v208, v208 op_sel_hi:[0,0,0]
	v_mfma_scale_f32_16x16x128_f8f6f4 v[6:9], v[132:139], v[172:179], v[248:251], v208, v208 op_sel_hi:[0,0,0]
	v_mfma_scale_f32_16x16x128_f8f6f4 v[2:5], v[140:147], v[172:179], v[204:207], v208, v208 op_sel_hi:[0,0,0]
	s_barrier
	s_add_i32 s46, s46, 2
	s_add_u32 s6, s6, 0x8000
	s_addc_u32 s7, s7, 0
	s_cmp_gt_u32 s46, 41
	s_cbranch_scc0 .LBB0_914
	v_readlane_b32 s4, v255, 1
	v_readlane_b32 s5, v255, 2
	s_and_b64 vcc, exec, s[4:5]
	s_cbranch_vccz .LBB0_917
	s_barrier

; #define PG8_STAGE(bufoff, gbase, unused) do { _Pragma("unroll") for (int _i = 0; _i < 2; ++_i) \
;         __builtin_amdgcn_global_load_lds((const unsigned*)((const char*)(gbase) + voff + _i * 8192), (LAS unsigned*)(lds + (bufoff) + ldsw + _i * 8192), 16, 0, 0); } while (0)
; #define PG8_LDA(dst, b, h) do { _Pragma("unroll") for (int m = 0; m < 4; ++m) _Pragma("unroll") for (int k = 0; k < 2; ++k) dst[m][k] = *(const LAS bf16x8*)(lds + PG8_SA(b, h) + aoff + m * 2048 + (FP8 ? k * 16 : k * 1024)); } while (0)
; #define PG8_LDB(dst, b, h) do { _Pragma("unroll") for (int n = 0; n < 2; ++n) _Pragma("unroll") for (int k = 0; k < 2; ++k) dst[n][k] = *(const LAS bf16x8*)(lds + PG8_SB(b, h) + boff + n * 2048 + (FP8 ? k * 16 : k * 1024)); } while (0)
; #define PG8_WAIT_V(n) asm volatile("s_waitcnt vmcnt(" #n ")" ::: "memory")
; #define PG8_WAIT_L(n) asm volatile("s_waitcnt lgkmcnt(" #n ")" ::: "memory")
; #define PG8_BAR __builtin_amdgcn_s_barrier()
; #define PG8_SCHED __builtin_amdgcn_sched_barrier(0)
; template <class Epi, class Sched, bool ALIGN_EPI, bool SP2, int MODE  >
; __device__ __forceinline__ void gemm_phase(LAS unsigned char* lds, const Gemm g, const Sched S, const Epi E, unsigned long long& probe_acc, int epi_id, int wv) {
;     ...
;         const char* nA = has_next ? (const char*)g.A + (size_t)nxt.pm * tA + (g.gt ? (size_t)(nxt.pn / g.gt) * gK2 : 0) : cA; const char* nB = has_next ? (const char*)g.Bt + (size_t)nxt.pn * tB : cB;
;         for (int t = 0; t < nt; t += 2) {
;             const bool last = (t == nt - 2);
;             const char* a1 = cA + (size_t)(t + 1) * kstep;
;             const char* a2 = last ? nA : cA + (size_t)(t + 2) * kstep; const char* b2 = last ? nB : cB + (size_t)(t + 2) * kstep;
;             const char* a3 = a2 + kstep; const char* b3 = b2 + kstep;
;             if constexpr (SP2) {
;             PG8_LDB(B0, 0, 0); PG8_LDB(B1, 0, 1); PG8_SCHED; PG8_LDA(At, 0, 0); PG8_STAGE(PG8_SA(1, 1), a1 + hA, voffA);
;             PG8_WAIT_V(8); PG8_WAIT_L(0); PG8_BAR; PG8_MMA(0, 0, At, B0); PG8_MMA(0, 1, At, B1); PG8_BAR; PG8_SCHED;
;             PG8_LDA(At, 0, 1); PG8_STAGE(PG8_SB(0, 0), b2, voffB); PG8_STAGE(PG8_SB(0, 1), b2 + hB, voffB); PG8_STAGE(PG8_SA(0, 0), a2, voffA);
;             PG8_WAIT_V(8); PG8_WAIT_L(0); PG8_BAR; PG8_MMA(1, 0, At, B0); PG8_MMA(1, 1, At, B1); PG8_BAR; PG8_SCHED;
.LBB0_1153:
	s_add_u32 s8, s4, s40
	s_addc_u32 s9, s5, 0
	s_add_u32 s10, s6, 0x8000
	s_waitcnt vmcnt(0)
	v_lshl_add_u64 v[130:131], s[8:9], 0, v[0:1]
	s_addc_u32 s11, s7, 0
	s_mov_b32 s34, -2
	s_mov_b64 s[6:7], 0
	s_waitcnt lgkmcnt(0)
	s_mov_b64 s[42:43], 0xb0000
	v_add_u32_e32 v144, s90, v200
	v_add_u32_e32 v160, s15, v200
	s_add_u32 s8, s4, s6
	ds_read_b128 v[132:135], v144
	ds_read_b128 v[136:139], v144 offset:1024
	ds_read_b128 v[140:143], v144 offset:2048
	ds_read_b128 v[144:147], v144 offset:3072
	ds_read_b128 v[148:151], v160
	ds_read_b128 v[152:155], v160 offset:1024
	ds_read_b128 v[156:159], v160 offset:2048
	ds_read_b128 v[164:167], v160 offset:3072
	s_addc_u32 s9, s5, s7
	s_add_u32 s8, s8, 0x8000
	s_addc_u32 s9, s9, 0
	s_add_u32 s28, s10, s6
	s_addc_u32 s29, s11, s7
	s_cmp_eq_u32 s6, 0xa8000
	s_cselect_b32 s9, s67, s9
	s_cselect_b32 s8, s66, s8
	s_cselect_b32 vcc_hi, s87, s29
	s_cselect_b32 vcc_lo, s86, s28
	v_lshl_add_u64 v[160:161], v[130:131], 0, s[6:7]
	v_lshl_add_u64 v[196:197], v[160:161], 0, s[76:77]
	s_add_i32 m0, s0, 0xc000
	ds_read_b128 v[168:171], v201
	ds_read_b128 v[172:175], v201 offset:1024
	ds_read_b128 v[176:179], v201 offset:2048
	ds_read_b128 v[180:183], v201 offset:3072
	ds_read_b128 v[184:187], v201 offset:4096
	ds_read_b128 v[188:191], v201 offset:5120
	ds_read_b128 v[192:195], v201 offset:6144
	ds_read_b128 v[212:215], v201 offset:7168
	global_load_lds_dwordx4 v[196:197], off
	v_lshl_add_u64 v[160:161], v[160:161], 0, s[78:79]
	s_add_i32 m0, s0, 0xe000
	s_nop 0
	global_load_lds_dwordx4 v[160:161], off
	s_waitcnt vmcnt(8)
	s_waitcnt lgkmcnt(0)
	s_barrier
	v_mfma_i32_16x16x64_i8 v[122:125], v[132:135], v[168:171], 0
	v_mfma_i32_16x16x64_i8 v[126:129], v[140:143], v[168:171], 0
	v_mfma_i32_16x16x64_i8 v[114:117], v[132:135], v[176:179], 0
	v_mfma_i32_16x16x64_i8 v[118:121], v[140:143], v[176:179], 0
	v_mfma_i32_16x16x64_i8 v[106:109], v[132:135], v[184:187], 0
	v_mfma_i32_16x16x64_i8 v[110:113], v[140:143], v[184:187], 0
	v_mfma_i32_16x16x64_i8 v[98:101], v[132:135], v[192:195], 0
	v_mfma_i32_16x16x64_i8 v[102:105], v[140:143], v[192:195], 0
	v_mfma_i32_16x16x64_i8 v[122:125], v[136:139], v[172:175], v[122:125]
	v_mfma_i32_16x16x64_i8 v[126:129], v[144:147], v[172:175], v[126:129]
	v_mfma_i32_16x16x64_i8 v[114:117], v[136:139], v[180:183], v[114:117]
	v_mfma_i32_16x16x64_i8 v[118:121], v[144:147], v[180:183], v[118:121]
	v_mfma_i32_16x16x64_i8 v[106:109], v[136:139], v[188:191], v[106:109]
	v_mfma_i32_16x16x64_i8 v[110:113], v[144:147], v[188:191], v[110:113]
	v_mfma_i32_16x16x64_i8 v[98:101], v[136:139], v[212:215], v[98:101]
	v_mfma_i32_16x16x64_i8 v[102:105], v[144:147], v[212:215], v[102:105]
	v_mfma_i32_16x16x64_i8 v[58:61], v[148:151], v[168:171], 0
	v_mfma_i32_16x16x64_i8 v[62:65], v[156:159], v[168:171], 0
	v_mfma_i32_16x16x64_i8 v[50:53], v[148:151], v[176:179], 0
	v_mfma_i32_16x16x64_i8 v[54:57], v[156:159], v[176:179], 0
	v_mfma_i32_16x16x64_i8 v[42:45], v[148:151], v[184:187], 0
	v_mfma_i32_16x16x64_i8 v[46:49], v[156:159], v[184:187], 0
	v_mfma_i32_16x16x64_i8 v[34:37], v[148:151], v[192:195], 0
	v_mfma_i32_16x16x64_i8 v[38:41], v[156:159], v[192:195], 0
	v_mfma_i32_16x16x64_i8 v[58:61], v[152:155], v[172:175], v[58:61]
	v_mfma_i32_16x16x64_i8 v[62:65], v[164:167], v[172:175], v[62:65]
	v_mfma_i32_16x16x64_i8 v[50:53], v[152:155], v[180:183], v[50:53]
	v_mfma_i32_16x16x64_i8 v[54:57], v[164:167], v[180:183], v[54:57]
	v_mfma_i32_16x16x64_i8 v[42:45], v[152:155], v[188:191], v[42:45]
	v_mfma_i32_16x16x64_i8 v[46:49], v[164:167], v[188:191], v[46:49]
	v_mfma_i32_16x16x64_i8 v[34:37], v[152:155], v[212:215], v[34:37]
	v_mfma_i32_16x16x64_i8 v[38:41], v[164:167], v[212:215], v[38:41]
	s_barrier
	s_mov_b32 m0, s91
	v_lshl_add_u64 v[160:161], vcc, 0, v[0:1]
	ds_read_b128 v[168:171], v201 offset:16384
	ds_read_b128 v[172:175], v201 offset:17408
	ds_read_b128 v[176:179], v201 offset:18432
	ds_read_b128 v[180:183], v201 offset:19456
	ds_read_b128 v[184:187], v201 offset:20480
	ds_read_b128 v[188:191], v201 offset:21504
	ds_read_b128 v[192:195], v201 offset:22528
	ds_read_b128 v[212:215], v201 offset:23552
	global_load_lds_dwordx4 v[160:161], off
	v_lshl_add_u64 v[196:197], v[160:161], 0, s[70:71]
	s_mov_b32 m0, s14
	s_nop 0
	global_load_lds_dwordx4 v[196:197], off
	v_lshl_add_u64 v[196:197], v[160:161], 0, s[42:43]
	s_mov_b32 m0, s26
	s_nop 0
	global_load_lds_dwordx4 v[196:197], off
	v_lshl_add_u64 v[196:197], v[160:161], 0, s[48:49]
	s_mov_b32 m0, s27
	s_nop 0
	global_load_lds_dwordx4 v[196:197], off
	v_lshl_add_u64 v[196:197], s[8:9], 0, v[0:1]
	s_mov_b32 m0, s0
	v_lshl_add_u64 v[202:203], v[196:197], 0, s[70:71]
	global_load_lds_dwordx4 v[196:197], off
	s_mov_b32 m0, s1
	s_nop 0
	global_load_lds_dwordx4 v[202:203], off
	s_waitcnt vmcnt(8)
	s_waitcnt lgkmcnt(0)
	s_barrier
; #define PG8_STAGE(bufoff, gbase, unused) do { _Pragma("unroll") for (int _i = 0; _i < 2; ++_i) \
;         __builtin_amdgcn_global_load_lds((const unsigned*)((const char*)(gbase) + voff + _i * 8192), (LAS unsigned*)(lds + (bufoff) + ldsw + _i * 8192), 16, 0, 0); } while (0)
; #define PG8_LDA(dst, b, h) do { _Pragma("unroll") for (int m = 0; m < 4; ++m) _Pragma("unroll") for (int k = 0; k < 2; ++k) dst[m][k] = *(const LAS bf16x8*)(lds + PG8_SA(b, h) + aoff + m * 2048 + (FP8 ? k * 16 : k * 1024)); } while (0)
; #define PG8_LDB(dst, b, h) do { _Pragma("unroll") for (int n = 0; n < 2; ++n) _Pragma("unroll") for (int k = 0; k < 2; ++k) dst[n][k] = *(const LAS bf16x8*)(lds + PG8_SB(b, h) + boff + n * 2048 + (FP8 ? k * 16 : k * 1024)); } while (0)
; #define PG8_WAIT_V(n) asm volatile("s_waitcnt vmcnt(" #n ")" ::: "memory")
; #define PG8_WAIT_L(n) asm volatile("s_waitcnt lgkmcnt(" #n ")" ::: "memory")
; #define PG8_BAR __builtin_amdgcn_s_barrier()
; #define PG8_SCHED __builtin_amdgcn_sched_barrier(0)
; template <class Epi, class Sched, bool ALIGN_EPI, bool SP2, int MODE  >
; __device__ __forceinline__ void gemm_phase(LAS unsigned char* lds, const Gemm g, const Sched S, const Epi E, unsigned long long& probe_acc, int epi_id, int wv) {
;     ...
;             PG8_WAIT_V(8); PG8_WAIT_L(0); PG8_BAR; PG8_MMA(1, 0, At, B0); PG8_MMA(1, 1, At, B1); PG8_BAR; PG8_SCHED;
;             PG8_LDB(B0, 1, 0); PG8_LDB(B1, 1, 1); PG8_SCHED; PG8_LDA(At, 1, 0); PG8_STAGE(PG8_SA(0, 1), a2 + hA, voffA);
;             PG8_WAIT_V(8); PG8_WAIT_L(0); PG8_BAR; PG8_MMA(0, 0, At, B0); PG8_MMA(0, 1, At, B1); PG8_BAR; PG8_SCHED;
	v_mfma_i32_16x16x64_i8 v[90:93], v[132:135], v[168:171], 0
	v_mfma_i32_16x16x64_i8 v[94:97], v[140:143], v[168:171], 0
	v_mfma_i32_16x16x64_i8 v[82:85], v[132:135], v[176:179], 0
	v_mfma_i32_16x16x64_i8 v[86:89], v[140:143], v[176:179], 0
	v_mfma_i32_16x16x64_i8 v[74:77], v[132:135], v[184:187], 0
	v_mfma_i32_16x16x64_i8 v[78:81], v[140:143], v[184:187], 0
	v_mfma_i32_16x16x64_i8 v[66:69], v[132:135], v[192:195], 0
	v_mfma_i32_16x16x64_i8 v[70:73], v[140:143], v[192:195], 0
	v_mfma_i32_16x16x64_i8 v[90:93], v[136:139], v[172:175], v[90:93]
	v_mfma_i32_16x16x64_i8 v[94:97], v[144:147], v[172:175], v[94:97]
	v_mfma_i32_16x16x64_i8 v[82:85], v[136:139], v[180:183], v[82:85]
	v_mfma_i32_16x16x64_i8 v[86:89], v[144:147], v[180:183], v[86:89]
	v_mfma_i32_16x16x64_i8 v[74:77], v[136:139], v[188:191], v[74:77]
	v_mfma_i32_16x16x64_i8 v[78:81], v[144:147], v[188:191], v[78:81]
	v_mfma_i32_16x16x64_i8 v[66:69], v[136:139], v[212:215], v[66:69]
	v_mfma_i32_16x16x64_i8 v[70:73], v[144:147], v[212:215], v[70:73]
	v_mfma_i32_16x16x64_i8 v[26:29], v[148:151], v[168:171], 0
	v_mfma_i32_16x16x64_i8 v[30:33], v[156:159], v[168:171], 0
	v_mfma_i32_16x16x64_i8 v[18:21], v[148:151], v[176:179], 0
	v_mfma_i32_16x16x64_i8 v[22:25], v[156:159], v[176:179], 0
	v_mfma_i32_16x16x64_i8 v[10:13], v[148:151], v[184:187], 0
	v_mfma_i32_16x16x64_i8 v[14:17], v[156:159], v[184:187], 0
	v_mfma_i32_16x16x64_i8 v[2:5], v[148:151], v[192:195], 0
	v_mfma_i32_16x16x64_i8 v[6:9], v[156:159], v[192:195], 0
	v_mfma_i32_16x16x64_i8 v[26:29], v[152:155], v[172:175], v[26:29]
	v_mfma_i32_16x16x64_i8 v[30:33], v[164:167], v[172:175], v[30:33]
	v_mfma_i32_16x16x64_i8 v[18:21], v[152:155], v[180:183], v[18:21]
	v_mfma_i32_16x16x64_i8 v[22:25], v[164:167], v[180:183], v[22:25]
	v_mfma_i32_16x16x64_i8 v[10:13], v[152:155], v[188:191], v[10:13]
	v_mfma_i32_16x16x64_i8 v[14:17], v[164:167], v[188:191], v[14:17]
	v_mfma_i32_16x16x64_i8 v[2:5], v[152:155], v[212:215], v[2:5]
	v_mfma_i32_16x16x64_i8 v[6:9], v[164:167], v[212:215], v[6:9]
	s_barrier
	v_add_u32_e32 v144, s88, v200
	v_add_u32_e32 v162, s95, v200
	ds_read_b128 v[132:135], v144
	ds_read_b128 v[136:139], v144 offset:1024
	ds_read_b128 v[140:143], v144 offset:2048
	ds_read_b128 v[144:147], v144 offset:3072
	ds_read_b128 v[148:151], v162
	ds_read_b128 v[152:155], v162 offset:1024
	ds_read_b128 v[156:159], v162 offset:2048
	ds_read_b128 v[164:167], v162 offset:3072
	s_add_u32 s8, s8, s40
	s_addc_u32 s9, s9, 0
	s_mov_b32 m0, s36
	v_lshl_add_u64 v[202:203], s[8:9], 0, v[0:1]
	ds_read_b128 v[168:171], v201 offset:32768
	ds_read_b128 v[172:175], v201 offset:33792
	ds_read_b128 v[176:179], v201 offset:34816
	ds_read_b128 v[180:183], v201 offset:35840
	ds_read_b128 v[184:187], v201 offset:36864
	ds_read_b128 v[188:191], v201 offset:37888
	ds_read_b128 v[192:195], v201 offset:38912
	ds_read_b128 v[212:215], v201 offset:39936
	global_load_lds_dwordx4 v[202:203], off
	v_lshl_add_u64 v[202:203], v[202:203], 0, s[70:71]
	s_mov_b32 m0, s37
	s_nop 0
	global_load_lds_dwordx4 v[202:203], off
	s_waitcnt vmcnt(8)
	s_waitcnt lgkmcnt(0)
	s_barrier
	v_mfma_i32_16x16x64_i8 v[122:125], v[132:135], v[168:171], v[122:125]
	v_mfma_i32_16x16x64_i8 v[126:129], v[140:143], v[168:171], v[126:129]
	v_mfma_i32_16x16x64_i8 v[114:117], v[132:135], v[176:179], v[114:117]
	v_mfma_i32_16x16x64_i8 v[118:121], v[140:143], v[176:179], v[118:121]
	v_mfma_i32_16x16x64_i8 v[106:109], v[132:135], v[184:187], v[106:109]
	v_mfma_i32_16x16x64_i8 v[110:113], v[140:143], v[184:187], v[110:113]
	v_mfma_i32_16x16x64_i8 v[98:101], v[132:135], v[192:195], v[98:101]
	v_mfma_i32_16x16x64_i8 v[102:105], v[140:143], v[192:195], v[102:105]
	v_mfma_i32_16x16x64_i8 v[122:125], v[136:139], v[172:175], v[122:125]
	v_mfma_i32_16x16x64_i8 v[126:129], v[144:147], v[172:175], v[126:129]
	v_mfma_i32_16x16x64_i8 v[114:117], v[136:139], v[180:183], v[114:117]
	v_mfma_i32_16x16x64_i8 v[118:121], v[144:147], v[180:183], v[118:121]
	v_mfma_i32_16x16x64_i8 v[106:109], v[136:139], v[188:191], v[106:109]
	v_mfma_i32_16x16x64_i8 v[110:113], v[144:147], v[188:191], v[110:113]
	v_mfma_i32_16x16x64_i8 v[98:101], v[136:139], v[212:215], v[98:101]
	v_mfma_i32_16x16x64_i8 v[102:105], v[144:147], v[212:215], v[102:105]
	v_mfma_i32_16x16x64_i8 v[58:61], v[148:151], v[168:171], v[58:61]
	v_mfma_i32_16x16x64_i8 v[62:65], v[156:159], v[168:171], v[62:65]
	v_mfma_i32_16x16x64_i8 v[50:53], v[148:151], v[176:179], v[50:53]
	v_mfma_i32_16x16x64_i8 v[54:57], v[156:159], v[176:179], v[54:57]
	v_mfma_i32_16x16x64_i8 v[42:45], v[148:151], v[184:187], v[42:45]
	v_mfma_i32_16x16x64_i8 v[46:49], v[156:159], v[184:187], v[46:49]
	v_mfma_i32_16x16x64_i8 v[34:37], v[148:151], v[192:195], v[34:37]
	v_mfma_i32_16x16x64_i8 v[38:41], v[156:159], v[192:195], v[38:41]
	v_mfma_i32_16x16x64_i8 v[58:61], v[152:155], v[172:175], v[58:61]
	v_mfma_i32_16x16x64_i8 v[62:65], v[164:167], v[172:175], v[62:65]
	v_mfma_i32_16x16x64_i8 v[50:53], v[152:155], v[180:183], v[50:53]
	v_mfma_i32_16x16x64_i8 v[54:57], v[164:167], v[180:183], v[54:57]
	v_mfma_i32_16x16x64_i8 v[42:45], v[152:155], v[188:191], v[42:45]
	v_mfma_i32_16x16x64_i8 v[46:49], v[164:167], v[188:191], v[46:49]
	v_mfma_i32_16x16x64_i8 v[34:37], v[152:155], v[212:215], v[34:37]
	v_mfma_i32_16x16x64_i8 v[38:41], v[164:167], v[212:215], v[38:41]
	s_barrier
; #define PG8_STAGE(bufoff, gbase, unused) do { _Pragma("unroll") for (int _i = 0; _i < 2; ++_i) \
;         __builtin_amdgcn_global_load_lds((const unsigned*)((const char*)(gbase) + voff + _i * 8192), (LAS unsigned*)(lds + (bufoff) + ldsw + _i * 8192), 16, 0, 0); } while (0)
; #define PG8_LDA(dst, b, h) do { _Pragma("unroll") for (int m = 0; m < 4; ++m) _Pragma("unroll") for (int k = 0; k < 2; ++k) dst[m][k] = *(const LAS bf16x8*)(lds + PG8_SA(b, h) + aoff + m * 2048 + (FP8 ? k * 16 : k * 1024)); } while (0)
; #define PG8_LDB(dst, b, h) do { _Pragma("unroll") for (int n = 0; n < 2; ++n) _Pragma("unroll") for (int k = 0; k < 2; ++k) dst[n][k] = *(const LAS bf16x8*)(lds + PG8_SB(b, h) + boff + n * 2048 + (FP8 ? k * 16 : k * 1024)); } while (0)
; #define PG8_WAIT_V(n) asm volatile("s_waitcnt vmcnt(" #n ")" ::: "memory")
; #define PG8_WAIT_L(n) asm volatile("s_waitcnt lgkmcnt(" #n ")" ::: "memory")
; #define PG8_BAR __builtin_amdgcn_s_barrier()
; #define PG8_SCHED __builtin_amdgcn_sched_barrier(0)
; template <class Epi, class Sched, bool ALIGN_EPI, bool SP2, int MODE  >
; __device__ __forceinline__ void gemm_phase(LAS unsigned char* lds, const Gemm g, const Sched S, const Epi E, unsigned long long& probe_acc, int epi_id, int wv) {
;     ...
;         for (int t = 0; t < nt; t += 2) {
;             const bool last = (t == nt - 2);
;             const char* a1 = cA + (size_t)(t + 1) * kstep;
;             const char* a2 = last ? nA : cA + (size_t)(t + 2) * kstep; const char* b2 = last ? nB : cB + (size_t)(t + 2) * kstep;
;             const char* a3 = a2 + kstep; const char* b3 = b2 + kstep;
;             if constexpr (SP2) {
;             PG8_LDB(B0, 0, 0); PG8_LDB(B1, 0, 1); PG8_SCHED; PG8_LDA(At, 0, 0); PG8_STAGE(PG8_SA(1, 1), a1 + hA, voffA);
;             PG8_WAIT_V(8); PG8_WAIT_L(0); PG8_BAR; PG8_MMA(0, 0, At, B0); PG8_MMA(0, 1, At, B1); PG8_BAR; PG8_SCHED;
;     ...
;             PG8_WAIT_V(8); PG8_WAIT_L(0); PG8_BAR; PG8_MMA(0, 0, At, B0); PG8_MMA(0, 1, At, B1); PG8_BAR; PG8_SCHED;
;             PG8_LDA(At, 1, 1); PG8_STAGE(PG8_SB(1, 0), b3, voffB); PG8_STAGE(PG8_SB(1, 1), b3 + hB, voffB); PG8_STAGE(PG8_SA(1, 0), a3, voffA);
;             PG8_WAIT_V(8); PG8_WAIT_L(0); PG8_BAR; PG8_MMA(1, 0, At, B0); PG8_MMA(1, 1, At, B1); PG8_BAR; PG8_SCHED;
	s_mov_b32 m0, s89
	v_lshl_add_u64 v[202:203], v[160:161], 0, s[76:77]
	ds_read_b128 v[168:171], v201 offset:49152
	ds_read_b128 v[172:175], v201 offset:50176
	ds_read_b128 v[176:179], v201 offset:51200
	ds_read_b128 v[180:183], v201 offset:52224
	ds_read_b128 v[184:187], v201 offset:53248
	ds_read_b128 v[188:191], v201 offset:54272
	ds_read_b128 v[192:195], v201 offset:55296
	ds_read_b128 v[212:215], v201 offset:56320
	global_load_lds_dwordx4 v[202:203], off
	v_lshl_add_u64 v[202:203], v[160:161], 0, s[78:79]
	s_mov_b32 m0, s92
	s_nop 0
	global_load_lds_dwordx4 v[202:203], off
	v_lshl_add_u64 v[202:203], v[160:161], 0, s[44:45]
	s_mov_b32 m0, s84
	v_lshl_add_u64 v[160:161], v[160:161], 0, s[56:57]
	global_load_lds_dwordx4 v[202:203], off
	s_mov_b32 m0, s12
	s_nop 0
	global_load_lds_dwordx4 v[160:161], off
	v_lshl_add_u64 v[160:161], v[196:197], 0, s[76:77]
	s_mov_b32 m0, s93
	s_nop 0
	global_load_lds_dwordx4 v[160:161], off
	v_lshl_add_u64 v[160:161], v[196:197], 0, s[78:79]
	s_mov_b32 m0, s94
	s_nop 0
	global_load_lds_dwordx4 v[160:161], off
	s_waitcnt vmcnt(8)
	s_waitcnt lgkmcnt(0)
	s_barrier
	v_mfma_i32_16x16x64_i8 v[90:93], v[132:135], v[168:171], v[90:93]
	v_mfma_i32_16x16x64_i8 v[94:97], v[140:143], v[168:171], v[94:97]
	v_mfma_i32_16x16x64_i8 v[82:85], v[132:135], v[176:179], v[82:85]
	v_mfma_i32_16x16x64_i8 v[86:89], v[140:143], v[176:179], v[86:89]
	v_mfma_i32_16x16x64_i8 v[74:77], v[132:135], v[184:187], v[74:77]
	v_mfma_i32_16x16x64_i8 v[78:81], v[140:143], v[184:187], v[78:81]
	v_mfma_i32_16x16x64_i8 v[66:69], v[132:135], v[192:195], v[66:69]
	v_mfma_i32_16x16x64_i8 v[70:73], v[140:143], v[192:195], v[70:73]
	v_mfma_i32_16x16x64_i8 v[90:93], v[136:139], v[172:175], v[90:93]
	v_mfma_i32_16x16x64_i8 v[94:97], v[144:147], v[172:175], v[94:97]
	v_mfma_i32_16x16x64_i8 v[82:85], v[136:139], v[180:183], v[82:85]
	v_mfma_i32_16x16x64_i8 v[86:89], v[144:147], v[180:183], v[86:89]
	v_mfma_i32_16x16x64_i8 v[74:77], v[136:139], v[188:191], v[74:77]
	v_mfma_i32_16x16x64_i8 v[78:81], v[144:147], v[188:191], v[78:81]
	v_mfma_i32_16x16x64_i8 v[66:69], v[136:139], v[212:215], v[66:69]
	v_mfma_i32_16x16x64_i8 v[70:73], v[144:147], v[212:215], v[70:73]
	v_mfma_i32_16x16x64_i8 v[26:29], v[148:151], v[168:171], v[26:29]
	v_mfma_i32_16x16x64_i8 v[30:33], v[156:159], v[168:171], v[30:33]
	v_mfma_i32_16x16x64_i8 v[18:21], v[148:151], v[176:179], v[18:21]
	v_mfma_i32_16x16x64_i8 v[22:25], v[156:159], v[176:179], v[22:25]
	v_mfma_i32_16x16x64_i8 v[10:13], v[148:151], v[184:187], v[10:13]
	v_mfma_i32_16x16x64_i8 v[14:17], v[156:159], v[184:187], v[14:17]
	v_mfma_i32_16x16x64_i8 v[2:5], v[148:151], v[192:195], v[2:5]
	v_mfma_i32_16x16x64_i8 v[6:9], v[156:159], v[192:195], v[6:9]
	v_mfma_i32_16x16x64_i8 v[26:29], v[152:155], v[172:175], v[26:29]
	v_mfma_i32_16x16x64_i8 v[30:33], v[164:167], v[172:175], v[30:33]
	v_mfma_i32_16x16x64_i8 v[18:21], v[152:155], v[180:183], v[18:21]
	v_mfma_i32_16x16x64_i8 v[22:25], v[164:167], v[180:183], v[22:25]
	v_mfma_i32_16x16x64_i8 v[10:13], v[152:155], v[188:191], v[10:13]
	v_mfma_i32_16x16x64_i8 v[14:17], v[164:167], v[188:191], v[14:17]
	v_mfma_i32_16x16x64_i8 v[2:5], v[152:155], v[212:215], v[2:5]
	v_mfma_i32_16x16x64_i8 v[6:9], v[164:167], v[212:215], v[6:9]
	s_barrier
	s_add_i32 s34, s34, 2
	s_add_u32 s6, s6, 0x8000
	s_addc_u32 s7, s7, 0
	s_cmp_gt_u32 s34, 41
	v_readlane_b32 s98, v254, 1
	s_nop 3
	s_cmp_ge_u32 s98, 4
	s_cbranch_scc0 .Lprio_skip_4
	s_setprio 1
.Lprio_skip_4:
.LBB0_1154:
	v_add_u32_e32 v144, s90, v200
	v_add_u32_e32 v160, s15, v200
	s_add_u32 s8, s4, s6
	ds_read_b128 v[132:135], v144
	ds_read_b128 v[136:139], v144 offset:1024
	ds_read_b128 v[140:143], v144 offset:2048
	ds_read_b128 v[144:147], v144 offset:3072
	ds_read_b128 v[148:151], v160
	ds_read_b128 v[152:155], v160 offset:1024
	ds_read_b128 v[156:159], v160 offset:2048
	ds_read_b128 v[164:167], v160 offset:3072
	s_addc_u32 s9, s5, s7
	s_add_u32 s8, s8, 0x8000
	s_addc_u32 s9, s9, 0
	s_add_u32 s28, s10, s6
	s_addc_u32 s29, s11, s7
	s_cmp_eq_u32 s6, 0xa8000
	s_cselect_b32 s9, s67, s9
	s_cselect_b32 s8, s66, s8
	s_cselect_b32 vcc_hi, s87, s29
	s_cselect_b32 vcc_lo, s86, s28
	v_lshl_add_u64 v[160:161], v[130:131], 0, s[6:7]
	v_lshl_add_u64 v[196:197], v[160:161], 0, s[76:77]
	s_add_i32 m0, s0, 0xc000
	ds_read_b128 v[168:171], v201
	ds_read_b128 v[172:175], v201 offset:1024
	ds_read_b128 v[176:179], v201 offset:2048
	ds_read_b128 v[180:183], v201 offset:3072
	ds_read_b128 v[184:187], v201 offset:4096
	ds_read_b128 v[188:191], v201 offset:5120
	ds_read_b128 v[192:195], v201 offset:6144
	ds_read_b128 v[212:215], v201 offset:7168
	global_load_lds_dwordx4 v[196:197], off
	v_lshl_add_u64 v[160:161], v[160:161], 0, s[78:79]
	s_add_i32 m0, s0, 0xe000
	s_nop 0
	global_load_lds_dwordx4 v[160:161], off
	s_waitcnt vmcnt(8)
	s_waitcnt lgkmcnt(0)
	s_barrier
; #define PG8_STAGE(bufoff, gbase, unused) do { _Pragma("unroll") for (int _i = 0; _i < 2; ++_i) \
;         __builtin_amdgcn_global_load_lds((const unsigned*)((const char*)(gbase) + voff + _i * 8192), (LAS unsigned*)(lds + (bufoff) + ldsw + _i * 8192), 16, 0, 0); } while (0)
; #define PG8_LDA(dst, b, h) do { _Pragma("unroll") for (int m = 0; m < 4; ++m) _Pragma("unroll") for (int k = 0; k < 2; ++k) dst[m][k] = *(const LAS bf16x8*)(lds + PG8_SA(b, h) + aoff + m * 2048 + (FP8 ? k * 16 : k * 1024)); } while (0)
; #define PG8_LDB(dst, b, h) do { _Pragma("unroll") for (int n = 0; n < 2; ++n) _Pragma("unroll") for (int k = 0; k < 2; ++k) dst[n][k] = *(const LAS bf16x8*)(lds + PG8_SB(b, h) + boff + n * 2048 + (FP8 ? k * 16 : k * 1024)); } while (0)
; #define PG8_WAIT_V(n) asm volatile("s_waitcnt vmcnt(" #n ")" ::: "memory")
; #define PG8_WAIT_L(n) asm volatile("s_waitcnt lgkmcnt(" #n ")" ::: "memory")
; #define PG8_BAR __builtin_amdgcn_s_barrier()
; #define PG8_SCHED __builtin_amdgcn_sched_barrier(0)
; template <class Epi, class Sched, bool ALIGN_EPI, bool SP2, int MODE  >
; __device__ __forceinline__ void gemm_phase(LAS unsigned char* lds, const Gemm g, const Sched S, const Epi E, unsigned long long& probe_acc, int epi_id, int wv) {
;     ...
;             PG8_LDB(B0, 0, 0); PG8_LDB(B1, 0, 1); PG8_SCHED; PG8_LDA(At, 0, 0); PG8_STAGE(PG8_SA(1, 1), a1 + hA, voffA);
;             PG8_WAIT_V(8); PG8_WAIT_L(0); PG8_BAR; PG8_MMA(0, 0, At, B0); PG8_MMA(0, 1, At, B1); PG8_BAR; PG8_SCHED;
;             PG8_LDA(At, 0, 1); PG8_STAGE(PG8_SB(0, 0), b2, voffB); PG8_STAGE(PG8_SB(0, 1), b2 + hB, voffB); PG8_STAGE(PG8_SA(0, 0), a2, voffA);
;             PG8_WAIT_V(8); PG8_WAIT_L(0); PG8_BAR; PG8_MMA(1, 0, At, B0); PG8_MMA(1, 1, At, B1); PG8_BAR; PG8_SCHED;
;             PG8_LDB(B0, 1, 0); PG8_LDB(B1, 1, 1); PG8_SCHED; PG8_LDA(At, 1, 0); PG8_STAGE(PG8_SA(0, 1), a2 + hA, voffA);
;             PG8_WAIT_V(8); PG8_WAIT_L(0); PG8_BAR; PG8_MMA(0, 0, At, B0); PG8_MMA(0, 1, At, B1); PG8_BAR; PG8_SCHED;
	v_mfma_i32_16x16x64_i8 v[122:125], v[132:135], v[168:171], v[122:125]
	v_mfma_i32_16x16x64_i8 v[126:129], v[140:143], v[168:171], v[126:129]
	v_mfma_i32_16x16x64_i8 v[114:117], v[132:135], v[176:179], v[114:117]
	v_mfma_i32_16x16x64_i8 v[118:121], v[140:143], v[176:179], v[118:121]
	v_mfma_i32_16x16x64_i8 v[106:109], v[132:135], v[184:187], v[106:109]
	v_mfma_i32_16x16x64_i8 v[110:113], v[140:143], v[184:187], v[110:113]
	v_mfma_i32_16x16x64_i8 v[98:101], v[132:135], v[192:195], v[98:101]
	v_mfma_i32_16x16x64_i8 v[102:105], v[140:143], v[192:195], v[102:105]
	v_mfma_i32_16x16x64_i8 v[122:125], v[136:139], v[172:175], v[122:125]
	v_mfma_i32_16x16x64_i8 v[126:129], v[144:147], v[172:175], v[126:129]
	v_mfma_i32_16x16x64_i8 v[114:117], v[136:139], v[180:183], v[114:117]
	v_mfma_i32_16x16x64_i8 v[118:121], v[144:147], v[180:183], v[118:121]
	v_mfma_i32_16x16x64_i8 v[106:109], v[136:139], v[188:191], v[106:109]
	v_mfma_i32_16x16x64_i8 v[110:113], v[144:147], v[188:191], v[110:113]
	v_mfma_i32_16x16x64_i8 v[98:101], v[136:139], v[212:215], v[98:101]
	v_mfma_i32_16x16x64_i8 v[102:105], v[144:147], v[212:215], v[102:105]
	v_mfma_i32_16x16x64_i8 v[58:61], v[148:151], v[168:171], v[58:61]
	v_mfma_i32_16x16x64_i8 v[62:65], v[156:159], v[168:171], v[62:65]
	v_mfma_i32_16x16x64_i8 v[50:53], v[148:151], v[176:179], v[50:53]
	v_mfma_i32_16x16x64_i8 v[54:57], v[156:159], v[176:179], v[54:57]
	v_mfma_i32_16x16x64_i8 v[42:45], v[148:151], v[184:187], v[42:45]
	v_mfma_i32_16x16x64_i8 v[46:49], v[156:159], v[184:187], v[46:49]
	v_mfma_i32_16x16x64_i8 v[34:37], v[148:151], v[192:195], v[34:37]
	v_mfma_i32_16x16x64_i8 v[38:41], v[156:159], v[192:195], v[38:41]
	v_mfma_i32_16x16x64_i8 v[58:61], v[152:155], v[172:175], v[58:61]
	v_mfma_i32_16x16x64_i8 v[62:65], v[164:167], v[172:175], v[62:65]
	v_mfma_i32_16x16x64_i8 v[50:53], v[152:155], v[180:183], v[50:53]
	v_mfma_i32_16x16x64_i8 v[54:57], v[164:167], v[180:183], v[54:57]
	v_mfma_i32_16x16x64_i8 v[42:45], v[152:155], v[188:191], v[42:45]
	v_mfma_i32_16x16x64_i8 v[46:49], v[164:167], v[188:191], v[46:49]
	v_mfma_i32_16x16x64_i8 v[34:37], v[152:155], v[212:215], v[34:37]
	v_mfma_i32_16x16x64_i8 v[38:41], v[164:167], v[212:215], v[38:41]
	s_barrier
	s_mov_b32 m0, s91
	v_lshl_add_u64 v[160:161], vcc, 0, v[0:1]
	ds_read_b128 v[168:171], v201 offset:16384
	ds_read_b128 v[172:175], v201 offset:17408
	ds_read_b128 v[176:179], v201 offset:18432
	ds_read_b128 v[180:183], v201 offset:19456
	ds_read_b128 v[184:187], v201 offset:20480
	ds_read_b128 v[188:191], v201 offset:21504
	ds_read_b128 v[192:195], v201 offset:22528
	ds_read_b128 v[212:215], v201 offset:23552
	global_load_lds_dwordx4 v[160:161], off
	v_lshl_add_u64 v[196:197], v[160:161], 0, s[70:71]
	s_mov_b32 m0, s14
	s_nop 0
	global_load_lds_dwordx4 v[196:197], off
	v_lshl_add_u64 v[196:197], v[160:161], 0, s[42:43]
	s_mov_b32 m0, s26
	s_nop 0
	global_load_lds_dwordx4 v[196:197], off
	v_lshl_add_u64 v[196:197], v[160:161], 0, s[48:49]
	s_mov_b32 m0, s27
	s_nop 0
	global_load_lds_dwordx4 v[196:197], off
	v_lshl_add_u64 v[196:197], s[8:9], 0, v[0:1]
	s_mov_b32 m0, s0
	v_lshl_add_u64 v[202:203], v[196:197], 0, s[70:71]
	global_load_lds_dwordx4 v[196:197], off
	s_mov_b32 m0, s1
	s_nop 0
	global_load_lds_dwordx4 v[202:203], off
	s_waitcnt vmcnt(8)
	s_waitcnt lgkmcnt(0)
	s_barrier
	v_mfma_i32_16x16x64_i8 v[90:93], v[132:135], v[168:171], v[90:93]
	v_mfma_i32_16x16x64_i8 v[94:97], v[140:143], v[168:171], v[94:97]
	v_mfma_i32_16x16x64_i8 v[82:85], v[132:135], v[176:179], v[82:85]
	v_mfma_i32_16x16x64_i8 v[86:89], v[140:143], v[176:179], v[86:89]
	v_mfma_i32_16x16x64_i8 v[74:77], v[132:135], v[184:187], v[74:77]
	v_mfma_i32_16x16x64_i8 v[78:81], v[140:143], v[184:187], v[78:81]
	v_mfma_i32_16x16x64_i8 v[66:69], v[132:135], v[192:195], v[66:69]
	v_mfma_i32_16x16x64_i8 v[70:73], v[140:143], v[192:195], v[70:73]
	v_mfma_i32_16x16x64_i8 v[90:93], v[136:139], v[172:175], v[90:93]
	v_mfma_i32_16x16x64_i8 v[94:97], v[144:147], v[172:175], v[94:97]
	v_mfma_i32_16x16x64_i8 v[82:85], v[136:139], v[180:183], v[82:85]
	v_mfma_i32_16x16x64_i8 v[86:89], v[144:147], v[180:183], v[86:89]
	v_mfma_i32_16x16x64_i8 v[74:77], v[136:139], v[188:191], v[74:77]
	v_mfma_i32_16x16x64_i8 v[78:81], v[144:147], v[188:191], v[78:81]
	v_mfma_i32_16x16x64_i8 v[66:69], v[136:139], v[212:215], v[66:69]
	v_mfma_i32_16x16x64_i8 v[70:73], v[144:147], v[212:215], v[70:73]
	v_mfma_i32_16x16x64_i8 v[26:29], v[148:151], v[168:171], v[26:29]
	v_mfma_i32_16x16x64_i8 v[30:33], v[156:159], v[168:171], v[30:33]
	v_mfma_i32_16x16x64_i8 v[18:21], v[148:151], v[176:179], v[18:21]
	v_mfma_i32_16x16x64_i8 v[22:25], v[156:159], v[176:179], v[22:25]
	v_mfma_i32_16x16x64_i8 v[10:13], v[148:151], v[184:187], v[10:13]
	v_mfma_i32_16x16x64_i8 v[14:17], v[156:159], v[184:187], v[14:17]
	v_mfma_i32_16x16x64_i8 v[2:5], v[148:151], v[192:195], v[2:5]
	v_mfma_i32_16x16x64_i8 v[6:9], v[156:159], v[192:195], v[6:9]
	v_mfma_i32_16x16x64_i8 v[26:29], v[152:155], v[172:175], v[26:29]
	v_mfma_i32_16x16x64_i8 v[30:33], v[164:167], v[172:175], v[30:33]
	v_mfma_i32_16x16x64_i8 v[18:21], v[152:155], v[180:183], v[18:21]
	v_mfma_i32_16x16x64_i8 v[22:25], v[164:167], v[180:183], v[22:25]
	v_mfma_i32_16x16x64_i8 v[10:13], v[152:155], v[188:191], v[10:13]
	v_mfma_i32_16x16x64_i8 v[14:17], v[164:167], v[188:191], v[14:17]
	v_mfma_i32_16x16x64_i8 v[2:5], v[152:155], v[212:215], v[2:5]
	v_mfma_i32_16x16x64_i8 v[6:9], v[164:167], v[212:215], v[6:9]
	s_barrier
; #define PG8_STAGE(bufoff, gbase, unused) do { _Pragma("unroll") for (int _i = 0; _i < 2; ++_i) \
;         __builtin_amdgcn_global_load_lds((const unsigned*)((const char*)(gbase) + voff + _i * 8192), (LAS unsigned*)(lds + (bufoff) + ldsw + _i * 8192), 16, 0, 0); } while (0)
; #define PG8_LDA(dst, b, h) do { _Pragma("unroll") for (int m = 0; m < 4; ++m) _Pragma("unroll") for (int k = 0; k < 2; ++k) dst[m][k] = *(const LAS bf16x8*)(lds + PG8_SA(b, h) + aoff + m * 2048 + (FP8 ? k * 16 : k * 1024)); } while (0)
; #define PG8_LDB(dst, b, h) do { _Pragma("unroll") for (int n = 0; n < 2; ++n) _Pragma("unroll") for (int k = 0; k < 2; ++k) dst[n][k] = *(const LAS bf16x8*)(lds + PG8_SB(b, h) + boff + n * 2048 + (FP8 ? k * 16 : k * 1024)); } while (0)
; #define PG8_WAIT_V(n) asm volatile("s_waitcnt vmcnt(" #n ")" ::: "memory")
; #define PG8_WAIT_L(n) asm volatile("s_waitcnt lgkmcnt(" #n ")" ::: "memory")
; #define PG8_BAR __builtin_amdgcn_s_barrier()
; #define PG8_SCHED __builtin_amdgcn_sched_barrier(0)
; template <class Epi, class Sched, bool ALIGN_EPI, bool SP2, int MODE  >
; __device__ __forceinline__ void gemm_phase(LAS unsigned char* lds, const Gemm g, const Sched S, const Epi E, unsigned long long& probe_acc, int epi_id, int wv) {
;     ...
;             PG8_LDB(B0, 1, 0); PG8_LDB(B1, 1, 1); PG8_SCHED; PG8_LDA(At, 1, 0); PG8_STAGE(PG8_SA(0, 1), a2 + hA, voffA);
;             PG8_WAIT_V(8); PG8_WAIT_L(0); PG8_BAR; PG8_MMA(0, 0, At, B0); PG8_MMA(0, 1, At, B1); PG8_BAR; PG8_SCHED;
;             PG8_LDA(At, 1, 1); PG8_STAGE(PG8_SB(1, 0), b3, voffB); PG8_STAGE(PG8_SB(1, 1), b3 + hB, voffB); PG8_STAGE(PG8_SA(1, 0), a3, voffA);
;             PG8_WAIT_V(8); PG8_WAIT_L(0); PG8_BAR; PG8_MMA(1, 0, At, B0); PG8_MMA(1, 1, At, B1); PG8_BAR; PG8_SCHED;
;     ...
;         if constexpr (ALIGN_EPI) { if (wr == 0) PG8_BAR; }
	v_add_u32_e32 v144, s88, v200
	v_add_u32_e32 v162, s95, v200
	ds_read_b128 v[132:135], v144
	ds_read_b128 v[136:139], v144 offset:1024
	ds_read_b128 v[140:143], v144 offset:2048
	ds_read_b128 v[144:147], v144 offset:3072
	ds_read_b128 v[148:151], v162
	ds_read_b128 v[152:155], v162 offset:1024
	ds_read_b128 v[156:159], v162 offset:2048
	ds_read_b128 v[164:167], v162 offset:3072
	s_add_u32 s8, s8, s40
	s_addc_u32 s9, s9, 0
	s_mov_b32 m0, s36
	v_lshl_add_u64 v[202:203], s[8:9], 0, v[0:1]
	ds_read_b128 v[168:171], v201 offset:32768
	ds_read_b128 v[172:175], v201 offset:33792
	ds_read_b128 v[176:179], v201 offset:34816
	ds_read_b128 v[180:183], v201 offset:35840
	ds_read_b128 v[184:187], v201 offset:36864
	ds_read_b128 v[188:191], v201 offset:37888
	ds_read_b128 v[192:195], v201 offset:38912
	ds_read_b128 v[212:215], v201 offset:39936
	global_load_lds_dwordx4 v[202:203], off
	v_lshl_add_u64 v[202:203], v[202:203], 0, s[70:71]
	s_mov_b32 m0, s37
	s_nop 0
	global_load_lds_dwordx4 v[202:203], off
	s_waitcnt vmcnt(8)
	s_waitcnt lgkmcnt(0)
	s_barrier
	v_mfma_i32_16x16x64_i8 v[122:125], v[132:135], v[168:171], v[122:125]
	v_mfma_i32_16x16x64_i8 v[126:129], v[140:143], v[168:171], v[126:129]
	v_mfma_i32_16x16x64_i8 v[114:117], v[132:135], v[176:179], v[114:117]
	v_mfma_i32_16x16x64_i8 v[118:121], v[140:143], v[176:179], v[118:121]
	v_mfma_i32_16x16x64_i8 v[106:109], v[132:135], v[184:187], v[106:109]
	v_mfma_i32_16x16x64_i8 v[110:113], v[140:143], v[184:187], v[110:113]
	v_mfma_i32_16x16x64_i8 v[98:101], v[132:135], v[192:195], v[98:101]
	v_mfma_i32_16x16x64_i8 v[102:105], v[140:143], v[192:195], v[102:105]
	v_mfma_i32_16x16x64_i8 v[122:125], v[136:139], v[172:175], v[122:125]
	v_mfma_i32_16x16x64_i8 v[126:129], v[144:147], v[172:175], v[126:129]
	v_mfma_i32_16x16x64_i8 v[114:117], v[136:139], v[180:183], v[114:117]
	v_mfma_i32_16x16x64_i8 v[118:121], v[144:147], v[180:183], v[118:121]
	v_mfma_i32_16x16x64_i8 v[106:109], v[136:139], v[188:191], v[106:109]
	v_mfma_i32_16x16x64_i8 v[110:113], v[144:147], v[188:191], v[110:113]
	v_mfma_i32_16x16x64_i8 v[98:101], v[136:139], v[212:215], v[98:101]
	v_mfma_i32_16x16x64_i8 v[102:105], v[144:147], v[212:215], v[102:105]
	v_mfma_i32_16x16x64_i8 v[58:61], v[148:151], v[168:171], v[58:61]
	v_mfma_i32_16x16x64_i8 v[62:65], v[156:159], v[168:171], v[62:65]
	v_mfma_i32_16x16x64_i8 v[50:53], v[148:151], v[176:179], v[50:53]
	v_mfma_i32_16x16x64_i8 v[54:57], v[156:159], v[176:179], v[54:57]
	v_mfma_i32_16x16x64_i8 v[42:45], v[148:151], v[184:187], v[42:45]
	v_mfma_i32_16x16x64_i8 v[46:49], v[156:159], v[184:187], v[46:49]
	v_mfma_i32_16x16x64_i8 v[34:37], v[148:151], v[192:195], v[34:37]
	v_mfma_i32_16x16x64_i8 v[38:41], v[156:159], v[192:195], v[38:41]
	v_mfma_i32_16x16x64_i8 v[58:61], v[152:155], v[172:175], v[58:61]
	v_mfma_i32_16x16x64_i8 v[62:65], v[164:167], v[172:175], v[62:65]
	v_mfma_i32_16x16x64_i8 v[50:53], v[152:155], v[180:183], v[50:53]
	v_mfma_i32_16x16x64_i8 v[54:57], v[164:167], v[180:183], v[54:57]
	v_mfma_i32_16x16x64_i8 v[42:45], v[152:155], v[188:191], v[42:45]
	v_mfma_i32_16x16x64_i8 v[46:49], v[164:167], v[188:191], v[46:49]
	v_mfma_i32_16x16x64_i8 v[34:37], v[152:155], v[212:215], v[34:37]
	v_mfma_i32_16x16x64_i8 v[38:41], v[164:167], v[212:215], v[38:41]
	s_barrier
	s_mov_b32 m0, s89
	v_lshl_add_u64 v[202:203], v[160:161], 0, s[76:77]
	ds_read_b128 v[168:171], v201 offset:49152
	ds_read_b128 v[172:175], v201 offset:50176
	ds_read_b128 v[176:179], v201 offset:51200
	ds_read_b128 v[180:183], v201 offset:52224
	ds_read_b128 v[184:187], v201 offset:53248
	ds_read_b128 v[188:191], v201 offset:54272
	ds_read_b128 v[192:195], v201 offset:55296
	ds_read_b128 v[212:215], v201 offset:56320
	global_load_lds_dwordx4 v[202:203], off
	v_lshl_add_u64 v[202:203], v[160:161], 0, s[78:79]
	s_mov_b32 m0, s92
	s_nop 0
	global_load_lds_dwordx4 v[202:203], off
	v_lshl_add_u64 v[202:203], v[160:161], 0, s[44:45]
	s_mov_b32 m0, s84
	v_lshl_add_u64 v[160:161], v[160:161], 0, s[56:57]
	global_load_lds_dwordx4 v[202:203], off
	s_mov_b32 m0, s12
	s_nop 0
	global_load_lds_dwordx4 v[160:161], off
	v_lshl_add_u64 v[160:161], v[196:197], 0, s[76:77]
	s_mov_b32 m0, s93
	s_nop 0
	global_load_lds_dwordx4 v[160:161], off
	v_lshl_add_u64 v[160:161], v[196:197], 0, s[78:79]
	s_mov_b32 m0, s94
	s_nop 0
	global_load_lds_dwordx4 v[160:161], off
	s_waitcnt vmcnt(8)
	s_waitcnt lgkmcnt(0)
	s_barrier
	v_mfma_i32_16x16x64_i8 v[90:93], v[132:135], v[168:171], v[90:93]
	v_mfma_i32_16x16x64_i8 v[94:97], v[140:143], v[168:171], v[94:97]
	v_mfma_i32_16x16x64_i8 v[82:85], v[132:135], v[176:179], v[82:85]
	v_mfma_i32_16x16x64_i8 v[86:89], v[140:143], v[176:179], v[86:89]
	v_mfma_i32_16x16x64_i8 v[74:77], v[132:135], v[184:187], v[74:77]
	v_mfma_i32_16x16x64_i8 v[78:81], v[140:143], v[184:187], v[78:81]
	v_mfma_i32_16x16x64_i8 v[66:69], v[132:135], v[192:195], v[66:69]
	v_mfma_i32_16x16x64_i8 v[70:73], v[140:143], v[192:195], v[70:73]
	v_mfma_i32_16x16x64_i8 v[90:93], v[136:139], v[172:175], v[90:93]
	v_mfma_i32_16x16x64_i8 v[94:97], v[144:147], v[172:175], v[94:97]
	v_mfma_i32_16x16x64_i8 v[82:85], v[136:139], v[180:183], v[82:85]
	v_mfma_i32_16x16x64_i8 v[86:89], v[144:147], v[180:183], v[86:89]
	v_mfma_i32_16x16x64_i8 v[74:77], v[136:139], v[188:191], v[74:77]
	v_mfma_i32_16x16x64_i8 v[78:81], v[144:147], v[188:191], v[78:81]
	v_mfma_i32_16x16x64_i8 v[66:69], v[136:139], v[212:215], v[66:69]
	v_mfma_i32_16x16x64_i8 v[70:73], v[144:147], v[212:215], v[70:73]
	v_mfma_i32_16x16x64_i8 v[26:29], v[148:151], v[168:171], v[26:29]
	v_mfma_i32_16x16x64_i8 v[30:33], v[156:159], v[168:171], v[30:33]
	v_mfma_i32_16x16x64_i8 v[18:21], v[148:151], v[176:179], v[18:21]
	v_mfma_i32_16x16x64_i8 v[22:25], v[156:159], v[176:179], v[22:25]
	v_mfma_i32_16x16x64_i8 v[10:13], v[148:151], v[184:187], v[10:13]
	v_mfma_i32_16x16x64_i8 v[14:17], v[156:159], v[184:187], v[14:17]
	v_mfma_i32_16x16x64_i8 v[2:5], v[148:151], v[192:195], v[2:5]
	v_mfma_i32_16x16x64_i8 v[6:9], v[156:159], v[192:195], v[6:9]
	v_mfma_i32_16x16x64_i8 v[26:29], v[152:155], v[172:175], v[26:29]
	v_mfma_i32_16x16x64_i8 v[30:33], v[164:167], v[172:175], v[30:33]
	v_mfma_i32_16x16x64_i8 v[18:21], v[152:155], v[180:183], v[18:21]
	v_mfma_i32_16x16x64_i8 v[22:25], v[164:167], v[180:183], v[22:25]
	v_mfma_i32_16x16x64_i8 v[10:13], v[152:155], v[188:191], v[10:13]
	v_mfma_i32_16x16x64_i8 v[14:17], v[164:167], v[188:191], v[14:17]
	v_mfma_i32_16x16x64_i8 v[2:5], v[152:155], v[212:215], v[2:5]
	v_mfma_i32_16x16x64_i8 v[6:9], v[164:167], v[212:215], v[6:9]
	s_barrier
	s_add_i32 s34, s34, 2
	s_add_u32 s6, s6, 0x8000
	s_addc_u32 s7, s7, 0
	s_cmp_gt_u32 s34, 41
	s_cbranch_scc0 .LBB0_1154
	v_readlane_b32 s4, v255, 34
	v_readlane_b32 s5, v255, 35
	s_and_b64 vcc, exec, s[4:5]
	s_cbranch_vccz .LBB0_1157
	s_barrier
